# v20 + removed redundant mid-segment s_setprio 0/1 pairs and duplicate post-barrier lgkmcnt(0) in the MFMA segments
# speedup vs baseline: 1.0027x; 1.0027x over previous
; #define PG8_STAGE(bufoff, gbase, voff) do { _Pragma("unroll") for (int _i = 0; _i < 2; ++_i) \
;         __builtin_amdgcn_global_load_lds((const unsigned*)((const char*)(gbase) + (voff)[_i]), (PG8_LAS unsigned*)(lds + (bufoff) + ldsw + _i * 8192), 16, 0, 0); } while (0)
; #define PG8_LDA(dst, b, h) do { _Pragma("unroll") for (int m = 0; m < 4; ++m) _Pragma("unroll") for (int k = 0; k < 2; ++k) dst[m][k] = *(const PG8_LAS bf16x8*)(lds + PG8_SA(b, h) + aoff + m * 2048 + k * 1024); } while (0)
; #define PG8_LDB(dst, b, h) do { _Pragma("unroll") for (int n = 0; n < 2; ++n) _Pragma("unroll") for (int k = 0; k < 2; ++k) dst[n][k] = *(const PG8_LAS bf16x8*)(lds + PG8_SB(b, h) + boff + n * 2048 + k * 1024); } while (0)
; template <class Epi, class Sched, bool ALIGN_EPI = false, bool SP2 = false>
; __device__ __forceinline__ void gemm_phase(PG8_LAS unsigned char* lds, const Gemm g, const Sched& S, const Epi& E) {
;     ...
;         for (int t = 0; t < nt; t += 2) {
;             const bool last = (t == nt - 2);
;             const char* a1 = cA + (size_t)(t + 1) * kstep;
;             const char* a2 = last ? nA : cA + (size_t)(t + 2) * kstep; const char* b2 = last ? nB : cB + (size_t)(t + 2) * kstep;
;             const char* a3 = a2 + kstep; const char* b3 = b2 + kstep;
;             if (last && has_next) S.a_ready(nxt);
;             if constexpr (SP2) {
;             PG8_LDB(B0, 0, 0); PG8_LDB(B1, 0, 1); PG8_SCHED; PG8_LDA(At, 0, 0); PG8_STAGE(PG8_SA(1, 1), a1 + hstepA, voffA);
;             PG8_WAIT_V(8); PG8_WAIT_L(0); PG8_BAR; PG8_MMA(0, 0, At, B0); PG8_MMA(0, 1, At, B1); PG8_BAR; PG8_SCHED;
;             PG8_LDA(At, 0, 1); PG8_STAGE(PG8_SB(0, 0), b2, voffB); PG8_STAGE(PG8_SB(0, 1), b2 + hstepB, voffB); PG8_STAGE(PG8_SA(0, 0), a2, voffA);
;             PG8_WAIT_V(8); PG8_WAIT_L(0); PG8_BAR; PG8_MMA(1, 0, At, B0); PG8_MMA(1, 1, At, B1); PG8_BAR; PG8_SCHED;
;             PG8_LDB(B0, 1, 0); PG8_LDB(B1, 1, 1); PG8_SCHED; PG8_LDA(At, 1, 0); PG8_STAGE(PG8_SA(0, 1), a2 + hstepA, voffA);
;             PG8_WAIT_V(8); PG8_WAIT_L(0); PG8_BAR; PG8_MMA(0, 0, At, B0); PG8_MMA(0, 1, At, B1); PG8_BAR; PG8_SCHED;
;             PG8_LDA(At, 1, 1); PG8_STAGE(PG8_SB(1, 0), b3, voffB); PG8_STAGE(PG8_SB(1, 1), b3 + hstepB, voffB); PG8_STAGE(PG8_SA(1, 0), a3, voffA);
;             PG8_WAIT_V(8); PG8_WAIT_L(0); PG8_BAR; PG8_MMA(1, 0, At, B0); PG8_MMA(1, 1, At, B1); PG8_BAR; PG8_SCHED;
.LBB0_231:
	ds_read_b128 v[146:149], v158
	ds_read_b128 v[162:165], v158 offset:1024
	ds_read_b128 v[182:185], v158 offset:2048
	ds_read_b128 v[186:189], v158 offset:3072
	ds_read_b128 v[190:193], v159
	ds_read_b128 v[194:197], v159 offset:1024
	ds_read_b128 v[198:201], v159 offset:2048
	ds_read_b128 v[202:205], v159 offset:3072
	s_add_u32 s45, s0, 0xfff00080
	s_addc_u32 s46, s1, -1
	s_cmp_eq_u32 s37, 60
	s_cselect_b32 s67, s55, s46
	s_cselect_b32 s66, s54, s45
	s_cselect_b32 s65, s29, s36
	s_cselect_b32 s64, s33, s35
	v_lshl_add_u64 v[166:167], s[0:1], 0, v[138:139]
	s_add_i32 m0, s13, 0xc000
	ds_read_b128 v[206:209], v160
	ds_read_b128 v[212:215], v160 offset:1024
	ds_read_b128 v[216:219], v160 offset:2048
	ds_read_b128 v[220:223], v160 offset:3072
	ds_read_b128 v[224:227], v160 offset:4096
	ds_read_b128 v[228:231], v160 offset:5120
	ds_read_b128 v[232:235], v160 offset:6144
	ds_read_b128 v[236:239], v160 offset:7168
	global_load_lds_dwordx4 v[166:167], off
	v_lshl_add_u64 v[166:167], s[0:1], 0, v[140:141]
	s_add_i32 m0, s13, 0xe000
	s_nop 0
	global_load_lds_dwordx4 v[166:167], off
	s_waitcnt vmcnt(8)
	s_waitcnt lgkmcnt(0)
	s_barrier
	s_setprio 1
	v_mfma_f32_16x16x32_bf16 v[126:129], v[146:149], v[206:209], v[126:129]
	v_mfma_f32_16x16x32_bf16 v[126:129], v[162:165], v[212:215], v[126:129]
	v_mfma_f32_16x16x32_bf16 v[122:125], v[186:189], v[212:215], v[122:125]
	v_mfma_f32_16x16x32_bf16 v[122:125], v[182:185], v[206:209], v[122:125]
	v_mfma_f32_16x16x32_bf16 v[110:113], v[182:185], v[216:219], v[110:113]
	v_mfma_f32_16x16x32_bf16 v[110:113], v[186:189], v[220:223], v[110:113]
	v_mfma_f32_16x16x32_bf16 v[118:121], v[162:165], v[220:223], v[118:121]
	v_mfma_f32_16x16x32_bf16 v[118:121], v[146:149], v[216:219], v[118:121]
	v_mfma_f32_16x16x32_bf16 v[102:105], v[146:149], v[224:227], v[102:105]
	v_mfma_f32_16x16x32_bf16 v[102:105], v[162:165], v[228:231], v[102:105]
	v_mfma_f32_16x16x32_bf16 v[94:97], v[186:189], v[228:231], v[94:97]
	v_mfma_f32_16x16x32_bf16 v[94:97], v[182:185], v[224:227], v[94:97]
	v_mfma_f32_16x16x32_bf16 v[78:81], v[182:185], v[232:235], v[78:81]
	v_mfma_f32_16x16x32_bf16 v[78:81], v[186:189], v[236:239], v[78:81]
	v_mfma_f32_16x16x32_bf16 v[86:89], v[162:165], v[236:239], v[86:89]
	v_mfma_f32_16x16x32_bf16 v[86:89], v[146:149], v[232:235], v[86:89]
	v_mfma_f32_16x16x32_bf16 v[114:117], v[190:193], v[206:209], v[114:117]
	v_mfma_f32_16x16x32_bf16 v[114:117], v[194:197], v[212:215], v[114:117]
	v_mfma_f32_16x16x32_bf16 v[106:109], v[202:205], v[212:215], v[106:109]
	v_mfma_f32_16x16x32_bf16 v[106:109], v[198:201], v[206:209], v[106:109]
	v_mfma_f32_16x16x32_bf16 v[90:93], v[198:201], v[216:219], v[90:93]
	v_mfma_f32_16x16x32_bf16 v[90:93], v[202:205], v[220:223], v[90:93]
	v_mfma_f32_16x16x32_bf16 v[98:101], v[194:197], v[220:223], v[98:101]
	v_mfma_f32_16x16x32_bf16 v[98:101], v[190:193], v[216:219], v[98:101]
	v_mfma_f32_16x16x32_bf16 v[82:85], v[190:193], v[224:227], v[82:85]
	v_mfma_f32_16x16x32_bf16 v[82:85], v[194:197], v[228:231], v[82:85]
	v_mfma_f32_16x16x32_bf16 v[74:77], v[202:205], v[228:231], v[74:77]
	v_mfma_f32_16x16x32_bf16 v[74:77], v[198:201], v[224:227], v[74:77]
	v_mfma_f32_16x16x32_bf16 v[66:69], v[198:201], v[232:235], v[66:69]
	v_mfma_f32_16x16x32_bf16 v[66:69], v[202:205], v[236:239], v[66:69]
	v_mfma_f32_16x16x32_bf16 v[70:73], v[194:197], v[236:239], v[70:73]
	v_mfma_f32_16x16x32_bf16 v[70:73], v[190:193], v[232:235], v[70:73]
	s_setprio 0
	s_barrier
	s_add_i32 s45, s26, s12
	v_lshl_add_u64 v[166:167], s[64:65], 0, v[132:133]
	s_mov_b32 m0, s45
	ds_read_b128 v[206:209], v160 offset:16384
	ds_read_b128 v[212:215], v160 offset:17408
	ds_read_b128 v[216:219], v160 offset:18432
	ds_read_b128 v[220:223], v160 offset:19456
	ds_read_b128 v[224:227], v160 offset:20480
	ds_read_b128 v[228:231], v160 offset:21504
	ds_read_b128 v[232:235], v160 offset:22528
	ds_read_b128 v[236:239], v160 offset:23552
	global_load_lds_dwordx4 v[166:167], off
	s_add_i32 m0, s45, 0x2000
	s_add_u32 s46, s64, 0x100000
	v_lshl_add_u64 v[176:177], s[64:65], 0, v[136:137]
	s_addc_u32 s47, s65, 0
	s_add_i32 s45, s27, s12
	global_load_lds_dwordx4 v[176:177], off
	v_lshl_add_u64 v[240:241], s[46:47], 0, v[132:133]
	s_mov_b32 m0, s45
	v_lshl_add_u64 v[242:243], s[66:67], 0, v[134:135]
	global_load_lds_dwordx4 v[240:241], off
	v_lshl_add_u64 v[240:241], s[46:47], 0, v[136:137]
	s_add_i32 m0, s45, 0x2000
	s_nop 0
	global_load_lds_dwordx4 v[240:241], off
	v_lshl_add_u64 v[240:241], s[66:67], 0, v[130:131]
	s_mov_b32 m0, s13
	s_nop 0
	global_load_lds_dwordx4 v[240:241], off
	s_mov_b32 m0, s18
	s_nop 0
	global_load_lds_dwordx4 v[242:243], off
	s_waitcnt vmcnt(8)
	s_waitcnt lgkmcnt(0)
	s_barrier
; #define PG8_STAGE(bufoff, gbase, voff) do { _Pragma("unroll") for (int _i = 0; _i < 2; ++_i) \
;         __builtin_amdgcn_global_load_lds((const unsigned*)((const char*)(gbase) + (voff)[_i]), (PG8_LAS unsigned*)(lds + (bufoff) + ldsw + _i * 8192), 16, 0, 0); } while (0)
; #define PG8_LDA(dst, b, h) do { _Pragma("unroll") for (int m = 0; m < 4; ++m) _Pragma("unroll") for (int k = 0; k < 2; ++k) dst[m][k] = *(const PG8_LAS bf16x8*)(lds + PG8_SA(b, h) + aoff + m * 2048 + k * 1024); } while (0)
; #define PG8_LDB(dst, b, h) do { _Pragma("unroll") for (int n = 0; n < 2; ++n) _Pragma("unroll") for (int k = 0; k < 2; ++k) dst[n][k] = *(const PG8_LAS bf16x8*)(lds + PG8_SB(b, h) + boff + n * 2048 + k * 1024); } while (0)
; template <class Epi, class Sched, bool ALIGN_EPI = false, bool SP2 = false>
; __device__ __forceinline__ void gemm_phase(PG8_LAS unsigned char* lds, const Gemm g, const Sched& S, const Epi& E) {
;     ...
;         for (int t = 0; t < nt; t += 2) {
;             const bool last = (t == nt - 2);
;             const char* a1 = cA + (size_t)(t + 1) * kstep;
;             const char* a2 = last ? nA : cA + (size_t)(t + 2) * kstep; const char* b2 = last ? nB : cB + (size_t)(t + 2) * kstep;
;             const char* a3 = a2 + kstep; const char* b3 = b2 + kstep;
;             if (last && has_next) S.a_ready(nxt);
;             if constexpr (SP2) {
;             PG8_LDB(B0, 0, 0); PG8_LDB(B1, 0, 1); PG8_SCHED; PG8_LDA(At, 0, 0); PG8_STAGE(PG8_SA(1, 1), a1 + hstepA, voffA);
;             PG8_WAIT_V(8); PG8_WAIT_L(0); PG8_BAR; PG8_MMA(0, 0, At, B0); PG8_MMA(0, 1, At, B1); PG8_BAR; PG8_SCHED;
;             PG8_LDA(At, 0, 1); PG8_STAGE(PG8_SB(0, 0), b2, voffB); PG8_STAGE(PG8_SB(0, 1), b2 + hstepB, voffB); PG8_STAGE(PG8_SA(0, 0), a2, voffA);
;             PG8_WAIT_V(8); PG8_WAIT_L(0); PG8_BAR; PG8_MMA(1, 0, At, B0); PG8_MMA(1, 1, At, B1); PG8_BAR; PG8_SCHED;
;             PG8_LDB(B0, 1, 0); PG8_LDB(B1, 1, 1); PG8_SCHED; PG8_LDA(At, 1, 0); PG8_STAGE(PG8_SA(0, 1), a2 + hstepA, voffA);
;             PG8_WAIT_V(8); PG8_WAIT_L(0); PG8_BAR; PG8_MMA(0, 0, At, B0); PG8_MMA(0, 1, At, B1); PG8_BAR; PG8_SCHED;
;             PG8_LDA(At, 1, 1); PG8_STAGE(PG8_SB(1, 0), b3, voffB); PG8_STAGE(PG8_SB(1, 1), b3 + hstepB, voffB); PG8_STAGE(PG8_SA(1, 0), a3, voffA);
;             PG8_WAIT_V(8); PG8_WAIT_L(0); PG8_BAR; PG8_MMA(1, 0, At, B0); PG8_MMA(1, 1, At, B1); PG8_BAR; PG8_SCHED;
	s_setprio 1
	v_mfma_f32_16x16x32_bf16 v[62:65], v[146:149], v[206:209], v[62:65]
	v_mfma_f32_16x16x32_bf16 v[62:65], v[162:165], v[212:215], v[62:65]
	v_mfma_f32_16x16x32_bf16 v[58:61], v[186:189], v[212:215], v[58:61]
	v_mfma_f32_16x16x32_bf16 v[58:61], v[182:185], v[206:209], v[58:61]
	v_mfma_f32_16x16x32_bf16 v[46:49], v[182:185], v[216:219], v[46:49]
	v_mfma_f32_16x16x32_bf16 v[46:49], v[186:189], v[220:223], v[46:49]
	v_mfma_f32_16x16x32_bf16 v[54:57], v[162:165], v[220:223], v[54:57]
	v_mfma_f32_16x16x32_bf16 v[54:57], v[146:149], v[216:219], v[54:57]
	v_mfma_f32_16x16x32_bf16 v[38:41], v[146:149], v[224:227], v[38:41]
	v_mfma_f32_16x16x32_bf16 v[38:41], v[162:165], v[228:231], v[38:41]
	v_mfma_f32_16x16x32_bf16 v[30:33], v[186:189], v[228:231], v[30:33]
	v_mfma_f32_16x16x32_bf16 v[30:33], v[182:185], v[224:227], v[30:33]
	v_mfma_f32_16x16x32_bf16 v[14:17], v[182:185], v[232:235], v[14:17]
	v_mfma_f32_16x16x32_bf16 v[14:17], v[186:189], v[236:239], v[14:17]
	v_mfma_f32_16x16x32_bf16 v[22:25], v[162:165], v[236:239], v[22:25]
	v_mfma_f32_16x16x32_bf16 v[22:25], v[146:149], v[232:235], v[22:25]
	v_mfma_f32_16x16x32_bf16 v[50:53], v[190:193], v[206:209], v[50:53]
	v_mfma_f32_16x16x32_bf16 v[50:53], v[194:197], v[212:215], v[50:53]
	v_mfma_f32_16x16x32_bf16 v[42:45], v[202:205], v[212:215], v[42:45]
	v_mfma_f32_16x16x32_bf16 v[42:45], v[198:201], v[206:209], v[42:45]
	v_mfma_f32_16x16x32_bf16 v[26:29], v[198:201], v[216:219], v[26:29]
	v_mfma_f32_16x16x32_bf16 v[26:29], v[202:205], v[220:223], v[26:29]
	v_mfma_f32_16x16x32_bf16 v[34:37], v[194:197], v[220:223], v[34:37]
	v_mfma_f32_16x16x32_bf16 v[34:37], v[190:193], v[216:219], v[34:37]
	v_mfma_f32_16x16x32_bf16 v[18:21], v[190:193], v[224:227], v[18:21]
	v_mfma_f32_16x16x32_bf16 v[18:21], v[194:197], v[228:231], v[18:21]
	v_mfma_f32_16x16x32_bf16 v[10:13], v[202:205], v[228:231], v[10:13]
	v_mfma_f32_16x16x32_bf16 v[10:13], v[198:201], v[224:227], v[10:13]
	v_mfma_f32_16x16x32_bf16 v[2:5], v[198:201], v[232:235], v[2:5]
	v_mfma_f32_16x16x32_bf16 v[2:5], v[202:205], v[236:239], v[2:5]
	v_mfma_f32_16x16x32_bf16 v[6:9], v[194:197], v[236:239], v[6:9]
	v_mfma_f32_16x16x32_bf16 v[6:9], v[190:193], v[232:235], v[6:9]
	s_setprio 0
	s_barrier
	s_add_i32 s45, 0, 0x18000
	v_add_u32_e32 v161, s45, v156
	s_add_i32 s49, 0, 0x1c000
	ds_read_b128 v[146:149], v161
	ds_read_b128 v[162:165], v161 offset:1024
	ds_read_b128 v[182:185], v161 offset:2048
	ds_read_b128 v[186:189], v161 offset:3072
	v_add_u32_e32 v161, s49, v156
	ds_read_b128 v[190:193], v161
	ds_read_b128 v[194:197], v161 offset:1024
	ds_read_b128 v[198:201], v161 offset:2048
	ds_read_b128 v[202:205], v161 offset:3072
	s_add_u32 s46, s66, 0x100000
	s_addc_u32 s47, s67, 0
	s_mov_b32 m0, s19
	v_lshl_add_u64 v[244:245], s[46:47], 0, v[130:131]
	ds_read_b128 v[206:209], v160 offset:32768
	ds_read_b128 v[212:215], v160 offset:33792
	ds_read_b128 v[216:219], v160 offset:34816
	ds_read_b128 v[220:223], v160 offset:35840
	ds_read_b128 v[224:227], v160 offset:36864
	ds_read_b128 v[228:231], v160 offset:37888
	ds_read_b128 v[232:235], v160 offset:38912
	ds_read_b128 v[236:239], v160 offset:39936
	global_load_lds_dwordx4 v[244:245], off
	v_lshl_add_u64 v[244:245], s[46:47], 0, v[134:135]
	s_mov_b32 m0, s20
	s_nop 0
	global_load_lds_dwordx4 v[244:245], off
	s_waitcnt vmcnt(8)
	s_waitcnt lgkmcnt(0)
	s_barrier
	s_setprio 1
	v_mfma_f32_16x16x32_bf16 v[126:129], v[146:149], v[206:209], v[126:129]
	v_mfma_f32_16x16x32_bf16 v[126:129], v[162:165], v[212:215], v[126:129]
	v_mfma_f32_16x16x32_bf16 v[122:125], v[186:189], v[212:215], v[122:125]
	v_mfma_f32_16x16x32_bf16 v[122:125], v[182:185], v[206:209], v[122:125]
	v_mfma_f32_16x16x32_bf16 v[110:113], v[182:185], v[216:219], v[110:113]
	v_mfma_f32_16x16x32_bf16 v[110:113], v[186:189], v[220:223], v[110:113]
	v_mfma_f32_16x16x32_bf16 v[118:121], v[162:165], v[220:223], v[118:121]
	v_mfma_f32_16x16x32_bf16 v[118:121], v[146:149], v[216:219], v[118:121]
	v_mfma_f32_16x16x32_bf16 v[102:105], v[146:149], v[224:227], v[102:105]
	v_mfma_f32_16x16x32_bf16 v[102:105], v[162:165], v[228:231], v[102:105]
	v_mfma_f32_16x16x32_bf16 v[94:97], v[186:189], v[228:231], v[94:97]
	v_mfma_f32_16x16x32_bf16 v[94:97], v[182:185], v[224:227], v[94:97]
	v_mfma_f32_16x16x32_bf16 v[78:81], v[182:185], v[232:235], v[78:81]
	v_mfma_f32_16x16x32_bf16 v[78:81], v[186:189], v[236:239], v[78:81]
	v_mfma_f32_16x16x32_bf16 v[86:89], v[162:165], v[236:239], v[86:89]
	v_mfma_f32_16x16x32_bf16 v[86:89], v[146:149], v[232:235], v[86:89]
	v_mfma_f32_16x16x32_bf16 v[114:117], v[190:193], v[206:209], v[114:117]
	v_mfma_f32_16x16x32_bf16 v[114:117], v[194:197], v[212:215], v[114:117]
	v_mfma_f32_16x16x32_bf16 v[106:109], v[202:205], v[212:215], v[106:109]
	v_mfma_f32_16x16x32_bf16 v[106:109], v[198:201], v[206:209], v[106:109]
	v_mfma_f32_16x16x32_bf16 v[90:93], v[198:201], v[216:219], v[90:93]
	v_mfma_f32_16x16x32_bf16 v[90:93], v[202:205], v[220:223], v[90:93]
	v_mfma_f32_16x16x32_bf16 v[98:101], v[194:197], v[220:223], v[98:101]
	v_mfma_f32_16x16x32_bf16 v[98:101], v[190:193], v[216:219], v[98:101]
	v_mfma_f32_16x16x32_bf16 v[82:85], v[190:193], v[224:227], v[82:85]
	v_mfma_f32_16x16x32_bf16 v[82:85], v[194:197], v[228:231], v[82:85]
	v_mfma_f32_16x16x32_bf16 v[74:77], v[202:205], v[228:231], v[74:77]
	v_mfma_f32_16x16x32_bf16 v[74:77], v[198:201], v[224:227], v[74:77]
	v_mfma_f32_16x16x32_bf16 v[66:69], v[198:201], v[232:235], v[66:69]
	v_mfma_f32_16x16x32_bf16 v[66:69], v[202:205], v[236:239], v[66:69]
	v_mfma_f32_16x16x32_bf16 v[70:73], v[194:197], v[236:239], v[70:73]
	v_mfma_f32_16x16x32_bf16 v[70:73], v[190:193], v[232:235], v[70:73]
	s_setprio 0
	s_barrier
; #define PG8_STAGE(bufoff, gbase, voff) do { _Pragma("unroll") for (int _i = 0; _i < 2; ++_i) \
;         __builtin_amdgcn_global_load_lds((const unsigned*)((const char*)(gbase) + (voff)[_i]), (PG8_LAS unsigned*)(lds + (bufoff) + ldsw + _i * 8192), 16, 0, 0); } while (0)
; #define PG8_LDA(dst, b, h) do { _Pragma("unroll") for (int m = 0; m < 4; ++m) _Pragma("unroll") for (int k = 0; k < 2; ++k) dst[m][k] = *(const PG8_LAS bf16x8*)(lds + PG8_SA(b, h) + aoff + m * 2048 + k * 1024); } while (0)
; #define PG8_LDB(dst, b, h) do { _Pragma("unroll") for (int n = 0; n < 2; ++n) _Pragma("unroll") for (int k = 0; k < 2; ++k) dst[n][k] = *(const PG8_LAS bf16x8*)(lds + PG8_SB(b, h) + boff + n * 2048 + k * 1024); } while (0)
; template <class Epi, class Sched, bool ALIGN_EPI = false, bool SP2 = false>
; __device__ __forceinline__ void gemm_phase(PG8_LAS unsigned char* lds, const Gemm g, const Sched& S, const Epi& E) {
;     ...
;         for (int t = 0; t < nt; t += 2) {
;             const bool last = (t == nt - 2);
;             const char* a1 = cA + (size_t)(t + 1) * kstep;
;             const char* a2 = last ? nA : cA + (size_t)(t + 2) * kstep; const char* b2 = last ? nB : cB + (size_t)(t + 2) * kstep;
;             const char* a3 = a2 + kstep; const char* b3 = b2 + kstep;
;             if (last && has_next) S.a_ready(nxt);
;             if constexpr (SP2) {
;             PG8_LDB(B0, 0, 0); PG8_LDB(B1, 0, 1); PG8_SCHED; PG8_LDA(At, 0, 0); PG8_STAGE(PG8_SA(1, 1), a1 + hstepA, voffA);
;             PG8_WAIT_V(8); PG8_WAIT_L(0); PG8_BAR; PG8_MMA(0, 0, At, B0); PG8_MMA(0, 1, At, B1); PG8_BAR; PG8_SCHED;
;             PG8_LDA(At, 0, 1); PG8_STAGE(PG8_SB(0, 0), b2, voffB); PG8_STAGE(PG8_SB(0, 1), b2 + hstepB, voffB); PG8_STAGE(PG8_SA(0, 0), a2, voffA);
;             PG8_WAIT_V(8); PG8_WAIT_L(0); PG8_BAR; PG8_MMA(1, 0, At, B0); PG8_MMA(1, 1, At, B1); PG8_BAR; PG8_SCHED;
;             PG8_LDB(B0, 1, 0); PG8_LDB(B1, 1, 1); PG8_SCHED; PG8_LDA(At, 1, 0); PG8_STAGE(PG8_SA(0, 1), a2 + hstepA, voffA);
;             PG8_WAIT_V(8); PG8_WAIT_L(0); PG8_BAR; PG8_MMA(0, 0, At, B0); PG8_MMA(0, 1, At, B1); PG8_BAR; PG8_SCHED;
;             PG8_LDA(At, 1, 1); PG8_STAGE(PG8_SB(1, 0), b3, voffB); PG8_STAGE(PG8_SB(1, 1), b3 + hstepB, voffB); PG8_STAGE(PG8_SA(1, 0), a3, voffA);
;             PG8_WAIT_V(8); PG8_WAIT_L(0); PG8_BAR; PG8_MMA(1, 0, At, B0); PG8_MMA(1, 1, At, B1); PG8_BAR; PG8_SCHED;
	s_add_i32 s45, s45, s12
	v_lshl_add_u64 v[166:167], v[166:167], 0, s[40:41]
	s_mov_b32 m0, s45
	ds_read_b128 v[206:209], v160 offset:49152
	ds_read_b128 v[212:215], v160 offset:50176
	ds_read_b128 v[216:219], v160 offset:51200
	ds_read_b128 v[220:223], v160 offset:52224
	ds_read_b128 v[224:227], v160 offset:53248
	ds_read_b128 v[228:231], v160 offset:54272
	ds_read_b128 v[232:235], v160 offset:55296
	ds_read_b128 v[236:239], v160 offset:56320
	global_load_lds_dwordx4 v[166:167], off
	s_add_i32 m0, s45, 0x2000
	s_add_u32 s46, s64, 0x100080
	v_lshl_add_u64 v[166:167], v[176:177], 0, s[40:41]
	s_addc_u32 s47, s65, 0
	s_add_i32 s45, s49, s12
	global_load_lds_dwordx4 v[166:167], off
	v_lshl_add_u64 v[166:167], s[46:47], 0, v[132:133]
	s_mov_b32 m0, s45
	s_nop 0
	global_load_lds_dwordx4 v[166:167], off
	v_lshl_add_u64 v[166:167], s[46:47], 0, v[136:137]
	s_add_i32 m0, s45, 0x2000
	s_nop 0
	global_load_lds_dwordx4 v[166:167], off
	v_lshl_add_u64 v[166:167], v[240:241], 0, s[40:41]
	s_mov_b32 m0, s22
	s_nop 0
	global_load_lds_dwordx4 v[166:167], off
	v_lshl_add_u64 v[166:167], v[242:243], 0, s[40:41]
	s_mov_b32 m0, s23
	s_nop 0
	global_load_lds_dwordx4 v[166:167], off
	s_waitcnt vmcnt(8)
	s_waitcnt lgkmcnt(0)
	s_barrier
	s_setprio 1
	v_mfma_f32_16x16x32_bf16 v[62:65], v[146:149], v[206:209], v[62:65]
	v_mfma_f32_16x16x32_bf16 v[62:65], v[162:165], v[212:215], v[62:65]
	v_mfma_f32_16x16x32_bf16 v[58:61], v[186:189], v[212:215], v[58:61]
	v_mfma_f32_16x16x32_bf16 v[58:61], v[182:185], v[206:209], v[58:61]
	v_mfma_f32_16x16x32_bf16 v[46:49], v[182:185], v[216:219], v[46:49]
	v_mfma_f32_16x16x32_bf16 v[46:49], v[186:189], v[220:223], v[46:49]
	v_mfma_f32_16x16x32_bf16 v[54:57], v[162:165], v[220:223], v[54:57]
	v_mfma_f32_16x16x32_bf16 v[54:57], v[146:149], v[216:219], v[54:57]
	v_mfma_f32_16x16x32_bf16 v[38:41], v[146:149], v[224:227], v[38:41]
	v_mfma_f32_16x16x32_bf16 v[38:41], v[162:165], v[228:231], v[38:41]
	v_mfma_f32_16x16x32_bf16 v[30:33], v[186:189], v[228:231], v[30:33]
	v_mfma_f32_16x16x32_bf16 v[30:33], v[182:185], v[224:227], v[30:33]
	v_mfma_f32_16x16x32_bf16 v[14:17], v[182:185], v[232:235], v[14:17]
	v_mfma_f32_16x16x32_bf16 v[14:17], v[186:189], v[236:239], v[14:17]
	v_mfma_f32_16x16x32_bf16 v[22:25], v[162:165], v[236:239], v[22:25]
	v_mfma_f32_16x16x32_bf16 v[22:25], v[146:149], v[232:235], v[22:25]
	v_mfma_f32_16x16x32_bf16 v[50:53], v[190:193], v[206:209], v[50:53]
	v_mfma_f32_16x16x32_bf16 v[50:53], v[194:197], v[212:215], v[50:53]
	v_mfma_f32_16x16x32_bf16 v[42:45], v[202:205], v[212:215], v[42:45]
	v_mfma_f32_16x16x32_bf16 v[42:45], v[198:201], v[206:209], v[42:45]
	v_mfma_f32_16x16x32_bf16 v[26:29], v[198:201], v[216:219], v[26:29]
	v_mfma_f32_16x16x32_bf16 v[26:29], v[202:205], v[220:223], v[26:29]
	v_mfma_f32_16x16x32_bf16 v[34:37], v[194:197], v[220:223], v[34:37]
	v_mfma_f32_16x16x32_bf16 v[34:37], v[190:193], v[216:219], v[34:37]
	v_mfma_f32_16x16x32_bf16 v[18:21], v[190:193], v[224:227], v[18:21]
	v_mfma_f32_16x16x32_bf16 v[18:21], v[194:197], v[228:231], v[18:21]
	v_mfma_f32_16x16x32_bf16 v[10:13], v[202:205], v[228:231], v[10:13]
	v_mfma_f32_16x16x32_bf16 v[10:13], v[198:201], v[224:227], v[10:13]
	v_mfma_f32_16x16x32_bf16 v[2:5], v[198:201], v[232:235], v[2:5]
	v_mfma_f32_16x16x32_bf16 v[2:5], v[202:205], v[236:239], v[2:5]
	v_mfma_f32_16x16x32_bf16 v[6:9], v[194:197], v[236:239], v[6:9]
	v_mfma_f32_16x16x32_bf16 v[6:9], v[190:193], v[232:235], v[6:9]
	s_setprio 0
	s_barrier
	s_add_i32 s37, s37, 2
	s_add_u32 s0, s0, 0x100
	s_addc_u32 s1, s1, 0
	s_add_u32 s35, s35, 0x100
	s_addc_u32 s36, s36, 0
	s_cmp_gt_u32 s37, 61
	s_cbranch_scc0 .LBB0_231
	s_and_b64 vcc, exec, s[42:43]
	s_cbranch_vccz .LBB0_234
	s_barrier

; #define PG8_STAGE(bufoff, gbase, voff) do { _Pragma("unroll") for (int _i = 0; _i < 2; ++_i) \
;         __builtin_amdgcn_global_load_lds((const unsigned*)((const char*)(gbase) + (voff)[_i]), (PG8_LAS unsigned*)(lds + (bufoff) + ldsw + _i * 8192), 16, 0, 0); } while (0)
; #define PG8_LDA(dst, b, h) do { _Pragma("unroll") for (int m = 0; m < 4; ++m) _Pragma("unroll") for (int k = 0; k < 2; ++k) dst[m][k] = *(const PG8_LAS bf16x8*)(lds + PG8_SA(b, h) + aoff + m * 2048 + k * 1024); } while (0)
; #define PG8_LDB(dst, b, h) do { _Pragma("unroll") for (int n = 0; n < 2; ++n) _Pragma("unroll") for (int k = 0; k < 2; ++k) dst[n][k] = *(const PG8_LAS bf16x8*)(lds + PG8_SB(b, h) + boff + n * 2048 + k * 1024); } while (0)
; template <class Epi, class Sched, bool ALIGN_EPI = false, bool SP2 = false>
; __device__ __forceinline__ void gemm_phase(PG8_LAS unsigned char* lds, const Gemm g, const Sched& S, const Epi& E) {
;     ...
;         for (int t = 0; t < nt; t += 2) {
;             const bool last = (t == nt - 2);
;             const char* a1 = cA + (size_t)(t + 1) * kstep;
;             const char* a2 = last ? nA : cA + (size_t)(t + 2) * kstep; const char* b2 = last ? nB : cB + (size_t)(t + 2) * kstep;
;             const char* a3 = a2 + kstep; const char* b3 = b2 + kstep;
;             if (last && has_next) S.a_ready(nxt);
;             if constexpr (SP2) {
;             PG8_LDB(B0, 0, 0); PG8_LDB(B1, 0, 1); PG8_SCHED; PG8_LDA(At, 0, 0); PG8_STAGE(PG8_SA(1, 1), a1 + hstepA, voffA);
;             PG8_WAIT_V(8); PG8_WAIT_L(0); PG8_BAR; PG8_MMA(0, 0, At, B0); PG8_MMA(0, 1, At, B1); PG8_BAR; PG8_SCHED;
;             PG8_LDA(At, 0, 1); PG8_STAGE(PG8_SB(0, 0), b2, voffB); PG8_STAGE(PG8_SB(0, 1), b2 + hstepB, voffB); PG8_STAGE(PG8_SA(0, 0), a2, voffA);
;             PG8_WAIT_V(8); PG8_WAIT_L(0); PG8_BAR; PG8_MMA(1, 0, At, B0); PG8_MMA(1, 1, At, B1); PG8_BAR; PG8_SCHED;
;             PG8_LDB(B0, 1, 0); PG8_LDB(B1, 1, 1); PG8_SCHED; PG8_LDA(At, 1, 0); PG8_STAGE(PG8_SA(0, 1), a2 + hstepA, voffA);
;             PG8_WAIT_V(8); PG8_WAIT_L(0); PG8_BAR; PG8_MMA(0, 0, At, B0); PG8_MMA(0, 1, At, B1); PG8_BAR; PG8_SCHED;
;             PG8_LDA(At, 1, 1); PG8_STAGE(PG8_SB(1, 0), b3, voffB); PG8_STAGE(PG8_SB(1, 1), b3 + hstepB, voffB); PG8_STAGE(PG8_SA(1, 0), a3, voffA);
;             PG8_WAIT_V(8); PG8_WAIT_L(0); PG8_BAR; PG8_MMA(1, 0, At, B0); PG8_MMA(1, 1, At, B1); PG8_BAR; PG8_SCHED;
.LBB0_249:
	ds_read_b128 v[122:125], v181
	ds_read_b128 v[126:129], v181 offset:1024
	ds_read_b128 v[134:137], v181 offset:2048
	ds_read_b128 v[142:145], v181 offset:3072
	ds_read_b128 v[184:187], v182
	ds_read_b128 v[188:191], v182 offset:1024
	ds_read_b128 v[192:195], v182 offset:2048
	ds_read_b128 v[196:199], v182 offset:3072
	s_add_u32 s51, s0, 0xfff80080
	s_addc_u32 s63, s1, -1
	s_cmp_eq_u32 s50, 28
	s_cselect_b32 s95, s65, s63
	s_cselect_b32 s94, s64, s51
	s_cselect_b32 s91, s36, s47
	s_cselect_b32 s90, s37, s46
	v_lshl_add_u64 v[166:167], s[0:1], 0, v[158:159]
	s_add_i32 m0, s13, 0xc000
	ds_read_b128 v[200:203], v183
	ds_read_b128 v[204:207], v183 offset:1024
	ds_read_b128 v[212:215], v183 offset:2048
	ds_read_b128 v[216:219], v183 offset:3072
	ds_read_b128 v[220:223], v183 offset:4096
	ds_read_b128 v[224:227], v183 offset:5120
	ds_read_b128 v[228:231], v183 offset:6144
	ds_read_b128 v[232:235], v183 offset:7168
	global_load_lds_dwordx4 v[166:167], off
	v_lshl_add_u64 v[166:167], s[0:1], 0, v[160:161]
	s_add_i32 m0, s13, 0xe000
	s_nop 0
	global_load_lds_dwordx4 v[166:167], off
	s_waitcnt vmcnt(8)
	s_waitcnt lgkmcnt(0)
	s_barrier
	s_setprio 1
	v_mfma_i32_16x16x64_i8 v[138:141], v[122:125], v[200:203], v[138:141]
	v_mfma_i32_16x16x64_i8 v[138:141], v[126:129], v[204:207], v[138:141]
	v_mfma_i32_16x16x64_i8 v[130:133], v[142:145], v[204:207], v[130:133]
	v_mfma_i32_16x16x64_i8 v[130:133], v[134:137], v[200:203], v[130:133]
	v_mfma_i32_16x16x64_i8 v[106:109], v[134:137], v[212:215], v[106:109]
	v_mfma_i32_16x16x64_i8 v[106:109], v[142:145], v[216:219], v[106:109]
	v_mfma_i32_16x16x64_i8 v[110:113], v[126:129], v[216:219], v[110:113]
	v_mfma_i32_16x16x64_i8 v[110:113], v[122:125], v[212:215], v[110:113]
	v_mfma_i32_16x16x64_i8 v[94:97], v[122:125], v[220:223], v[94:97]
	v_mfma_i32_16x16x64_i8 v[94:97], v[126:129], v[224:227], v[94:97]
	v_mfma_i32_16x16x64_i8 v[90:93], v[142:145], v[224:227], v[90:93]
	v_mfma_i32_16x16x64_i8 v[90:93], v[134:137], v[220:223], v[90:93]
	v_mfma_i32_16x16x64_i8 v[74:77], v[134:137], v[228:231], v[74:77]
	v_mfma_i32_16x16x64_i8 v[74:77], v[142:145], v[232:235], v[74:77]
	v_mfma_i32_16x16x64_i8 v[78:81], v[126:129], v[232:235], v[78:81]
	v_mfma_i32_16x16x64_i8 v[78:81], v[122:125], v[228:231], v[78:81]
	v_mfma_i32_16x16x64_i8 v[118:121], v[184:187], v[200:203], v[118:121]
	v_mfma_i32_16x16x64_i8 v[118:121], v[188:191], v[204:207], v[118:121]
	v_mfma_i32_16x16x64_i8 v[114:117], v[196:199], v[204:207], v[114:117]
	v_mfma_i32_16x16x64_i8 v[114:117], v[192:195], v[200:203], v[114:117]
	v_mfma_i32_16x16x64_i8 v[98:101], v[192:195], v[212:215], v[98:101]
	v_mfma_i32_16x16x64_i8 v[98:101], v[196:199], v[216:219], v[98:101]
	v_mfma_i32_16x16x64_i8 v[102:105], v[188:191], v[216:219], v[102:105]
	v_mfma_i32_16x16x64_i8 v[102:105], v[184:187], v[212:215], v[102:105]
	v_mfma_i32_16x16x64_i8 v[86:89], v[184:187], v[220:223], v[86:89]
	v_mfma_i32_16x16x64_i8 v[86:89], v[188:191], v[224:227], v[86:89]
	v_mfma_i32_16x16x64_i8 v[82:85], v[196:199], v[224:227], v[82:85]
	v_mfma_i32_16x16x64_i8 v[82:85], v[192:195], v[220:223], v[82:85]
	v_mfma_i32_16x16x64_i8 v[66:69], v[192:195], v[228:231], v[66:69]
	v_mfma_i32_16x16x64_i8 v[66:69], v[196:199], v[232:235], v[66:69]
	v_mfma_i32_16x16x64_i8 v[70:73], v[188:191], v[232:235], v[70:73]
	v_mfma_i32_16x16x64_i8 v[70:73], v[184:187], v[228:231], v[70:73]
	s_setprio 0
	s_barrier
	s_add_i32 s51, s27, s7
	v_lshl_add_u64 v[166:167], s[90:91], 0, v[148:149]
	s_mov_b32 m0, s51
	ds_read_b128 v[200:203], v183 offset:16384
	ds_read_b128 v[204:207], v183 offset:17408
	ds_read_b128 v[212:215], v183 offset:18432
	ds_read_b128 v[216:219], v183 offset:19456
	ds_read_b128 v[220:223], v183 offset:20480
	ds_read_b128 v[224:227], v183 offset:21504
	ds_read_b128 v[228:231], v183 offset:22528
	ds_read_b128 v[232:235], v183 offset:23552
	global_load_lds_dwordx4 v[166:167], off
	s_add_i32 m0, s51, 0x2000
	s_add_u32 s68, s90, 0x80000
	v_lshl_add_u64 v[208:209], s[90:91], 0, v[152:153]
	s_addc_u32 s69, s91, 0
	s_add_i32 s51, s28, s7
	global_load_lds_dwordx4 v[208:209], off
	v_lshl_add_u64 v[236:237], s[68:69], 0, v[148:149]
	s_mov_b32 m0, s51
	v_lshl_add_u64 v[238:239], s[94:95], 0, v[150:151]
	global_load_lds_dwordx4 v[236:237], off
	v_lshl_add_u64 v[236:237], s[68:69], 0, v[152:153]
	s_add_i32 m0, s51, 0x2000
	s_nop 0
	global_load_lds_dwordx4 v[236:237], off
	v_lshl_add_u64 v[236:237], s[94:95], 0, v[146:147]
	s_mov_b32 m0, s13
	s_nop 0
	global_load_lds_dwordx4 v[236:237], off
	s_mov_b32 m0, s18
	s_nop 0
	global_load_lds_dwordx4 v[238:239], off
	s_waitcnt vmcnt(8)
	s_waitcnt lgkmcnt(0)
	s_barrier
; #define PG8_STAGE(bufoff, gbase, voff) do { _Pragma("unroll") for (int _i = 0; _i < 2; ++_i) \
;         __builtin_amdgcn_global_load_lds((const unsigned*)((const char*)(gbase) + (voff)[_i]), (PG8_LAS unsigned*)(lds + (bufoff) + ldsw + _i * 8192), 16, 0, 0); } while (0)
; #define PG8_LDA(dst, b, h) do { _Pragma("unroll") for (int m = 0; m < 4; ++m) _Pragma("unroll") for (int k = 0; k < 2; ++k) dst[m][k] = *(const PG8_LAS bf16x8*)(lds + PG8_SA(b, h) + aoff + m * 2048 + k * 1024); } while (0)
; #define PG8_LDB(dst, b, h) do { _Pragma("unroll") for (int n = 0; n < 2; ++n) _Pragma("unroll") for (int k = 0; k < 2; ++k) dst[n][k] = *(const PG8_LAS bf16x8*)(lds + PG8_SB(b, h) + boff + n * 2048 + k * 1024); } while (0)
; template <class Epi, class Sched, bool ALIGN_EPI = false, bool SP2 = false>
; __device__ __forceinline__ void gemm_phase(PG8_LAS unsigned char* lds, const Gemm g, const Sched& S, const Epi& E) {
;     ...
;         for (int t = 0; t < nt; t += 2) {
;             const bool last = (t == nt - 2);
;             const char* a1 = cA + (size_t)(t + 1) * kstep;
;             const char* a2 = last ? nA : cA + (size_t)(t + 2) * kstep; const char* b2 = last ? nB : cB + (size_t)(t + 2) * kstep;
;             const char* a3 = a2 + kstep; const char* b3 = b2 + kstep;
;             if (last && has_next) S.a_ready(nxt);
;             if constexpr (SP2) {
;             PG8_LDB(B0, 0, 0); PG8_LDB(B1, 0, 1); PG8_SCHED; PG8_LDA(At, 0, 0); PG8_STAGE(PG8_SA(1, 1), a1 + hstepA, voffA);
;             PG8_WAIT_V(8); PG8_WAIT_L(0); PG8_BAR; PG8_MMA(0, 0, At, B0); PG8_MMA(0, 1, At, B1); PG8_BAR; PG8_SCHED;
;             PG8_LDA(At, 0, 1); PG8_STAGE(PG8_SB(0, 0), b2, voffB); PG8_STAGE(PG8_SB(0, 1), b2 + hstepB, voffB); PG8_STAGE(PG8_SA(0, 0), a2, voffA);
;             PG8_WAIT_V(8); PG8_WAIT_L(0); PG8_BAR; PG8_MMA(1, 0, At, B0); PG8_MMA(1, 1, At, B1); PG8_BAR; PG8_SCHED;
;             PG8_LDB(B0, 1, 0); PG8_LDB(B1, 1, 1); PG8_SCHED; PG8_LDA(At, 1, 0); PG8_STAGE(PG8_SA(0, 1), a2 + hstepA, voffA);
;             PG8_WAIT_V(8); PG8_WAIT_L(0); PG8_BAR; PG8_MMA(0, 0, At, B0); PG8_MMA(0, 1, At, B1); PG8_BAR; PG8_SCHED;
;             PG8_LDA(At, 1, 1); PG8_STAGE(PG8_SB(1, 0), b3, voffB); PG8_STAGE(PG8_SB(1, 1), b3 + hstepB, voffB); PG8_STAGE(PG8_SA(1, 0), a3, voffA);
;             PG8_WAIT_V(8); PG8_WAIT_L(0); PG8_BAR; PG8_MMA(1, 0, At, B0); PG8_MMA(1, 1, At, B1); PG8_BAR; PG8_SCHED;
	s_setprio 1
	v_mfma_i32_16x16x64_i8 v[62:65], v[122:125], v[200:203], v[62:65]
	v_mfma_i32_16x16x64_i8 v[62:65], v[126:129], v[204:207], v[62:65]
	v_mfma_i32_16x16x64_i8 v[58:61], v[142:145], v[204:207], v[58:61]
	v_mfma_i32_16x16x64_i8 v[58:61], v[134:137], v[200:203], v[58:61]
	v_mfma_i32_16x16x64_i8 v[42:45], v[134:137], v[212:215], v[42:45]
	v_mfma_i32_16x16x64_i8 v[42:45], v[142:145], v[216:219], v[42:45]
	v_mfma_i32_16x16x64_i8 v[46:49], v[126:129], v[216:219], v[46:49]
	v_mfma_i32_16x16x64_i8 v[46:49], v[122:125], v[212:215], v[46:49]
	v_mfma_i32_16x16x64_i8 v[30:33], v[122:125], v[220:223], v[30:33]
	v_mfma_i32_16x16x64_i8 v[30:33], v[126:129], v[224:227], v[30:33]
	v_mfma_i32_16x16x64_i8 v[26:29], v[142:145], v[224:227], v[26:29]
	v_mfma_i32_16x16x64_i8 v[26:29], v[134:137], v[220:223], v[26:29]
	v_mfma_i32_16x16x64_i8 v[10:13], v[134:137], v[228:231], v[10:13]
	v_mfma_i32_16x16x64_i8 v[10:13], v[142:145], v[232:235], v[10:13]
	v_mfma_i32_16x16x64_i8 v[14:17], v[126:129], v[232:235], v[14:17]
	v_mfma_i32_16x16x64_i8 v[14:17], v[122:125], v[228:231], v[14:17]
	v_mfma_i32_16x16x64_i8 v[54:57], v[184:187], v[200:203], v[54:57]
	v_mfma_i32_16x16x64_i8 v[54:57], v[188:191], v[204:207], v[54:57]
	v_mfma_i32_16x16x64_i8 v[50:53], v[196:199], v[204:207], v[50:53]
	v_mfma_i32_16x16x64_i8 v[50:53], v[192:195], v[200:203], v[50:53]
	v_mfma_i32_16x16x64_i8 v[34:37], v[192:195], v[212:215], v[34:37]
	v_mfma_i32_16x16x64_i8 v[34:37], v[196:199], v[216:219], v[34:37]
	v_mfma_i32_16x16x64_i8 v[38:41], v[188:191], v[216:219], v[38:41]
	v_mfma_i32_16x16x64_i8 v[38:41], v[184:187], v[212:215], v[38:41]
	v_mfma_i32_16x16x64_i8 v[22:25], v[184:187], v[220:223], v[22:25]
	v_mfma_i32_16x16x64_i8 v[22:25], v[188:191], v[224:227], v[22:25]
	v_mfma_i32_16x16x64_i8 v[18:21], v[196:199], v[224:227], v[18:21]
	v_mfma_i32_16x16x64_i8 v[18:21], v[192:195], v[220:223], v[18:21]
	v_mfma_i32_16x16x64_i8 v[2:5], v[192:195], v[228:231], v[2:5]
	v_mfma_i32_16x16x64_i8 v[2:5], v[196:199], v[232:235], v[2:5]
	v_mfma_i32_16x16x64_i8 v[6:9], v[188:191], v[232:235], v[6:9]
	v_mfma_i32_16x16x64_i8 v[6:9], v[184:187], v[228:231], v[6:9]
	s_setprio 0
	s_barrier
	s_add_i32 s51, 0, 0x18000
	s_add_i32 s63, 0, 0x1c000
	v_add_u32_e32 v142, s51, v176
	v_add_u32_e32 v196, s63, v176
	ds_read_b128 v[122:125], v142
	ds_read_b128 v[126:129], v142 offset:1024
	ds_read_b128 v[134:137], v142 offset:2048
	ds_read_b128 v[142:145], v142 offset:3072
	ds_read_b128 v[184:187], v196
	ds_read_b128 v[188:191], v196 offset:1024
	ds_read_b128 v[192:195], v196 offset:2048
	ds_read_b128 v[196:199], v196 offset:3072
	s_add_u32 s68, s94, 0x80000
	s_addc_u32 s69, s95, 0
	s_mov_b32 m0, s19
	v_lshl_add_u64 v[240:241], s[68:69], 0, v[146:147]
	ds_read_b128 v[200:203], v183 offset:32768
	ds_read_b128 v[204:207], v183 offset:33792
	ds_read_b128 v[212:215], v183 offset:34816
	ds_read_b128 v[216:219], v183 offset:35840
	ds_read_b128 v[220:223], v183 offset:36864
	ds_read_b128 v[224:227], v183 offset:37888
	ds_read_b128 v[228:231], v183 offset:38912
	ds_read_b128 v[232:235], v183 offset:39936
	global_load_lds_dwordx4 v[240:241], off
	v_lshl_add_u64 v[240:241], s[68:69], 0, v[150:151]
	s_mov_b32 m0, s20
	s_nop 0
	global_load_lds_dwordx4 v[240:241], off
	s_waitcnt vmcnt(8)
	s_waitcnt lgkmcnt(0)
	s_barrier
	s_setprio 1
	v_mfma_i32_16x16x64_i8 v[138:141], v[122:125], v[200:203], v[138:141]
	v_mfma_i32_16x16x64_i8 v[138:141], v[126:129], v[204:207], v[138:141]
	v_mfma_i32_16x16x64_i8 v[130:133], v[142:145], v[204:207], v[130:133]
	v_mfma_i32_16x16x64_i8 v[130:133], v[134:137], v[200:203], v[130:133]
	v_mfma_i32_16x16x64_i8 v[106:109], v[134:137], v[212:215], v[106:109]
	v_mfma_i32_16x16x64_i8 v[106:109], v[142:145], v[216:219], v[106:109]
	v_mfma_i32_16x16x64_i8 v[110:113], v[126:129], v[216:219], v[110:113]
	v_mfma_i32_16x16x64_i8 v[110:113], v[122:125], v[212:215], v[110:113]
	v_mfma_i32_16x16x64_i8 v[94:97], v[122:125], v[220:223], v[94:97]
	v_mfma_i32_16x16x64_i8 v[94:97], v[126:129], v[224:227], v[94:97]
	v_mfma_i32_16x16x64_i8 v[90:93], v[142:145], v[224:227], v[90:93]
	v_mfma_i32_16x16x64_i8 v[90:93], v[134:137], v[220:223], v[90:93]
	v_mfma_i32_16x16x64_i8 v[74:77], v[134:137], v[228:231], v[74:77]
	v_mfma_i32_16x16x64_i8 v[74:77], v[142:145], v[232:235], v[74:77]
	v_mfma_i32_16x16x64_i8 v[78:81], v[126:129], v[232:235], v[78:81]
	v_mfma_i32_16x16x64_i8 v[78:81], v[122:125], v[228:231], v[78:81]
	v_mfma_i32_16x16x64_i8 v[118:121], v[184:187], v[200:203], v[118:121]
	v_mfma_i32_16x16x64_i8 v[118:121], v[188:191], v[204:207], v[118:121]
	v_mfma_i32_16x16x64_i8 v[114:117], v[196:199], v[204:207], v[114:117]
	v_mfma_i32_16x16x64_i8 v[114:117], v[192:195], v[200:203], v[114:117]
	v_mfma_i32_16x16x64_i8 v[98:101], v[192:195], v[212:215], v[98:101]
	v_mfma_i32_16x16x64_i8 v[98:101], v[196:199], v[216:219], v[98:101]
	v_mfma_i32_16x16x64_i8 v[102:105], v[188:191], v[216:219], v[102:105]
	v_mfma_i32_16x16x64_i8 v[102:105], v[184:187], v[212:215], v[102:105]
	v_mfma_i32_16x16x64_i8 v[86:89], v[184:187], v[220:223], v[86:89]
	v_mfma_i32_16x16x64_i8 v[86:89], v[188:191], v[224:227], v[86:89]
	v_mfma_i32_16x16x64_i8 v[82:85], v[196:199], v[224:227], v[82:85]
	v_mfma_i32_16x16x64_i8 v[82:85], v[192:195], v[220:223], v[82:85]
	v_mfma_i32_16x16x64_i8 v[66:69], v[192:195], v[228:231], v[66:69]
	v_mfma_i32_16x16x64_i8 v[66:69], v[196:199], v[232:235], v[66:69]
	v_mfma_i32_16x16x64_i8 v[70:73], v[188:191], v[232:235], v[70:73]
	v_mfma_i32_16x16x64_i8 v[70:73], v[184:187], v[228:231], v[70:73]
	s_setprio 0
	s_barrier
; #define PG8_STAGE(bufoff, gbase, voff) do { _Pragma("unroll") for (int _i = 0; _i < 2; ++_i) \
;         __builtin_amdgcn_global_load_lds((const unsigned*)((const char*)(gbase) + (voff)[_i]), (PG8_LAS unsigned*)(lds + (bufoff) + ldsw + _i * 8192), 16, 0, 0); } while (0)
; #define PG8_LDA(dst, b, h) do { _Pragma("unroll") for (int m = 0; m < 4; ++m) _Pragma("unroll") for (int k = 0; k < 2; ++k) dst[m][k] = *(const PG8_LAS bf16x8*)(lds + PG8_SA(b, h) + aoff + m * 2048 + k * 1024); } while (0)
; #define PG8_LDB(dst, b, h) do { _Pragma("unroll") for (int n = 0; n < 2; ++n) _Pragma("unroll") for (int k = 0; k < 2; ++k) dst[n][k] = *(const PG8_LAS bf16x8*)(lds + PG8_SB(b, h) + boff + n * 2048 + k * 1024); } while (0)
; template <class Epi, class Sched, bool ALIGN_EPI = false, bool SP2 = false>
; __device__ __forceinline__ void gemm_phase(PG8_LAS unsigned char* lds, const Gemm g, const Sched& S, const Epi& E) {
;     ...
;         for (int t = 0; t < nt; t += 2) {
;             const bool last = (t == nt - 2);
;             const char* a1 = cA + (size_t)(t + 1) * kstep;
;             const char* a2 = last ? nA : cA + (size_t)(t + 2) * kstep; const char* b2 = last ? nB : cB + (size_t)(t + 2) * kstep;
;             const char* a3 = a2 + kstep; const char* b3 = b2 + kstep;
;             if (last && has_next) S.a_ready(nxt);
;             if constexpr (SP2) {
;             PG8_LDB(B0, 0, 0); PG8_LDB(B1, 0, 1); PG8_SCHED; PG8_LDA(At, 0, 0); PG8_STAGE(PG8_SA(1, 1), a1 + hstepA, voffA);
;             PG8_WAIT_V(8); PG8_WAIT_L(0); PG8_BAR; PG8_MMA(0, 0, At, B0); PG8_MMA(0, 1, At, B1); PG8_BAR; PG8_SCHED;
;             PG8_LDA(At, 0, 1); PG8_STAGE(PG8_SB(0, 0), b2, voffB); PG8_STAGE(PG8_SB(0, 1), b2 + hstepB, voffB); PG8_STAGE(PG8_SA(0, 0), a2, voffA);
;             PG8_WAIT_V(8); PG8_WAIT_L(0); PG8_BAR; PG8_MMA(1, 0, At, B0); PG8_MMA(1, 1, At, B1); PG8_BAR; PG8_SCHED;
;             PG8_LDB(B0, 1, 0); PG8_LDB(B1, 1, 1); PG8_SCHED; PG8_LDA(At, 1, 0); PG8_STAGE(PG8_SA(0, 1), a2 + hstepA, voffA);
;             PG8_WAIT_V(8); PG8_WAIT_L(0); PG8_BAR; PG8_MMA(0, 0, At, B0); PG8_MMA(0, 1, At, B1); PG8_BAR; PG8_SCHED;
;             PG8_LDA(At, 1, 1); PG8_STAGE(PG8_SB(1, 0), b3, voffB); PG8_STAGE(PG8_SB(1, 1), b3 + hstepB, voffB); PG8_STAGE(PG8_SA(1, 0), a3, voffA);
;             PG8_WAIT_V(8); PG8_WAIT_L(0); PG8_BAR; PG8_MMA(1, 0, At, B0); PG8_MMA(1, 1, At, B1); PG8_BAR; PG8_SCHED;
	s_add_i32 s51, s51, s7
	v_lshl_add_u64 v[166:167], v[166:167], 0, s[48:49]
	s_mov_b32 m0, s51
	ds_read_b128 v[200:203], v183 offset:49152
	ds_read_b128 v[204:207], v183 offset:50176
	ds_read_b128 v[212:215], v183 offset:51200
	ds_read_b128 v[216:219], v183 offset:52224
	ds_read_b128 v[220:223], v183 offset:53248
	ds_read_b128 v[224:227], v183 offset:54272
	ds_read_b128 v[228:231], v183 offset:55296
	ds_read_b128 v[232:235], v183 offset:56320
	global_load_lds_dwordx4 v[166:167], off
	s_add_i32 m0, s51, 0x2000
	s_add_u32 s68, s90, 0x80080
	v_lshl_add_u64 v[166:167], v[208:209], 0, s[48:49]
	s_addc_u32 s69, s91, 0
	s_add_i32 s51, s63, s7
	global_load_lds_dwordx4 v[166:167], off
	v_lshl_add_u64 v[166:167], s[68:69], 0, v[148:149]
	s_mov_b32 m0, s51
	s_nop 0
	global_load_lds_dwordx4 v[166:167], off
	v_lshl_add_u64 v[166:167], s[68:69], 0, v[152:153]
	s_add_i32 m0, s51, 0x2000
	s_nop 0
	global_load_lds_dwordx4 v[166:167], off
	v_lshl_add_u64 v[166:167], v[236:237], 0, s[48:49]
	s_mov_b32 m0, s23
	s_nop 0
	global_load_lds_dwordx4 v[166:167], off
	v_lshl_add_u64 v[166:167], v[238:239], 0, s[48:49]
	s_mov_b32 m0, s24
	s_nop 0
	global_load_lds_dwordx4 v[166:167], off
	s_waitcnt vmcnt(8)
	s_waitcnt lgkmcnt(0)
	s_barrier
	s_setprio 1
	v_mfma_i32_16x16x64_i8 v[62:65], v[122:125], v[200:203], v[62:65]
	v_mfma_i32_16x16x64_i8 v[62:65], v[126:129], v[204:207], v[62:65]
	v_mfma_i32_16x16x64_i8 v[58:61], v[142:145], v[204:207], v[58:61]
	v_mfma_i32_16x16x64_i8 v[58:61], v[134:137], v[200:203], v[58:61]
	v_mfma_i32_16x16x64_i8 v[42:45], v[134:137], v[212:215], v[42:45]
	v_mfma_i32_16x16x64_i8 v[42:45], v[142:145], v[216:219], v[42:45]
	v_mfma_i32_16x16x64_i8 v[46:49], v[126:129], v[216:219], v[46:49]
	v_mfma_i32_16x16x64_i8 v[46:49], v[122:125], v[212:215], v[46:49]
	v_mfma_i32_16x16x64_i8 v[30:33], v[122:125], v[220:223], v[30:33]
	v_mfma_i32_16x16x64_i8 v[30:33], v[126:129], v[224:227], v[30:33]
	v_mfma_i32_16x16x64_i8 v[26:29], v[142:145], v[224:227], v[26:29]
	v_mfma_i32_16x16x64_i8 v[26:29], v[134:137], v[220:223], v[26:29]
	v_mfma_i32_16x16x64_i8 v[10:13], v[134:137], v[228:231], v[10:13]
	v_mfma_i32_16x16x64_i8 v[10:13], v[142:145], v[232:235], v[10:13]
	v_mfma_i32_16x16x64_i8 v[14:17], v[126:129], v[232:235], v[14:17]
	v_mfma_i32_16x16x64_i8 v[14:17], v[122:125], v[228:231], v[14:17]
	v_mfma_i32_16x16x64_i8 v[54:57], v[184:187], v[200:203], v[54:57]
	v_mfma_i32_16x16x64_i8 v[54:57], v[188:191], v[204:207], v[54:57]
	v_mfma_i32_16x16x64_i8 v[50:53], v[196:199], v[204:207], v[50:53]
	v_mfma_i32_16x16x64_i8 v[50:53], v[192:195], v[200:203], v[50:53]
	v_mfma_i32_16x16x64_i8 v[34:37], v[192:195], v[212:215], v[34:37]
	v_mfma_i32_16x16x64_i8 v[34:37], v[196:199], v[216:219], v[34:37]
	v_mfma_i32_16x16x64_i8 v[38:41], v[188:191], v[216:219], v[38:41]
	v_mfma_i32_16x16x64_i8 v[38:41], v[184:187], v[212:215], v[38:41]
	v_mfma_i32_16x16x64_i8 v[22:25], v[184:187], v[220:223], v[22:25]
	v_mfma_i32_16x16x64_i8 v[22:25], v[188:191], v[224:227], v[22:25]
	v_mfma_i32_16x16x64_i8 v[18:21], v[196:199], v[224:227], v[18:21]
	v_mfma_i32_16x16x64_i8 v[18:21], v[192:195], v[220:223], v[18:21]
	v_mfma_i32_16x16x64_i8 v[2:5], v[192:195], v[228:231], v[2:5]
	v_mfma_i32_16x16x64_i8 v[2:5], v[196:199], v[232:235], v[2:5]
	v_mfma_i32_16x16x64_i8 v[6:9], v[188:191], v[232:235], v[6:9]
	v_mfma_i32_16x16x64_i8 v[6:9], v[184:187], v[228:231], v[6:9]
	s_setprio 0
	s_barrier
	s_add_i32 s50, s50, 2
	s_add_u32 s0, s0, 0x100
	s_addc_u32 s1, s1, 0
	s_add_u32 s46, s46, 0x100
	s_addc_u32 s47, s47, 0
	s_cmp_gt_u32 s50, 29
	s_cbranch_scc0 .LBB0_249
	s_and_b64 vcc, exec, s[54:55]
	s_cbranch_vccz .LBB0_252
	s_barrier

; #define PG8_STAGE(bufoff, gbase, voff) do { _Pragma("unroll") for (int _i = 0; _i < 2; ++_i) \
;         __builtin_amdgcn_global_load_lds((const unsigned*)((const char*)(gbase) + (voff)[_i]), (PG8_LAS unsigned*)(lds + (bufoff) + ldsw + _i * 8192), 16, 0, 0); } while (0)
; #define PG8_LDA(dst, b, h) do { _Pragma("unroll") for (int m = 0; m < 4; ++m) _Pragma("unroll") for (int k = 0; k < 2; ++k) dst[m][k] = *(const PG8_LAS bf16x8*)(lds + PG8_SA(b, h) + aoff + m * 2048 + k * 1024); } while (0)
; #define PG8_LDB(dst, b, h) do { _Pragma("unroll") for (int n = 0; n < 2; ++n) _Pragma("unroll") for (int k = 0; k < 2; ++k) dst[n][k] = *(const PG8_LAS bf16x8*)(lds + PG8_SB(b, h) + boff + n * 2048 + k * 1024); } while (0)
; template <class Epi, class Sched, bool ALIGN_EPI = false, bool SP2 = false>
; __device__ __forceinline__ void gemm_phase(PG8_LAS unsigned char* lds, const Gemm g, const Sched& S, const Epi& E) {
;     ...
;         for (int t = 0; t < nt; t += 2) {
;             const bool last = (t == nt - 2);
;             const char* a1 = cA + (size_t)(t + 1) * kstep;
;             const char* a2 = last ? nA : cA + (size_t)(t + 2) * kstep; const char* b2 = last ? nB : cB + (size_t)(t + 2) * kstep;
;             const char* a3 = a2 + kstep; const char* b3 = b2 + kstep;
;             if (last && has_next) S.a_ready(nxt);
;             if constexpr (SP2) {
;             PG8_LDB(B0, 0, 0); PG8_LDB(B1, 0, 1); PG8_SCHED; PG8_LDA(At, 0, 0); PG8_STAGE(PG8_SA(1, 1), a1 + hstepA, voffA);
;             PG8_WAIT_V(8); PG8_WAIT_L(0); PG8_BAR; PG8_MMA(0, 0, At, B0); PG8_MMA(0, 1, At, B1); PG8_BAR; PG8_SCHED;
;             PG8_LDA(At, 0, 1); PG8_STAGE(PG8_SB(0, 0), b2, voffB); PG8_STAGE(PG8_SB(0, 1), b2 + hstepB, voffB); PG8_STAGE(PG8_SA(0, 0), a2, voffA);
;             PG8_WAIT_V(8); PG8_WAIT_L(0); PG8_BAR; PG8_MMA(1, 0, At, B0); PG8_MMA(1, 1, At, B1); PG8_BAR; PG8_SCHED;
;             PG8_LDB(B0, 1, 0); PG8_LDB(B1, 1, 1); PG8_SCHED; PG8_LDA(At, 1, 0); PG8_STAGE(PG8_SA(0, 1), a2 + hstepA, voffA);
;             PG8_WAIT_V(8); PG8_WAIT_L(0); PG8_BAR; PG8_MMA(0, 0, At, B0); PG8_MMA(0, 1, At, B1); PG8_BAR; PG8_SCHED;
;             PG8_LDA(At, 1, 1); PG8_STAGE(PG8_SB(1, 0), b3, voffB); PG8_STAGE(PG8_SB(1, 1), b3 + hstepB, voffB); PG8_STAGE(PG8_SA(1, 0), a3, voffA);
;             PG8_WAIT_V(8); PG8_WAIT_L(0); PG8_BAR; PG8_MMA(1, 0, At, B0); PG8_MMA(1, 1, At, B1); PG8_BAR; PG8_SCHED;
.LBB0_275:
	ds_read_b128 v[122:125], v169
	ds_read_b128 v[126:129], v169 offset:1024
	ds_read_b128 v[134:137], v169 offset:2048
	ds_read_b128 v[142:145], v169 offset:3072
	ds_read_b128 v[182:185], v170
	ds_read_b128 v[186:189], v170 offset:1024
	ds_read_b128 v[190:193], v170 offset:2048
	ds_read_b128 v[194:197], v170 offset:3072
	s_add_u32 s51, s0, 0xfff80080
	s_addc_u32 s63, s1, -1
	s_cmp_eq_u32 s50, 28
	s_cselect_b32 s67, s55, s63
	s_cselect_b32 s66, s54, s51
	s_cselect_b32 s65, s37, s49
	s_cselect_b32 s64, s46, s47
	v_lshl_add_u64 v[166:167], s[0:1], 0, v[158:159]
	s_add_i32 m0, s18, 0xc000
	ds_read_b128 v[198:201], v171
	ds_read_b128 v[202:205], v171 offset:1024
	ds_read_b128 v[206:209], v171 offset:2048
	ds_read_b128 v[212:215], v171 offset:3072
	ds_read_b128 v[216:219], v171 offset:4096
	ds_read_b128 v[220:223], v171 offset:5120
	ds_read_b128 v[224:227], v171 offset:6144
	ds_read_b128 v[228:231], v171 offset:7168
	global_load_lds_dwordx4 v[166:167], off
	v_lshl_add_u64 v[166:167], s[0:1], 0, v[160:161]
	s_add_i32 m0, s18, 0xe000
	s_nop 0
	global_load_lds_dwordx4 v[166:167], off
	s_waitcnt vmcnt(8)
	s_waitcnt lgkmcnt(0)
	s_barrier
	s_setprio 1
	v_mfma_i32_16x16x64_i8 v[138:141], v[122:125], v[198:201], v[138:141]
	v_mfma_i32_16x16x64_i8 v[138:141], v[126:129], v[202:205], v[138:141]
	v_mfma_i32_16x16x64_i8 v[130:133], v[142:145], v[202:205], v[130:133]
	v_mfma_i32_16x16x64_i8 v[130:133], v[134:137], v[198:201], v[130:133]
	v_mfma_i32_16x16x64_i8 v[106:109], v[134:137], v[206:209], v[106:109]
	v_mfma_i32_16x16x64_i8 v[106:109], v[142:145], v[212:215], v[106:109]
	v_mfma_i32_16x16x64_i8 v[110:113], v[126:129], v[212:215], v[110:113]
	v_mfma_i32_16x16x64_i8 v[110:113], v[122:125], v[206:209], v[110:113]
	v_mfma_i32_16x16x64_i8 v[94:97], v[122:125], v[216:219], v[94:97]
	v_mfma_i32_16x16x64_i8 v[94:97], v[126:129], v[220:223], v[94:97]
	v_mfma_i32_16x16x64_i8 v[90:93], v[142:145], v[220:223], v[90:93]
	v_mfma_i32_16x16x64_i8 v[90:93], v[134:137], v[216:219], v[90:93]
	v_mfma_i32_16x16x64_i8 v[74:77], v[134:137], v[224:227], v[74:77]
	v_mfma_i32_16x16x64_i8 v[74:77], v[142:145], v[228:231], v[74:77]
	v_mfma_i32_16x16x64_i8 v[78:81], v[126:129], v[228:231], v[78:81]
	v_mfma_i32_16x16x64_i8 v[78:81], v[122:125], v[224:227], v[78:81]
	v_mfma_i32_16x16x64_i8 v[118:121], v[182:185], v[198:201], v[118:121]
	v_mfma_i32_16x16x64_i8 v[118:121], v[186:189], v[202:205], v[118:121]
	v_mfma_i32_16x16x64_i8 v[114:117], v[194:197], v[202:205], v[114:117]
	v_mfma_i32_16x16x64_i8 v[114:117], v[190:193], v[198:201], v[114:117]
	v_mfma_i32_16x16x64_i8 v[98:101], v[190:193], v[206:209], v[98:101]
	v_mfma_i32_16x16x64_i8 v[98:101], v[194:197], v[212:215], v[98:101]
	v_mfma_i32_16x16x64_i8 v[102:105], v[186:189], v[212:215], v[102:105]
	v_mfma_i32_16x16x64_i8 v[102:105], v[182:185], v[206:209], v[102:105]
	v_mfma_i32_16x16x64_i8 v[86:89], v[182:185], v[216:219], v[86:89]
	v_mfma_i32_16x16x64_i8 v[86:89], v[186:189], v[220:223], v[86:89]
	v_mfma_i32_16x16x64_i8 v[82:85], v[194:197], v[220:223], v[82:85]
	v_mfma_i32_16x16x64_i8 v[82:85], v[190:193], v[216:219], v[82:85]
	v_mfma_i32_16x16x64_i8 v[66:69], v[190:193], v[224:227], v[66:69]
	v_mfma_i32_16x16x64_i8 v[66:69], v[194:197], v[228:231], v[66:69]
	v_mfma_i32_16x16x64_i8 v[70:73], v[186:189], v[228:231], v[70:73]
	v_mfma_i32_16x16x64_i8 v[70:73], v[182:185], v[224:227], v[70:73]
	s_setprio 0
	s_barrier
	s_add_i32 s51, s28, s12
	v_lshl_add_u64 v[166:167], s[64:65], 0, v[148:149]
	s_mov_b32 m0, s51
	ds_read_b128 v[198:201], v171 offset:16384
	ds_read_b128 v[202:205], v171 offset:17408
	ds_read_b128 v[206:209], v171 offset:18432
	ds_read_b128 v[212:215], v171 offset:19456
	ds_read_b128 v[216:219], v171 offset:20480
	ds_read_b128 v[220:223], v171 offset:21504
	ds_read_b128 v[224:227], v171 offset:22528
	ds_read_b128 v[228:231], v171 offset:23552
	global_load_lds_dwordx4 v[166:167], off
	s_add_i32 m0, s51, 0x2000
	s_add_u32 s68, s64, 0x80000
	v_lshl_add_u64 v[176:177], s[64:65], 0, v[152:153]
	s_addc_u32 s69, s65, 0
	s_add_i32 s51, s29, s12
	global_load_lds_dwordx4 v[176:177], off
	v_lshl_add_u64 v[232:233], s[68:69], 0, v[148:149]
	s_mov_b32 m0, s51
	v_lshl_add_u64 v[234:235], s[66:67], 0, v[150:151]
	global_load_lds_dwordx4 v[232:233], off
	v_lshl_add_u64 v[232:233], s[68:69], 0, v[152:153]
	s_add_i32 m0, s51, 0x2000
	s_nop 0
	global_load_lds_dwordx4 v[232:233], off
	v_lshl_add_u64 v[232:233], s[66:67], 0, v[146:147]
	s_mov_b32 m0, s18
	s_nop 0
	global_load_lds_dwordx4 v[232:233], off
	s_mov_b32 m0, s19
	s_nop 0
	global_load_lds_dwordx4 v[234:235], off
	s_waitcnt vmcnt(8)
	s_waitcnt lgkmcnt(0)
	s_barrier
; #define PG8_STAGE(bufoff, gbase, voff) do { _Pragma("unroll") for (int _i = 0; _i < 2; ++_i) \
;         __builtin_amdgcn_global_load_lds((const unsigned*)((const char*)(gbase) + (voff)[_i]), (PG8_LAS unsigned*)(lds + (bufoff) + ldsw + _i * 8192), 16, 0, 0); } while (0)
; #define PG8_LDA(dst, b, h) do { _Pragma("unroll") for (int m = 0; m < 4; ++m) _Pragma("unroll") for (int k = 0; k < 2; ++k) dst[m][k] = *(const PG8_LAS bf16x8*)(lds + PG8_SA(b, h) + aoff + m * 2048 + k * 1024); } while (0)
; #define PG8_LDB(dst, b, h) do { _Pragma("unroll") for (int n = 0; n < 2; ++n) _Pragma("unroll") for (int k = 0; k < 2; ++k) dst[n][k] = *(const PG8_LAS bf16x8*)(lds + PG8_SB(b, h) + boff + n * 2048 + k * 1024); } while (0)
; template <class Epi, class Sched, bool ALIGN_EPI = false, bool SP2 = false>
; __device__ __forceinline__ void gemm_phase(PG8_LAS unsigned char* lds, const Gemm g, const Sched& S, const Epi& E) {
;     ...
;         for (int t = 0; t < nt; t += 2) {
;             const bool last = (t == nt - 2);
;             const char* a1 = cA + (size_t)(t + 1) * kstep;
;             const char* a2 = last ? nA : cA + (size_t)(t + 2) * kstep; const char* b2 = last ? nB : cB + (size_t)(t + 2) * kstep;
;             const char* a3 = a2 + kstep; const char* b3 = b2 + kstep;
;             if (last && has_next) S.a_ready(nxt);
;             if constexpr (SP2) {
;             PG8_LDB(B0, 0, 0); PG8_LDB(B1, 0, 1); PG8_SCHED; PG8_LDA(At, 0, 0); PG8_STAGE(PG8_SA(1, 1), a1 + hstepA, voffA);
;             PG8_WAIT_V(8); PG8_WAIT_L(0); PG8_BAR; PG8_MMA(0, 0, At, B0); PG8_MMA(0, 1, At, B1); PG8_BAR; PG8_SCHED;
;             PG8_LDA(At, 0, 1); PG8_STAGE(PG8_SB(0, 0), b2, voffB); PG8_STAGE(PG8_SB(0, 1), b2 + hstepB, voffB); PG8_STAGE(PG8_SA(0, 0), a2, voffA);
;             PG8_WAIT_V(8); PG8_WAIT_L(0); PG8_BAR; PG8_MMA(1, 0, At, B0); PG8_MMA(1, 1, At, B1); PG8_BAR; PG8_SCHED;
;             PG8_LDB(B0, 1, 0); PG8_LDB(B1, 1, 1); PG8_SCHED; PG8_LDA(At, 1, 0); PG8_STAGE(PG8_SA(0, 1), a2 + hstepA, voffA);
;             PG8_WAIT_V(8); PG8_WAIT_L(0); PG8_BAR; PG8_MMA(0, 0, At, B0); PG8_MMA(0, 1, At, B1); PG8_BAR; PG8_SCHED;
;             PG8_LDA(At, 1, 1); PG8_STAGE(PG8_SB(1, 0), b3, voffB); PG8_STAGE(PG8_SB(1, 1), b3 + hstepB, voffB); PG8_STAGE(PG8_SA(1, 0), a3, voffA);
;             PG8_WAIT_V(8); PG8_WAIT_L(0); PG8_BAR; PG8_MMA(1, 0, At, B0); PG8_MMA(1, 1, At, B1); PG8_BAR; PG8_SCHED;
	s_setprio 1
	v_mfma_i32_16x16x64_i8 v[62:65], v[122:125], v[198:201], v[62:65]
	v_mfma_i32_16x16x64_i8 v[62:65], v[126:129], v[202:205], v[62:65]
	v_mfma_i32_16x16x64_i8 v[58:61], v[142:145], v[202:205], v[58:61]
	v_mfma_i32_16x16x64_i8 v[58:61], v[134:137], v[198:201], v[58:61]
	v_mfma_i32_16x16x64_i8 v[42:45], v[134:137], v[206:209], v[42:45]
	v_mfma_i32_16x16x64_i8 v[42:45], v[142:145], v[212:215], v[42:45]
	v_mfma_i32_16x16x64_i8 v[46:49], v[126:129], v[212:215], v[46:49]
	v_mfma_i32_16x16x64_i8 v[46:49], v[122:125], v[206:209], v[46:49]
	v_mfma_i32_16x16x64_i8 v[30:33], v[122:125], v[216:219], v[30:33]
	v_mfma_i32_16x16x64_i8 v[30:33], v[126:129], v[220:223], v[30:33]
	v_mfma_i32_16x16x64_i8 v[26:29], v[142:145], v[220:223], v[26:29]
	v_mfma_i32_16x16x64_i8 v[26:29], v[134:137], v[216:219], v[26:29]
	v_mfma_i32_16x16x64_i8 v[10:13], v[134:137], v[224:227], v[10:13]
	v_mfma_i32_16x16x64_i8 v[10:13], v[142:145], v[228:231], v[10:13]
	v_mfma_i32_16x16x64_i8 v[14:17], v[126:129], v[228:231], v[14:17]
	v_mfma_i32_16x16x64_i8 v[14:17], v[122:125], v[224:227], v[14:17]
	v_mfma_i32_16x16x64_i8 v[54:57], v[182:185], v[198:201], v[54:57]
	v_mfma_i32_16x16x64_i8 v[54:57], v[186:189], v[202:205], v[54:57]
	v_mfma_i32_16x16x64_i8 v[50:53], v[194:197], v[202:205], v[50:53]
	v_mfma_i32_16x16x64_i8 v[50:53], v[190:193], v[198:201], v[50:53]
	v_mfma_i32_16x16x64_i8 v[34:37], v[190:193], v[206:209], v[34:37]
	v_mfma_i32_16x16x64_i8 v[34:37], v[194:197], v[212:215], v[34:37]
	v_mfma_i32_16x16x64_i8 v[38:41], v[186:189], v[212:215], v[38:41]
	v_mfma_i32_16x16x64_i8 v[38:41], v[182:185], v[206:209], v[38:41]
	v_mfma_i32_16x16x64_i8 v[22:25], v[182:185], v[216:219], v[22:25]
	v_mfma_i32_16x16x64_i8 v[22:25], v[186:189], v[220:223], v[22:25]
	v_mfma_i32_16x16x64_i8 v[18:21], v[194:197], v[220:223], v[18:21]
	v_mfma_i32_16x16x64_i8 v[18:21], v[190:193], v[216:219], v[18:21]
	v_mfma_i32_16x16x64_i8 v[2:5], v[190:193], v[224:227], v[2:5]
	v_mfma_i32_16x16x64_i8 v[2:5], v[194:197], v[228:231], v[2:5]
	v_mfma_i32_16x16x64_i8 v[6:9], v[186:189], v[228:231], v[6:9]
	v_mfma_i32_16x16x64_i8 v[6:9], v[182:185], v[224:227], v[6:9]
	s_setprio 0
	s_barrier
	s_add_i32 s51, 0, 0x18000
	s_add_i32 s63, 0, 0x1c000
	v_add_u32_e32 v142, s51, v173
	v_add_u32_e32 v172, s63, v173
	ds_read_b128 v[122:125], v142
	ds_read_b128 v[126:129], v142 offset:1024
	ds_read_b128 v[134:137], v142 offset:2048
	ds_read_b128 v[142:145], v142 offset:3072
	ds_read_b128 v[182:185], v172
	ds_read_b128 v[186:189], v172 offset:1024
	ds_read_b128 v[190:193], v172 offset:2048
	ds_read_b128 v[194:197], v172 offset:3072
	s_add_u32 s66, s66, 0x80000
	s_addc_u32 s67, s67, 0
	s_mov_b32 m0, s20
	v_lshl_add_u64 v[236:237], s[66:67], 0, v[146:147]
	ds_read_b128 v[198:201], v171 offset:32768
	ds_read_b128 v[202:205], v171 offset:33792
	ds_read_b128 v[206:209], v171 offset:34816
	ds_read_b128 v[212:215], v171 offset:35840
	ds_read_b128 v[216:219], v171 offset:36864
	ds_read_b128 v[220:223], v171 offset:37888
	ds_read_b128 v[224:227], v171 offset:38912
	ds_read_b128 v[228:231], v171 offset:39936
	global_load_lds_dwordx4 v[236:237], off
	v_lshl_add_u64 v[236:237], s[66:67], 0, v[150:151]
	s_mov_b32 m0, s21
	s_nop 0
	global_load_lds_dwordx4 v[236:237], off
	s_waitcnt vmcnt(8)
	s_waitcnt lgkmcnt(0)
	s_barrier
	s_setprio 1
	v_mfma_i32_16x16x64_i8 v[138:141], v[122:125], v[198:201], v[138:141]
	v_mfma_i32_16x16x64_i8 v[138:141], v[126:129], v[202:205], v[138:141]
	v_mfma_i32_16x16x64_i8 v[130:133], v[142:145], v[202:205], v[130:133]
	v_mfma_i32_16x16x64_i8 v[130:133], v[134:137], v[198:201], v[130:133]
	v_mfma_i32_16x16x64_i8 v[106:109], v[134:137], v[206:209], v[106:109]
	v_mfma_i32_16x16x64_i8 v[106:109], v[142:145], v[212:215], v[106:109]
	v_mfma_i32_16x16x64_i8 v[110:113], v[126:129], v[212:215], v[110:113]
	v_mfma_i32_16x16x64_i8 v[110:113], v[122:125], v[206:209], v[110:113]
	v_mfma_i32_16x16x64_i8 v[94:97], v[122:125], v[216:219], v[94:97]
	v_mfma_i32_16x16x64_i8 v[94:97], v[126:129], v[220:223], v[94:97]
	v_mfma_i32_16x16x64_i8 v[90:93], v[142:145], v[220:223], v[90:93]
	v_mfma_i32_16x16x64_i8 v[90:93], v[134:137], v[216:219], v[90:93]
	v_mfma_i32_16x16x64_i8 v[74:77], v[134:137], v[224:227], v[74:77]
	v_mfma_i32_16x16x64_i8 v[74:77], v[142:145], v[228:231], v[74:77]
	v_mfma_i32_16x16x64_i8 v[78:81], v[126:129], v[228:231], v[78:81]
	v_mfma_i32_16x16x64_i8 v[78:81], v[122:125], v[224:227], v[78:81]
	v_mfma_i32_16x16x64_i8 v[118:121], v[182:185], v[198:201], v[118:121]
	v_mfma_i32_16x16x64_i8 v[118:121], v[186:189], v[202:205], v[118:121]
	v_mfma_i32_16x16x64_i8 v[114:117], v[194:197], v[202:205], v[114:117]
	v_mfma_i32_16x16x64_i8 v[114:117], v[190:193], v[198:201], v[114:117]
	v_mfma_i32_16x16x64_i8 v[98:101], v[190:193], v[206:209], v[98:101]
	v_mfma_i32_16x16x64_i8 v[98:101], v[194:197], v[212:215], v[98:101]
	v_mfma_i32_16x16x64_i8 v[102:105], v[186:189], v[212:215], v[102:105]
	v_mfma_i32_16x16x64_i8 v[102:105], v[182:185], v[206:209], v[102:105]
	v_mfma_i32_16x16x64_i8 v[86:89], v[182:185], v[216:219], v[86:89]
	v_mfma_i32_16x16x64_i8 v[86:89], v[186:189], v[220:223], v[86:89]
	v_mfma_i32_16x16x64_i8 v[82:85], v[194:197], v[220:223], v[82:85]
	v_mfma_i32_16x16x64_i8 v[82:85], v[190:193], v[216:219], v[82:85]
	v_mfma_i32_16x16x64_i8 v[66:69], v[190:193], v[224:227], v[66:69]
	v_mfma_i32_16x16x64_i8 v[66:69], v[194:197], v[228:231], v[66:69]
	v_mfma_i32_16x16x64_i8 v[70:73], v[186:189], v[228:231], v[70:73]
	v_mfma_i32_16x16x64_i8 v[70:73], v[182:185], v[224:227], v[70:73]
	s_setprio 0
	s_barrier
; #define PG8_STAGE(bufoff, gbase, voff) do { _Pragma("unroll") for (int _i = 0; _i < 2; ++_i) \
;         __builtin_amdgcn_global_load_lds((const unsigned*)((const char*)(gbase) + (voff)[_i]), (PG8_LAS unsigned*)(lds + (bufoff) + ldsw + _i * 8192), 16, 0, 0); } while (0)
; #define PG8_LDA(dst, b, h) do { _Pragma("unroll") for (int m = 0; m < 4; ++m) _Pragma("unroll") for (int k = 0; k < 2; ++k) dst[m][k] = *(const PG8_LAS bf16x8*)(lds + PG8_SA(b, h) + aoff + m * 2048 + k * 1024); } while (0)
; #define PG8_LDB(dst, b, h) do { _Pragma("unroll") for (int n = 0; n < 2; ++n) _Pragma("unroll") for (int k = 0; k < 2; ++k) dst[n][k] = *(const PG8_LAS bf16x8*)(lds + PG8_SB(b, h) + boff + n * 2048 + k * 1024); } while (0)
; template <class Epi, class Sched, bool ALIGN_EPI = false, bool SP2 = false>
; __device__ __forceinline__ void gemm_phase(PG8_LAS unsigned char* lds, const Gemm g, const Sched& S, const Epi& E) {
;     ...
;         for (int t = 0; t < nt; t += 2) {
;             const bool last = (t == nt - 2);
;             const char* a1 = cA + (size_t)(t + 1) * kstep;
;             const char* a2 = last ? nA : cA + (size_t)(t + 2) * kstep; const char* b2 = last ? nB : cB + (size_t)(t + 2) * kstep;
;             const char* a3 = a2 + kstep; const char* b3 = b2 + kstep;
;             if (last && has_next) S.a_ready(nxt);
;             if constexpr (SP2) {
;             PG8_LDB(B0, 0, 0); PG8_LDB(B1, 0, 1); PG8_SCHED; PG8_LDA(At, 0, 0); PG8_STAGE(PG8_SA(1, 1), a1 + hstepA, voffA);
;             PG8_WAIT_V(8); PG8_WAIT_L(0); PG8_BAR; PG8_MMA(0, 0, At, B0); PG8_MMA(0, 1, At, B1); PG8_BAR; PG8_SCHED;
;             PG8_LDA(At, 0, 1); PG8_STAGE(PG8_SB(0, 0), b2, voffB); PG8_STAGE(PG8_SB(0, 1), b2 + hstepB, voffB); PG8_STAGE(PG8_SA(0, 0), a2, voffA);
;             PG8_WAIT_V(8); PG8_WAIT_L(0); PG8_BAR; PG8_MMA(1, 0, At, B0); PG8_MMA(1, 1, At, B1); PG8_BAR; PG8_SCHED;
;             PG8_LDB(B0, 1, 0); PG8_LDB(B1, 1, 1); PG8_SCHED; PG8_LDA(At, 1, 0); PG8_STAGE(PG8_SA(0, 1), a2 + hstepA, voffA);
;             PG8_WAIT_V(8); PG8_WAIT_L(0); PG8_BAR; PG8_MMA(0, 0, At, B0); PG8_MMA(0, 1, At, B1); PG8_BAR; PG8_SCHED;
;             PG8_LDA(At, 1, 1); PG8_STAGE(PG8_SB(1, 0), b3, voffB); PG8_STAGE(PG8_SB(1, 1), b3 + hstepB, voffB); PG8_STAGE(PG8_SA(1, 0), a3, voffA);
;             PG8_WAIT_V(8); PG8_WAIT_L(0); PG8_BAR; PG8_MMA(1, 0, At, B0); PG8_MMA(1, 1, At, B1); PG8_BAR; PG8_SCHED;
	s_add_i32 s51, s51, s12
	v_lshl_add_u64 v[166:167], v[166:167], 0, s[42:43]
	s_mov_b32 m0, s51
	ds_read_b128 v[198:201], v171 offset:49152
	ds_read_b128 v[202:205], v171 offset:50176
	ds_read_b128 v[206:209], v171 offset:51200
	ds_read_b128 v[212:215], v171 offset:52224
	ds_read_b128 v[216:219], v171 offset:53248
	ds_read_b128 v[220:223], v171 offset:54272
	ds_read_b128 v[224:227], v171 offset:55296
	ds_read_b128 v[228:231], v171 offset:56320
	global_load_lds_dwordx4 v[166:167], off
	s_add_i32 m0, s51, 0x2000
	s_add_u32 s64, s64, 0x80080
	v_lshl_add_u64 v[166:167], v[176:177], 0, s[42:43]
	s_addc_u32 s65, s65, 0
	s_add_i32 s51, s63, s12
	global_load_lds_dwordx4 v[166:167], off
	v_lshl_add_u64 v[166:167], s[64:65], 0, v[148:149]
	s_mov_b32 m0, s51
	s_nop 0
	global_load_lds_dwordx4 v[166:167], off
	v_lshl_add_u64 v[166:167], s[64:65], 0, v[152:153]
	s_add_i32 m0, s51, 0x2000
	s_nop 0
	global_load_lds_dwordx4 v[166:167], off
	v_lshl_add_u64 v[166:167], v[232:233], 0, s[42:43]
	s_mov_b32 m0, s24
	s_nop 0
	global_load_lds_dwordx4 v[166:167], off
	v_lshl_add_u64 v[166:167], v[234:235], 0, s[42:43]
	s_mov_b32 m0, s25
	s_nop 0
	global_load_lds_dwordx4 v[166:167], off
	s_waitcnt vmcnt(8)
	s_waitcnt lgkmcnt(0)
	s_barrier
	s_setprio 1
	v_mfma_i32_16x16x64_i8 v[62:65], v[122:125], v[198:201], v[62:65]
	v_mfma_i32_16x16x64_i8 v[62:65], v[126:129], v[202:205], v[62:65]
	v_mfma_i32_16x16x64_i8 v[58:61], v[142:145], v[202:205], v[58:61]
	v_mfma_i32_16x16x64_i8 v[58:61], v[134:137], v[198:201], v[58:61]
	v_mfma_i32_16x16x64_i8 v[42:45], v[134:137], v[206:209], v[42:45]
	v_mfma_i32_16x16x64_i8 v[42:45], v[142:145], v[212:215], v[42:45]
	v_mfma_i32_16x16x64_i8 v[46:49], v[126:129], v[212:215], v[46:49]
	v_mfma_i32_16x16x64_i8 v[46:49], v[122:125], v[206:209], v[46:49]
	v_mfma_i32_16x16x64_i8 v[30:33], v[122:125], v[216:219], v[30:33]
	v_mfma_i32_16x16x64_i8 v[30:33], v[126:129], v[220:223], v[30:33]
	v_mfma_i32_16x16x64_i8 v[26:29], v[142:145], v[220:223], v[26:29]
	v_mfma_i32_16x16x64_i8 v[26:29], v[134:137], v[216:219], v[26:29]
	v_mfma_i32_16x16x64_i8 v[10:13], v[134:137], v[224:227], v[10:13]
	v_mfma_i32_16x16x64_i8 v[10:13], v[142:145], v[228:231], v[10:13]
	v_mfma_i32_16x16x64_i8 v[14:17], v[126:129], v[228:231], v[14:17]
	v_mfma_i32_16x16x64_i8 v[14:17], v[122:125], v[224:227], v[14:17]
	v_mfma_i32_16x16x64_i8 v[54:57], v[182:185], v[198:201], v[54:57]
	v_mfma_i32_16x16x64_i8 v[54:57], v[186:189], v[202:205], v[54:57]
	v_mfma_i32_16x16x64_i8 v[50:53], v[194:197], v[202:205], v[50:53]
	v_mfma_i32_16x16x64_i8 v[50:53], v[190:193], v[198:201], v[50:53]
	v_mfma_i32_16x16x64_i8 v[34:37], v[190:193], v[206:209], v[34:37]
	v_mfma_i32_16x16x64_i8 v[34:37], v[194:197], v[212:215], v[34:37]
	v_mfma_i32_16x16x64_i8 v[38:41], v[186:189], v[212:215], v[38:41]
	v_mfma_i32_16x16x64_i8 v[38:41], v[182:185], v[206:209], v[38:41]
	v_mfma_i32_16x16x64_i8 v[22:25], v[182:185], v[216:219], v[22:25]
	v_mfma_i32_16x16x64_i8 v[22:25], v[186:189], v[220:223], v[22:25]
	v_mfma_i32_16x16x64_i8 v[18:21], v[194:197], v[220:223], v[18:21]
	v_mfma_i32_16x16x64_i8 v[18:21], v[190:193], v[216:219], v[18:21]
	v_mfma_i32_16x16x64_i8 v[2:5], v[190:193], v[224:227], v[2:5]
	v_mfma_i32_16x16x64_i8 v[2:5], v[194:197], v[228:231], v[2:5]
	v_mfma_i32_16x16x64_i8 v[6:9], v[186:189], v[228:231], v[6:9]
	v_mfma_i32_16x16x64_i8 v[6:9], v[182:185], v[224:227], v[6:9]
	s_setprio 0
	s_barrier
	s_add_i32 s50, s50, 2
	s_add_u32 s0, s0, 0x100
	s_addc_u32 s1, s1, 0
	s_add_u32 s47, s47, 0x100
	s_addc_u32 s49, s49, 0
	s_cmp_gt_u32 s50, 29
	s_cbranch_scc0 .LBB0_275
	s_and_b64 vcc, exec, s[44:45]
	s_cbranch_vccz .LBB0_278
	s_barrier

; #define PG8_STAGE(bufoff, gbase, voff) do { _Pragma("unroll") for (int _i = 0; _i < 2; ++_i) \
;         __builtin_amdgcn_global_load_lds((const unsigned*)((const char*)(gbase) + (voff)[_i]), (PG8_LAS unsigned*)(lds + (bufoff) + ldsw + _i * 8192), 16, 0, 0); } while (0)
; #define PG8_LDA(dst, b, h) do { _Pragma("unroll") for (int m = 0; m < 4; ++m) _Pragma("unroll") for (int k = 0; k < 2; ++k) dst[m][k] = *(const PG8_LAS bf16x8*)(lds + PG8_SA(b, h) + aoff + m * 2048 + k * 1024); } while (0)
; #define PG8_LDB(dst, b, h) do { _Pragma("unroll") for (int n = 0; n < 2; ++n) _Pragma("unroll") for (int k = 0; k < 2; ++k) dst[n][k] = *(const PG8_LAS bf16x8*)(lds + PG8_SB(b, h) + boff + n * 2048 + k * 1024); } while (0)
; template <class Epi, class Sched, bool ALIGN_EPI = false, bool SP2 = false>
; __device__ __forceinline__ void gemm_phase(PG8_LAS unsigned char* lds, const Gemm g, const Sched& S, const Epi& E) {
;     ...
;         for (int t = 0; t < nt; t += 2) {
;             const bool last = (t == nt - 2);
;             const char* a1 = cA + (size_t)(t + 1) * kstep;
;             const char* a2 = last ? nA : cA + (size_t)(t + 2) * kstep; const char* b2 = last ? nB : cB + (size_t)(t + 2) * kstep;
;             const char* a3 = a2 + kstep; const char* b3 = b2 + kstep;
;             if (last && has_next) S.a_ready(nxt);
;             if constexpr (SP2) {
;             PG8_LDB(B0, 0, 0); PG8_LDB(B1, 0, 1); PG8_SCHED; PG8_LDA(At, 0, 0); PG8_STAGE(PG8_SA(1, 1), a1 + hstepA, voffA);
;             PG8_WAIT_V(8); PG8_WAIT_L(0); PG8_BAR; PG8_MMA(0, 0, At, B0); PG8_MMA(0, 1, At, B1); PG8_BAR; PG8_SCHED;
;             PG8_LDA(At, 0, 1); PG8_STAGE(PG8_SB(0, 0), b2, voffB); PG8_STAGE(PG8_SB(0, 1), b2 + hstepB, voffB); PG8_STAGE(PG8_SA(0, 0), a2, voffA);
;             PG8_WAIT_V(8); PG8_WAIT_L(0); PG8_BAR; PG8_MMA(1, 0, At, B0); PG8_MMA(1, 1, At, B1); PG8_BAR; PG8_SCHED;
;             PG8_LDB(B0, 1, 0); PG8_LDB(B1, 1, 1); PG8_SCHED; PG8_LDA(At, 1, 0); PG8_STAGE(PG8_SA(0, 1), a2 + hstepA, voffA);
;             PG8_WAIT_V(8); PG8_WAIT_L(0); PG8_BAR; PG8_MMA(0, 0, At, B0); PG8_MMA(0, 1, At, B1); PG8_BAR; PG8_SCHED;
;             PG8_LDA(At, 1, 1); PG8_STAGE(PG8_SB(1, 0), b3, voffB); PG8_STAGE(PG8_SB(1, 1), b3 + hstepB, voffB); PG8_STAGE(PG8_SA(1, 0), a3, voffA);
;             PG8_WAIT_V(8); PG8_WAIT_L(0); PG8_BAR; PG8_MMA(1, 0, At, B0); PG8_MMA(1, 1, At, B1); PG8_BAR; PG8_SCHED;
.LBB0_389:
	ds_read_b128 v[154:157], v150
	ds_read_b128 v[158:161], v150 offset:1024
	ds_read_b128 v[162:165], v150 offset:2048
	ds_read_b128 v[166:169], v150 offset:3072
	ds_read_b128 v[170:173], v151
	ds_read_b128 v[174:177], v151 offset:1024
	ds_read_b128 v[182:185], v151 offset:2048
	ds_read_b128 v[186:189], v151 offset:3072
	s_add_u32 s33, s0, 0xfff00080
	s_addc_u32 s35, s1, -1
	s_cmp_eq_u32 s29, 12
	s_cselect_b32 s59, s49, s35
	s_cselect_b32 s58, s48, s33
	s_cselect_b32 s55, s25, s28
	s_cselect_b32 s54, s26, s27
	v_lshl_add_u64 v[146:147], s[0:1], 0, v[138:139]
	s_add_i32 m0, s12, 0xc000
	ds_read_b128 v[190:193], v152
	ds_read_b128 v[194:197], v152 offset:1024
	ds_read_b128 v[198:201], v152 offset:2048
	ds_read_b128 v[202:205], v152 offset:3072
	ds_read_b128 v[206:209], v152 offset:4096
	ds_read_b128 v[212:215], v152 offset:5120
	ds_read_b128 v[216:219], v152 offset:6144
	ds_read_b128 v[220:223], v152 offset:7168
	global_load_lds_dwordx4 v[146:147], off
	v_lshl_add_u64 v[146:147], s[0:1], 0, v[140:141]
	s_add_i32 m0, s12, 0xe000
	s_nop 0
	global_load_lds_dwordx4 v[146:147], off
	s_waitcnt vmcnt(8)
	s_waitcnt lgkmcnt(0)
	s_barrier
	s_setprio 1
	v_mfma_f32_16x16x32_bf16 v[126:129], v[154:157], v[190:193], v[126:129]
	v_mfma_f32_16x16x32_bf16 v[126:129], v[158:161], v[194:197], v[126:129]
	v_mfma_f32_16x16x32_bf16 v[122:125], v[166:169], v[194:197], v[122:125]
	v_mfma_f32_16x16x32_bf16 v[122:125], v[162:165], v[190:193], v[122:125]
	v_mfma_f32_16x16x32_bf16 v[110:113], v[162:165], v[198:201], v[110:113]
	v_mfma_f32_16x16x32_bf16 v[110:113], v[166:169], v[202:205], v[110:113]
	v_mfma_f32_16x16x32_bf16 v[118:121], v[158:161], v[202:205], v[118:121]
	v_mfma_f32_16x16x32_bf16 v[118:121], v[154:157], v[198:201], v[118:121]
	v_mfma_f32_16x16x32_bf16 v[102:105], v[154:157], v[206:209], v[102:105]
	v_mfma_f32_16x16x32_bf16 v[102:105], v[158:161], v[212:215], v[102:105]
	v_mfma_f32_16x16x32_bf16 v[94:97], v[166:169], v[212:215], v[94:97]
	v_mfma_f32_16x16x32_bf16 v[94:97], v[162:165], v[206:209], v[94:97]
	v_mfma_f32_16x16x32_bf16 v[78:81], v[162:165], v[216:219], v[78:81]
	v_mfma_f32_16x16x32_bf16 v[78:81], v[166:169], v[220:223], v[78:81]
	v_mfma_f32_16x16x32_bf16 v[86:89], v[158:161], v[220:223], v[86:89]
	v_mfma_f32_16x16x32_bf16 v[86:89], v[154:157], v[216:219], v[86:89]
	v_mfma_f32_16x16x32_bf16 v[114:117], v[170:173], v[190:193], v[114:117]
	v_mfma_f32_16x16x32_bf16 v[114:117], v[174:177], v[194:197], v[114:117]
	v_mfma_f32_16x16x32_bf16 v[106:109], v[186:189], v[194:197], v[106:109]
	v_mfma_f32_16x16x32_bf16 v[106:109], v[182:185], v[190:193], v[106:109]
	v_mfma_f32_16x16x32_bf16 v[90:93], v[182:185], v[198:201], v[90:93]
	v_mfma_f32_16x16x32_bf16 v[90:93], v[186:189], v[202:205], v[90:93]
	v_mfma_f32_16x16x32_bf16 v[98:101], v[174:177], v[202:205], v[98:101]
	v_mfma_f32_16x16x32_bf16 v[98:101], v[170:173], v[198:201], v[98:101]
	v_mfma_f32_16x16x32_bf16 v[82:85], v[170:173], v[206:209], v[82:85]
	v_mfma_f32_16x16x32_bf16 v[82:85], v[174:177], v[212:215], v[82:85]
	v_mfma_f32_16x16x32_bf16 v[74:77], v[186:189], v[212:215], v[74:77]
	v_mfma_f32_16x16x32_bf16 v[74:77], v[182:185], v[206:209], v[74:77]
	v_mfma_f32_16x16x32_bf16 v[66:69], v[182:185], v[216:219], v[66:69]
	v_mfma_f32_16x16x32_bf16 v[66:69], v[186:189], v[220:223], v[66:69]
	v_mfma_f32_16x16x32_bf16 v[70:73], v[174:177], v[220:223], v[70:73]
	v_mfma_f32_16x16x32_bf16 v[70:73], v[170:173], v[216:219], v[70:73]
	s_setprio 0
	s_barrier
	s_add_i32 s33, s22, s7
	v_lshl_add_u64 v[146:147], s[54:55], 0, v[132:133]
	s_mov_b32 m0, s33
	ds_read_b128 v[190:193], v152 offset:16384
	ds_read_b128 v[194:197], v152 offset:17408
	ds_read_b128 v[198:201], v152 offset:18432
	ds_read_b128 v[202:205], v152 offset:19456
	ds_read_b128 v[206:209], v152 offset:20480
	ds_read_b128 v[212:215], v152 offset:21504
	ds_read_b128 v[216:219], v152 offset:22528
	ds_read_b128 v[220:223], v152 offset:23552
	global_load_lds_dwordx4 v[146:147], off
	s_add_i32 m0, s33, 0x2000
	s_add_u32 s36, s54, 0x40000
	v_lshl_add_u64 v[224:225], s[54:55], 0, v[136:137]
	s_addc_u32 s37, s55, 0
	s_add_i32 s33, s23, s7
	global_load_lds_dwordx4 v[224:225], off
	v_lshl_add_u64 v[226:227], s[36:37], 0, v[132:133]
	s_mov_b32 m0, s33
	v_lshl_add_u64 v[228:229], s[58:59], 0, v[134:135]
	global_load_lds_dwordx4 v[226:227], off
	v_lshl_add_u64 v[226:227], s[36:37], 0, v[136:137]
	s_add_i32 m0, s33, 0x2000
	s_nop 0
	global_load_lds_dwordx4 v[226:227], off
	v_lshl_add_u64 v[226:227], s[58:59], 0, v[130:131]
	s_mov_b32 m0, s12
	s_nop 0
	global_load_lds_dwordx4 v[226:227], off
	s_mov_b32 m0, s13
	s_nop 0
	global_load_lds_dwordx4 v[228:229], off
	s_waitcnt vmcnt(8)
	s_waitcnt lgkmcnt(0)
	s_barrier
; #define PG8_STAGE(bufoff, gbase, voff) do { _Pragma("unroll") for (int _i = 0; _i < 2; ++_i) \
;         __builtin_amdgcn_global_load_lds((const unsigned*)((const char*)(gbase) + (voff)[_i]), (PG8_LAS unsigned*)(lds + (bufoff) + ldsw + _i * 8192), 16, 0, 0); } while (0)
; #define PG8_LDA(dst, b, h) do { _Pragma("unroll") for (int m = 0; m < 4; ++m) _Pragma("unroll") for (int k = 0; k < 2; ++k) dst[m][k] = *(const PG8_LAS bf16x8*)(lds + PG8_SA(b, h) + aoff + m * 2048 + k * 1024); } while (0)
; #define PG8_LDB(dst, b, h) do { _Pragma("unroll") for (int n = 0; n < 2; ++n) _Pragma("unroll") for (int k = 0; k < 2; ++k) dst[n][k] = *(const PG8_LAS bf16x8*)(lds + PG8_SB(b, h) + boff + n * 2048 + k * 1024); } while (0)
; template <class Epi, class Sched, bool ALIGN_EPI = false, bool SP2 = false>
; __device__ __forceinline__ void gemm_phase(PG8_LAS unsigned char* lds, const Gemm g, const Sched& S, const Epi& E) {
;     ...
;         for (int t = 0; t < nt; t += 2) {
;             const bool last = (t == nt - 2);
;             const char* a1 = cA + (size_t)(t + 1) * kstep;
;             const char* a2 = last ? nA : cA + (size_t)(t + 2) * kstep; const char* b2 = last ? nB : cB + (size_t)(t + 2) * kstep;
;             const char* a3 = a2 + kstep; const char* b3 = b2 + kstep;
;             if (last && has_next) S.a_ready(nxt);
;             if constexpr (SP2) {
;             PG8_LDB(B0, 0, 0); PG8_LDB(B1, 0, 1); PG8_SCHED; PG8_LDA(At, 0, 0); PG8_STAGE(PG8_SA(1, 1), a1 + hstepA, voffA);
;             PG8_WAIT_V(8); PG8_WAIT_L(0); PG8_BAR; PG8_MMA(0, 0, At, B0); PG8_MMA(0, 1, At, B1); PG8_BAR; PG8_SCHED;
;             PG8_LDA(At, 0, 1); PG8_STAGE(PG8_SB(0, 0), b2, voffB); PG8_STAGE(PG8_SB(0, 1), b2 + hstepB, voffB); PG8_STAGE(PG8_SA(0, 0), a2, voffA);
;             PG8_WAIT_V(8); PG8_WAIT_L(0); PG8_BAR; PG8_MMA(1, 0, At, B0); PG8_MMA(1, 1, At, B1); PG8_BAR; PG8_SCHED;
;             PG8_LDB(B0, 1, 0); PG8_LDB(B1, 1, 1); PG8_SCHED; PG8_LDA(At, 1, 0); PG8_STAGE(PG8_SA(0, 1), a2 + hstepA, voffA);
;             PG8_WAIT_V(8); PG8_WAIT_L(0); PG8_BAR; PG8_MMA(0, 0, At, B0); PG8_MMA(0, 1, At, B1); PG8_BAR; PG8_SCHED;
;             PG8_LDA(At, 1, 1); PG8_STAGE(PG8_SB(1, 0), b3, voffB); PG8_STAGE(PG8_SB(1, 1), b3 + hstepB, voffB); PG8_STAGE(PG8_SA(1, 0), a3, voffA);
;             PG8_WAIT_V(8); PG8_WAIT_L(0); PG8_BAR; PG8_MMA(1, 0, At, B0); PG8_MMA(1, 1, At, B1); PG8_BAR; PG8_SCHED;
	s_setprio 1
	v_mfma_f32_16x16x32_bf16 v[62:65], v[154:157], v[190:193], v[62:65]
	v_mfma_f32_16x16x32_bf16 v[62:65], v[158:161], v[194:197], v[62:65]
	v_mfma_f32_16x16x32_bf16 v[58:61], v[166:169], v[194:197], v[58:61]
	v_mfma_f32_16x16x32_bf16 v[58:61], v[162:165], v[190:193], v[58:61]
	v_mfma_f32_16x16x32_bf16 v[46:49], v[162:165], v[198:201], v[46:49]
	v_mfma_f32_16x16x32_bf16 v[46:49], v[166:169], v[202:205], v[46:49]
	v_mfma_f32_16x16x32_bf16 v[54:57], v[158:161], v[202:205], v[54:57]
	v_mfma_f32_16x16x32_bf16 v[54:57], v[154:157], v[198:201], v[54:57]
	v_mfma_f32_16x16x32_bf16 v[38:41], v[154:157], v[206:209], v[38:41]
	v_mfma_f32_16x16x32_bf16 v[38:41], v[158:161], v[212:215], v[38:41]
	v_mfma_f32_16x16x32_bf16 v[30:33], v[166:169], v[212:215], v[30:33]
	v_mfma_f32_16x16x32_bf16 v[30:33], v[162:165], v[206:209], v[30:33]
	v_mfma_f32_16x16x32_bf16 v[14:17], v[162:165], v[216:219], v[14:17]
	v_mfma_f32_16x16x32_bf16 v[14:17], v[166:169], v[220:223], v[14:17]
	v_mfma_f32_16x16x32_bf16 v[22:25], v[158:161], v[220:223], v[22:25]
	v_mfma_f32_16x16x32_bf16 v[22:25], v[154:157], v[216:219], v[22:25]
	v_mfma_f32_16x16x32_bf16 v[50:53], v[170:173], v[190:193], v[50:53]
	v_mfma_f32_16x16x32_bf16 v[50:53], v[174:177], v[194:197], v[50:53]
	v_mfma_f32_16x16x32_bf16 v[42:45], v[186:189], v[194:197], v[42:45]
	v_mfma_f32_16x16x32_bf16 v[42:45], v[182:185], v[190:193], v[42:45]
	v_mfma_f32_16x16x32_bf16 v[26:29], v[182:185], v[198:201], v[26:29]
	v_mfma_f32_16x16x32_bf16 v[26:29], v[186:189], v[202:205], v[26:29]
	v_mfma_f32_16x16x32_bf16 v[34:37], v[174:177], v[202:205], v[34:37]
	v_mfma_f32_16x16x32_bf16 v[34:37], v[170:173], v[198:201], v[34:37]
	v_mfma_f32_16x16x32_bf16 v[18:21], v[170:173], v[206:209], v[18:21]
	v_mfma_f32_16x16x32_bf16 v[18:21], v[174:177], v[212:215], v[18:21]
	v_mfma_f32_16x16x32_bf16 v[10:13], v[186:189], v[212:215], v[10:13]
	v_mfma_f32_16x16x32_bf16 v[10:13], v[182:185], v[206:209], v[10:13]
	v_mfma_f32_16x16x32_bf16 v[2:5], v[182:185], v[216:219], v[2:5]
	v_mfma_f32_16x16x32_bf16 v[2:5], v[186:189], v[220:223], v[2:5]
	v_mfma_f32_16x16x32_bf16 v[6:9], v[174:177], v[220:223], v[6:9]
	v_mfma_f32_16x16x32_bf16 v[6:9], v[170:173], v[216:219], v[6:9]
	s_setprio 0
	s_barrier
	s_add_i32 s33, 0, 0x18000
	v_add_u32_e32 v153, s33, v148
	s_add_i32 s35, 0, 0x1c000
	ds_read_b128 v[154:157], v153
	ds_read_b128 v[158:161], v153 offset:1024
	ds_read_b128 v[162:165], v153 offset:2048
	ds_read_b128 v[166:169], v153 offset:3072
	v_add_u32_e32 v153, s35, v148
	ds_read_b128 v[170:173], v153
	ds_read_b128 v[174:177], v153 offset:1024
	ds_read_b128 v[182:185], v153 offset:2048
	ds_read_b128 v[186:189], v153 offset:3072
	s_add_u32 s36, s58, 0x100000
	s_addc_u32 s37, s59, 0
	s_mov_b32 m0, s16
	v_lshl_add_u64 v[230:231], s[36:37], 0, v[130:131]
	ds_read_b128 v[190:193], v152 offset:32768
	ds_read_b128 v[194:197], v152 offset:33792
	ds_read_b128 v[198:201], v152 offset:34816
	ds_read_b128 v[202:205], v152 offset:35840
	ds_read_b128 v[206:209], v152 offset:36864
	ds_read_b128 v[212:215], v152 offset:37888
	ds_read_b128 v[216:219], v152 offset:38912
	ds_read_b128 v[220:223], v152 offset:39936
	global_load_lds_dwordx4 v[230:231], off
	v_lshl_add_u64 v[230:231], s[36:37], 0, v[134:135]
	s_mov_b32 m0, s17
	s_nop 0
	global_load_lds_dwordx4 v[230:231], off
	s_waitcnt vmcnt(8)
	s_waitcnt lgkmcnt(0)
	s_barrier
	s_setprio 1
	v_mfma_f32_16x16x32_bf16 v[126:129], v[154:157], v[190:193], v[126:129]
	v_mfma_f32_16x16x32_bf16 v[126:129], v[158:161], v[194:197], v[126:129]
	v_mfma_f32_16x16x32_bf16 v[122:125], v[166:169], v[194:197], v[122:125]
	v_mfma_f32_16x16x32_bf16 v[122:125], v[162:165], v[190:193], v[122:125]
	v_mfma_f32_16x16x32_bf16 v[110:113], v[162:165], v[198:201], v[110:113]
	v_mfma_f32_16x16x32_bf16 v[110:113], v[166:169], v[202:205], v[110:113]
	v_mfma_f32_16x16x32_bf16 v[118:121], v[158:161], v[202:205], v[118:121]
	v_mfma_f32_16x16x32_bf16 v[118:121], v[154:157], v[198:201], v[118:121]
	v_mfma_f32_16x16x32_bf16 v[102:105], v[154:157], v[206:209], v[102:105]
	v_mfma_f32_16x16x32_bf16 v[102:105], v[158:161], v[212:215], v[102:105]
	v_mfma_f32_16x16x32_bf16 v[94:97], v[166:169], v[212:215], v[94:97]
	v_mfma_f32_16x16x32_bf16 v[94:97], v[162:165], v[206:209], v[94:97]
	v_mfma_f32_16x16x32_bf16 v[78:81], v[162:165], v[216:219], v[78:81]
	v_mfma_f32_16x16x32_bf16 v[78:81], v[166:169], v[220:223], v[78:81]
	v_mfma_f32_16x16x32_bf16 v[86:89], v[158:161], v[220:223], v[86:89]
	v_mfma_f32_16x16x32_bf16 v[86:89], v[154:157], v[216:219], v[86:89]
	v_mfma_f32_16x16x32_bf16 v[114:117], v[170:173], v[190:193], v[114:117]
	v_mfma_f32_16x16x32_bf16 v[114:117], v[174:177], v[194:197], v[114:117]
	v_mfma_f32_16x16x32_bf16 v[106:109], v[186:189], v[194:197], v[106:109]
	v_mfma_f32_16x16x32_bf16 v[106:109], v[182:185], v[190:193], v[106:109]
	v_mfma_f32_16x16x32_bf16 v[90:93], v[182:185], v[198:201], v[90:93]
	v_mfma_f32_16x16x32_bf16 v[90:93], v[186:189], v[202:205], v[90:93]
	v_mfma_f32_16x16x32_bf16 v[98:101], v[174:177], v[202:205], v[98:101]
	v_mfma_f32_16x16x32_bf16 v[98:101], v[170:173], v[198:201], v[98:101]
	v_mfma_f32_16x16x32_bf16 v[82:85], v[170:173], v[206:209], v[82:85]
	v_mfma_f32_16x16x32_bf16 v[82:85], v[174:177], v[212:215], v[82:85]
	v_mfma_f32_16x16x32_bf16 v[74:77], v[186:189], v[212:215], v[74:77]
	v_mfma_f32_16x16x32_bf16 v[74:77], v[182:185], v[206:209], v[74:77]
	v_mfma_f32_16x16x32_bf16 v[66:69], v[182:185], v[216:219], v[66:69]
	v_mfma_f32_16x16x32_bf16 v[66:69], v[186:189], v[220:223], v[66:69]
	v_mfma_f32_16x16x32_bf16 v[70:73], v[174:177], v[220:223], v[70:73]
	v_mfma_f32_16x16x32_bf16 v[70:73], v[170:173], v[216:219], v[70:73]
	s_setprio 0
	s_barrier
; #define PG8_STAGE(bufoff, gbase, voff) do { _Pragma("unroll") for (int _i = 0; _i < 2; ++_i) \
;         __builtin_amdgcn_global_load_lds((const unsigned*)((const char*)(gbase) + (voff)[_i]), (PG8_LAS unsigned*)(lds + (bufoff) + ldsw + _i * 8192), 16, 0, 0); } while (0)
; #define PG8_LDA(dst, b, h) do { _Pragma("unroll") for (int m = 0; m < 4; ++m) _Pragma("unroll") for (int k = 0; k < 2; ++k) dst[m][k] = *(const PG8_LAS bf16x8*)(lds + PG8_SA(b, h) + aoff + m * 2048 + k * 1024); } while (0)
; #define PG8_LDB(dst, b, h) do { _Pragma("unroll") for (int n = 0; n < 2; ++n) _Pragma("unroll") for (int k = 0; k < 2; ++k) dst[n][k] = *(const PG8_LAS bf16x8*)(lds + PG8_SB(b, h) + boff + n * 2048 + k * 1024); } while (0)
; template <class Epi, class Sched, bool ALIGN_EPI = false, bool SP2 = false>
; __device__ __forceinline__ void gemm_phase(PG8_LAS unsigned char* lds, const Gemm g, const Sched& S, const Epi& E) {
;     ...
;         for (int t = 0; t < nt; t += 2) {
;             const bool last = (t == nt - 2);
;             const char* a1 = cA + (size_t)(t + 1) * kstep;
;             const char* a2 = last ? nA : cA + (size_t)(t + 2) * kstep; const char* b2 = last ? nB : cB + (size_t)(t + 2) * kstep;
;             const char* a3 = a2 + kstep; const char* b3 = b2 + kstep;
;             if (last && has_next) S.a_ready(nxt);
;             if constexpr (SP2) {
;             PG8_LDB(B0, 0, 0); PG8_LDB(B1, 0, 1); PG8_SCHED; PG8_LDA(At, 0, 0); PG8_STAGE(PG8_SA(1, 1), a1 + hstepA, voffA);
;             PG8_WAIT_V(8); PG8_WAIT_L(0); PG8_BAR; PG8_MMA(0, 0, At, B0); PG8_MMA(0, 1, At, B1); PG8_BAR; PG8_SCHED;
;             PG8_LDA(At, 0, 1); PG8_STAGE(PG8_SB(0, 0), b2, voffB); PG8_STAGE(PG8_SB(0, 1), b2 + hstepB, voffB); PG8_STAGE(PG8_SA(0, 0), a2, voffA);
;             PG8_WAIT_V(8); PG8_WAIT_L(0); PG8_BAR; PG8_MMA(1, 0, At, B0); PG8_MMA(1, 1, At, B1); PG8_BAR; PG8_SCHED;
;             PG8_LDB(B0, 1, 0); PG8_LDB(B1, 1, 1); PG8_SCHED; PG8_LDA(At, 1, 0); PG8_STAGE(PG8_SA(0, 1), a2 + hstepA, voffA);
;             PG8_WAIT_V(8); PG8_WAIT_L(0); PG8_BAR; PG8_MMA(0, 0, At, B0); PG8_MMA(0, 1, At, B1); PG8_BAR; PG8_SCHED;
;             PG8_LDA(At, 1, 1); PG8_STAGE(PG8_SB(1, 0), b3, voffB); PG8_STAGE(PG8_SB(1, 1), b3 + hstepB, voffB); PG8_STAGE(PG8_SA(1, 0), a3, voffA);
;             PG8_WAIT_V(8); PG8_WAIT_L(0); PG8_BAR; PG8_MMA(1, 0, At, B0); PG8_MMA(1, 1, At, B1); PG8_BAR; PG8_SCHED;
	s_add_i32 s33, s33, s7
	v_lshl_add_u64 v[146:147], v[146:147], 0, s[38:39]
	s_mov_b32 m0, s33
	ds_read_b128 v[190:193], v152 offset:49152
	ds_read_b128 v[194:197], v152 offset:50176
	ds_read_b128 v[198:201], v152 offset:51200
	ds_read_b128 v[202:205], v152 offset:52224
	ds_read_b128 v[206:209], v152 offset:53248
	ds_read_b128 v[212:215], v152 offset:54272
	ds_read_b128 v[216:219], v152 offset:55296
	ds_read_b128 v[220:223], v152 offset:56320
	global_load_lds_dwordx4 v[146:147], off
	s_add_i32 m0, s33, 0x2000
	s_add_u32 s36, s54, 0x40080
	v_lshl_add_u64 v[146:147], v[224:225], 0, s[38:39]
	s_addc_u32 s37, s55, 0
	s_add_i32 s33, s35, s7
	global_load_lds_dwordx4 v[146:147], off
	v_lshl_add_u64 v[146:147], s[36:37], 0, v[132:133]
	s_mov_b32 m0, s33
	s_nop 0
	global_load_lds_dwordx4 v[146:147], off
	v_lshl_add_u64 v[146:147], s[36:37], 0, v[136:137]
	s_add_i32 m0, s33, 0x2000
	s_nop 0
	global_load_lds_dwordx4 v[146:147], off
	v_lshl_add_u64 v[146:147], v[226:227], 0, s[38:39]
	s_mov_b32 m0, s19
	s_nop 0
	global_load_lds_dwordx4 v[146:147], off
	v_lshl_add_u64 v[146:147], v[228:229], 0, s[38:39]
	s_mov_b32 m0, s20
	s_nop 0
	global_load_lds_dwordx4 v[146:147], off
	s_waitcnt vmcnt(8)
	s_waitcnt lgkmcnt(0)
	s_barrier
	s_setprio 1
	v_mfma_f32_16x16x32_bf16 v[62:65], v[154:157], v[190:193], v[62:65]
	v_mfma_f32_16x16x32_bf16 v[62:65], v[158:161], v[194:197], v[62:65]
	v_mfma_f32_16x16x32_bf16 v[58:61], v[166:169], v[194:197], v[58:61]
	v_mfma_f32_16x16x32_bf16 v[58:61], v[162:165], v[190:193], v[58:61]
	v_mfma_f32_16x16x32_bf16 v[46:49], v[162:165], v[198:201], v[46:49]
	v_mfma_f32_16x16x32_bf16 v[46:49], v[166:169], v[202:205], v[46:49]
	v_mfma_f32_16x16x32_bf16 v[54:57], v[158:161], v[202:205], v[54:57]
	v_mfma_f32_16x16x32_bf16 v[54:57], v[154:157], v[198:201], v[54:57]
	v_mfma_f32_16x16x32_bf16 v[38:41], v[154:157], v[206:209], v[38:41]
	v_mfma_f32_16x16x32_bf16 v[38:41], v[158:161], v[212:215], v[38:41]
	v_mfma_f32_16x16x32_bf16 v[30:33], v[166:169], v[212:215], v[30:33]
	v_mfma_f32_16x16x32_bf16 v[30:33], v[162:165], v[206:209], v[30:33]
	v_mfma_f32_16x16x32_bf16 v[14:17], v[162:165], v[216:219], v[14:17]
	v_mfma_f32_16x16x32_bf16 v[14:17], v[166:169], v[220:223], v[14:17]
	v_mfma_f32_16x16x32_bf16 v[22:25], v[158:161], v[220:223], v[22:25]
	v_mfma_f32_16x16x32_bf16 v[22:25], v[154:157], v[216:219], v[22:25]
	v_mfma_f32_16x16x32_bf16 v[50:53], v[170:173], v[190:193], v[50:53]
	v_mfma_f32_16x16x32_bf16 v[50:53], v[174:177], v[194:197], v[50:53]
	v_mfma_f32_16x16x32_bf16 v[42:45], v[186:189], v[194:197], v[42:45]
	v_mfma_f32_16x16x32_bf16 v[42:45], v[182:185], v[190:193], v[42:45]
	v_mfma_f32_16x16x32_bf16 v[26:29], v[182:185], v[198:201], v[26:29]
	v_mfma_f32_16x16x32_bf16 v[26:29], v[186:189], v[202:205], v[26:29]
	v_mfma_f32_16x16x32_bf16 v[34:37], v[174:177], v[202:205], v[34:37]
	v_mfma_f32_16x16x32_bf16 v[34:37], v[170:173], v[198:201], v[34:37]
	v_mfma_f32_16x16x32_bf16 v[18:21], v[170:173], v[206:209], v[18:21]
	v_mfma_f32_16x16x32_bf16 v[18:21], v[174:177], v[212:215], v[18:21]
	v_mfma_f32_16x16x32_bf16 v[10:13], v[186:189], v[212:215], v[10:13]
	v_mfma_f32_16x16x32_bf16 v[10:13], v[182:185], v[206:209], v[10:13]
	v_mfma_f32_16x16x32_bf16 v[2:5], v[182:185], v[216:219], v[2:5]
	v_mfma_f32_16x16x32_bf16 v[2:5], v[186:189], v[220:223], v[2:5]
	v_mfma_f32_16x16x32_bf16 v[6:9], v[174:177], v[220:223], v[6:9]
	v_mfma_f32_16x16x32_bf16 v[6:9], v[170:173], v[216:219], v[6:9]
	s_setprio 0
	s_barrier
	s_add_i32 s29, s29, 2
	s_add_u32 s0, s0, 0x100
	s_addc_u32 s1, s1, 0
	s_add_u32 s27, s27, 0x100
	s_addc_u32 s28, s28, 0
	s_cmp_gt_u32 s29, 13
	s_cbranch_scc0 .LBB0_389
	s_and_b64 vcc, exec, s[40:41]
	s_cbranch_vccz .LBB0_392
	s_barrier

; #define PG8_STAGE(bufoff, gbase, voff) do { _Pragma("unroll") for (int _i = 0; _i < 2; ++_i) \
;         __builtin_amdgcn_global_load_lds((const unsigned*)((const char*)(gbase) + (voff)[_i]), (PG8_LAS unsigned*)(lds + (bufoff) + ldsw + _i * 8192), 16, 0, 0); } while (0)
; #define PG8_LDA(dst, b, h) do { _Pragma("unroll") for (int m = 0; m < 4; ++m) _Pragma("unroll") for (int k = 0; k < 2; ++k) dst[m][k] = *(const PG8_LAS bf16x8*)(lds + PG8_SA(b, h) + aoff + m * 2048 + k * 1024); } while (0)
; #define PG8_LDB(dst, b, h) do { _Pragma("unroll") for (int n = 0; n < 2; ++n) _Pragma("unroll") for (int k = 0; k < 2; ++k) dst[n][k] = *(const PG8_LAS bf16x8*)(lds + PG8_SB(b, h) + boff + n * 2048 + k * 1024); } while (0)
; template <class Epi, class Sched, bool ALIGN_EPI = false, bool SP2 = false>
; __device__ __forceinline__ void gemm_phase(PG8_LAS unsigned char* lds, const Gemm g, const Sched& S, const Epi& E) {
;     ...
;         for (int t = 0; t < nt; t += 2) {
;             const bool last = (t == nt - 2);
;             const char* a1 = cA + (size_t)(t + 1) * kstep;
;             const char* a2 = last ? nA : cA + (size_t)(t + 2) * kstep; const char* b2 = last ? nB : cB + (size_t)(t + 2) * kstep;
;             const char* a3 = a2 + kstep; const char* b3 = b2 + kstep;
;             if (last && has_next) S.a_ready(nxt);
;             if constexpr (SP2) {
;             PG8_LDB(B0, 0, 0); PG8_LDB(B1, 0, 1); PG8_SCHED; PG8_LDA(At, 0, 0); PG8_STAGE(PG8_SA(1, 1), a1 + hstepA, voffA);
;             PG8_WAIT_V(8); PG8_WAIT_L(0); PG8_BAR; PG8_MMA(0, 0, At, B0); PG8_MMA(0, 1, At, B1); PG8_BAR; PG8_SCHED;
;             PG8_LDA(At, 0, 1); PG8_STAGE(PG8_SB(0, 0), b2, voffB); PG8_STAGE(PG8_SB(0, 1), b2 + hstepB, voffB); PG8_STAGE(PG8_SA(0, 0), a2, voffA);
;             PG8_WAIT_V(8); PG8_WAIT_L(0); PG8_BAR; PG8_MMA(1, 0, At, B0); PG8_MMA(1, 1, At, B1); PG8_BAR; PG8_SCHED;
;             PG8_LDB(B0, 1, 0); PG8_LDB(B1, 1, 1); PG8_SCHED; PG8_LDA(At, 1, 0); PG8_STAGE(PG8_SA(0, 1), a2 + hstepA, voffA);
;             PG8_WAIT_V(8); PG8_WAIT_L(0); PG8_BAR; PG8_MMA(0, 0, At, B0); PG8_MMA(0, 1, At, B1); PG8_BAR; PG8_SCHED;
;             PG8_LDA(At, 1, 1); PG8_STAGE(PG8_SB(1, 0), b3, voffB); PG8_STAGE(PG8_SB(1, 1), b3 + hstepB, voffB); PG8_STAGE(PG8_SA(1, 0), a3, voffA);
;             PG8_WAIT_V(8); PG8_WAIT_L(0); PG8_BAR; PG8_MMA(1, 0, At, B0); PG8_MMA(1, 1, At, B1); PG8_BAR; PG8_SCHED;
.LBB0_555:
	ds_read_b128 v[82:85], v181
	ds_read_b128 v[86:89], v181 offset:1024
	ds_read_b128 v[138:141], v181 offset:2048
	ds_read_b128 v[142:145], v181 offset:3072
	ds_read_b128 v[146:149], v213
	ds_read_b128 v[150:153], v213 offset:1024
	ds_read_b128 v[154:157], v213 offset:2048
	ds_read_b128 v[158:161], v213 offset:3072
	s_add_u32 s47, s62, 0xfff80080
	s_addc_u32 s61, s63, -1
	s_cmp_eq_u32 s46, 28
	s_cselect_b32 s67, s28, s61
	s_cselect_b32 s66, s29, s47
	s_cselect_b32 s65, s33, s37
	s_cselect_b32 s64, s35, s36
	v_lshl_add_u64 v[194:195], s[62:63], 0, v[174:175]
	s_add_i32 m0, s11, 0xc000
	ds_read_b128 v[186:189], v214
	ds_read_b128 v[190:193], v214 offset:1024
	ds_read_b128 v[216:219], v214 offset:2048
	ds_read_b128 v[220:223], v214 offset:3072
	ds_read_b128 v[224:227], v214 offset:4096
	ds_read_b128 v[228:231], v214 offset:5120
	ds_read_b128 v[232:235], v214 offset:6144
	ds_read_b128 v[236:239], v214 offset:7168
	global_load_lds_dwordx4 v[194:195], off
	v_lshl_add_u64 v[194:195], s[62:63], 0, v[176:177]
	s_add_i32 m0, s11, 0xe000
	s_nop 0
	global_load_lds_dwordx4 v[194:195], off
	s_waitcnt vmcnt(8)
	s_waitcnt lgkmcnt(0)
	s_barrier
	s_setprio 1
	v_mfma_i32_16x16x64_i8 v[70:73], v[82:85], v[186:189], v[70:73]
	v_mfma_i32_16x16x64_i8 v[70:73], v[86:89], v[190:193], v[70:73]
	v_mfma_i32_16x16x64_i8 v[66:69], v[142:145], v[190:193], v[66:69]
	v_mfma_i32_16x16x64_i8 v[66:69], v[138:141], v[186:189], v[66:69]
	v_mfma_i32_16x16x64_i8 v[122:125], v[138:141], v[216:219], v[122:125]
	v_mfma_i32_16x16x64_i8 v[122:125], v[142:145], v[220:223], v[122:125]
	v_mfma_i32_16x16x64_i8 v[126:129], v[86:89], v[220:223], v[126:129]
	v_mfma_i32_16x16x64_i8 v[126:129], v[82:85], v[216:219], v[126:129]
	v_mfma_i32_16x16x64_i8 v[110:113], v[82:85], v[224:227], v[110:113]
	v_mfma_i32_16x16x64_i8 v[110:113], v[86:89], v[228:231], v[110:113]
	v_mfma_i32_16x16x64_i8 v[106:109], v[142:145], v[228:231], v[106:109]
	v_mfma_i32_16x16x64_i8 v[106:109], v[138:141], v[224:227], v[106:109]
	v_mfma_i32_16x16x64_i8 v[90:93], v[138:141], v[232:235], v[90:93]
	v_mfma_i32_16x16x64_i8 v[90:93], v[142:145], v[236:239], v[90:93]
	v_mfma_i32_16x16x64_i8 v[94:97], v[86:89], v[236:239], v[94:97]
	v_mfma_i32_16x16x64_i8 v[94:97], v[82:85], v[232:235], v[94:97]
	v_mfma_i32_16x16x64_i8 v[134:137], v[146:149], v[186:189], v[134:137]
	v_mfma_i32_16x16x64_i8 v[134:137], v[150:153], v[190:193], v[134:137]
	v_mfma_i32_16x16x64_i8 v[130:133], v[158:161], v[190:193], v[130:133]
	v_mfma_i32_16x16x64_i8 v[130:133], v[154:157], v[186:189], v[130:133]
	v_mfma_i32_16x16x64_i8 v[114:117], v[154:157], v[216:219], v[114:117]
	v_mfma_i32_16x16x64_i8 v[114:117], v[158:161], v[220:223], v[114:117]
	v_mfma_i32_16x16x64_i8 v[118:121], v[150:153], v[220:223], v[118:121]
	v_mfma_i32_16x16x64_i8 v[118:121], v[146:149], v[216:219], v[118:121]
	v_mfma_i32_16x16x64_i8 v[102:105], v[146:149], v[224:227], v[102:105]
	v_mfma_i32_16x16x64_i8 v[102:105], v[150:153], v[228:231], v[102:105]
	v_mfma_i32_16x16x64_i8 v[98:101], v[158:161], v[228:231], v[98:101]
	v_mfma_i32_16x16x64_i8 v[98:101], v[154:157], v[224:227], v[98:101]
	v_mfma_i32_16x16x64_i8 v[74:77], v[154:157], v[232:235], v[74:77]
	v_mfma_i32_16x16x64_i8 v[74:77], v[158:161], v[236:239], v[74:77]
	v_mfma_i32_16x16x64_i8 v[78:81], v[150:153], v[236:239], v[78:81]
	v_mfma_i32_16x16x64_i8 v[78:81], v[146:149], v[232:235], v[78:81]
	s_setprio 0
	s_barrier
	s_add_i32 s47, s23, s7
	v_lshl_add_u64 v[194:195], s[64:65], 0, v[164:165]
	s_mov_b32 m0, s47
	ds_read_b128 v[186:189], v214 offset:16384
	ds_read_b128 v[190:193], v214 offset:17408
	ds_read_b128 v[216:219], v214 offset:18432
	ds_read_b128 v[220:223], v214 offset:19456
	ds_read_b128 v[224:227], v214 offset:20480
	ds_read_b128 v[228:231], v214 offset:21504
	ds_read_b128 v[232:235], v214 offset:22528
	ds_read_b128 v[236:239], v214 offset:23552
	global_load_lds_dwordx4 v[194:195], off
	s_add_i32 m0, s47, 0x2000
	s_add_u32 s68, s64, 0x80000
	v_lshl_add_u64 v[240:241], s[64:65], 0, v[168:169]
	s_addc_u32 s69, s65, 0
	s_add_i32 s47, s24, s7
	global_load_lds_dwordx4 v[240:241], off
	v_lshl_add_u64 v[242:243], s[68:69], 0, v[164:165]
	s_mov_b32 m0, s47
	v_lshl_add_u64 v[244:245], s[66:67], 0, v[166:167]
	global_load_lds_dwordx4 v[242:243], off
	v_lshl_add_u64 v[242:243], s[68:69], 0, v[168:169]
	s_add_i32 m0, s47, 0x2000
	s_nop 0
	global_load_lds_dwordx4 v[242:243], off
	v_lshl_add_u64 v[242:243], s[66:67], 0, v[162:163]
	s_mov_b32 m0, s11
	s_nop 0
	global_load_lds_dwordx4 v[242:243], off
	s_mov_b32 m0, s12
	s_nop 0
	global_load_lds_dwordx4 v[244:245], off
	s_waitcnt vmcnt(8)
	s_waitcnt lgkmcnt(0)
	s_barrier
; #define PG8_STAGE(bufoff, gbase, voff) do { _Pragma("unroll") for (int _i = 0; _i < 2; ++_i) \
;         __builtin_amdgcn_global_load_lds((const unsigned*)((const char*)(gbase) + (voff)[_i]), (PG8_LAS unsigned*)(lds + (bufoff) + ldsw + _i * 8192), 16, 0, 0); } while (0)
; #define PG8_LDA(dst, b, h) do { _Pragma("unroll") for (int m = 0; m < 4; ++m) _Pragma("unroll") for (int k = 0; k < 2; ++k) dst[m][k] = *(const PG8_LAS bf16x8*)(lds + PG8_SA(b, h) + aoff + m * 2048 + k * 1024); } while (0)
; #define PG8_LDB(dst, b, h) do { _Pragma("unroll") for (int n = 0; n < 2; ++n) _Pragma("unroll") for (int k = 0; k < 2; ++k) dst[n][k] = *(const PG8_LAS bf16x8*)(lds + PG8_SB(b, h) + boff + n * 2048 + k * 1024); } while (0)
; template <class Epi, class Sched, bool ALIGN_EPI = false, bool SP2 = false>
; __device__ __forceinline__ void gemm_phase(PG8_LAS unsigned char* lds, const Gemm g, const Sched& S, const Epi& E) {
;     ...
;         for (int t = 0; t < nt; t += 2) {
;             const bool last = (t == nt - 2);
;             const char* a1 = cA + (size_t)(t + 1) * kstep;
;             const char* a2 = last ? nA : cA + (size_t)(t + 2) * kstep; const char* b2 = last ? nB : cB + (size_t)(t + 2) * kstep;
;             const char* a3 = a2 + kstep; const char* b3 = b2 + kstep;
;             if (last && has_next) S.a_ready(nxt);
;             if constexpr (SP2) {
;             PG8_LDB(B0, 0, 0); PG8_LDB(B1, 0, 1); PG8_SCHED; PG8_LDA(At, 0, 0); PG8_STAGE(PG8_SA(1, 1), a1 + hstepA, voffA);
;             PG8_WAIT_V(8); PG8_WAIT_L(0); PG8_BAR; PG8_MMA(0, 0, At, B0); PG8_MMA(0, 1, At, B1); PG8_BAR; PG8_SCHED;
;             PG8_LDA(At, 0, 1); PG8_STAGE(PG8_SB(0, 0), b2, voffB); PG8_STAGE(PG8_SB(0, 1), b2 + hstepB, voffB); PG8_STAGE(PG8_SA(0, 0), a2, voffA);
;             PG8_WAIT_V(8); PG8_WAIT_L(0); PG8_BAR; PG8_MMA(1, 0, At, B0); PG8_MMA(1, 1, At, B1); PG8_BAR; PG8_SCHED;
;             PG8_LDB(B0, 1, 0); PG8_LDB(B1, 1, 1); PG8_SCHED; PG8_LDA(At, 1, 0); PG8_STAGE(PG8_SA(0, 1), a2 + hstepA, voffA);
;             PG8_WAIT_V(8); PG8_WAIT_L(0); PG8_BAR; PG8_MMA(0, 0, At, B0); PG8_MMA(0, 1, At, B1); PG8_BAR; PG8_SCHED;
;             PG8_LDA(At, 1, 1); PG8_STAGE(PG8_SB(1, 0), b3, voffB); PG8_STAGE(PG8_SB(1, 1), b3 + hstepB, voffB); PG8_STAGE(PG8_SA(1, 0), a3, voffA);
;             PG8_WAIT_V(8); PG8_WAIT_L(0); PG8_BAR; PG8_MMA(1, 0, At, B0); PG8_MMA(1, 1, At, B1); PG8_BAR; PG8_SCHED;
	s_setprio 1
	v_mfma_i32_16x16x64_i8 v[62:65], v[82:85], v[186:189], v[62:65]
	v_mfma_i32_16x16x64_i8 v[62:65], v[86:89], v[190:193], v[62:65]
	v_mfma_i32_16x16x64_i8 v[58:61], v[142:145], v[190:193], v[58:61]
	v_mfma_i32_16x16x64_i8 v[58:61], v[138:141], v[186:189], v[58:61]
	v_mfma_i32_16x16x64_i8 v[42:45], v[138:141], v[216:219], v[42:45]
	v_mfma_i32_16x16x64_i8 v[42:45], v[142:145], v[220:223], v[42:45]
	v_mfma_i32_16x16x64_i8 v[46:49], v[86:89], v[220:223], v[46:49]
	v_mfma_i32_16x16x64_i8 v[46:49], v[82:85], v[216:219], v[46:49]
	v_mfma_i32_16x16x64_i8 v[30:33], v[82:85], v[224:227], v[30:33]
	v_mfma_i32_16x16x64_i8 v[30:33], v[86:89], v[228:231], v[30:33]
	v_mfma_i32_16x16x64_i8 v[26:29], v[142:145], v[228:231], v[26:29]
	v_mfma_i32_16x16x64_i8 v[26:29], v[138:141], v[224:227], v[26:29]
	v_mfma_i32_16x16x64_i8 v[10:13], v[138:141], v[232:235], v[10:13]
	v_mfma_i32_16x16x64_i8 v[10:13], v[142:145], v[236:239], v[10:13]
	v_mfma_i32_16x16x64_i8 v[14:17], v[86:89], v[236:239], v[14:17]
	v_mfma_i32_16x16x64_i8 v[14:17], v[82:85], v[232:235], v[14:17]
	v_mfma_i32_16x16x64_i8 v[54:57], v[146:149], v[186:189], v[54:57]
	v_mfma_i32_16x16x64_i8 v[54:57], v[150:153], v[190:193], v[54:57]
	v_mfma_i32_16x16x64_i8 v[50:53], v[158:161], v[190:193], v[50:53]
	v_mfma_i32_16x16x64_i8 v[50:53], v[154:157], v[186:189], v[50:53]
	v_mfma_i32_16x16x64_i8 v[34:37], v[154:157], v[216:219], v[34:37]
	v_mfma_i32_16x16x64_i8 v[34:37], v[158:161], v[220:223], v[34:37]
	v_mfma_i32_16x16x64_i8 v[38:41], v[150:153], v[220:223], v[38:41]
	v_mfma_i32_16x16x64_i8 v[38:41], v[146:149], v[216:219], v[38:41]
	v_mfma_i32_16x16x64_i8 v[22:25], v[146:149], v[224:227], v[22:25]
	v_mfma_i32_16x16x64_i8 v[22:25], v[150:153], v[228:231], v[22:25]
	v_mfma_i32_16x16x64_i8 v[18:21], v[158:161], v[228:231], v[18:21]
	v_mfma_i32_16x16x64_i8 v[18:21], v[154:157], v[224:227], v[18:21]
	v_mfma_i32_16x16x64_i8 v[2:5], v[154:157], v[232:235], v[2:5]
	v_mfma_i32_16x16x64_i8 v[2:5], v[158:161], v[236:239], v[2:5]
	v_mfma_i32_16x16x64_i8 v[6:9], v[150:153], v[236:239], v[6:9]
	v_mfma_i32_16x16x64_i8 v[6:9], v[146:149], v[232:235], v[6:9]
	s_setprio 0
	s_barrier
	s_add_i32 s47, 0, 0x18000
	s_add_i32 s61, 0, 0x1c000
	v_add_u32_e32 v142, s47, v209
	v_add_u32_e32 v158, s61, v209
	ds_read_b128 v[82:85], v142
	ds_read_b128 v[86:89], v142 offset:1024
	ds_read_b128 v[138:141], v142 offset:2048
	ds_read_b128 v[142:145], v142 offset:3072
	ds_read_b128 v[146:149], v158
	ds_read_b128 v[150:153], v158 offset:1024
	ds_read_b128 v[154:157], v158 offset:2048
	ds_read_b128 v[158:161], v158 offset:3072
	s_add_u32 s66, s66, 0x80000
	s_addc_u32 s67, s67, 0
	s_mov_b32 m0, s13
	v_lshl_add_u64 v[246:247], s[66:67], 0, v[162:163]
	ds_read_b128 v[186:189], v214 offset:32768
	ds_read_b128 v[190:193], v214 offset:33792
	ds_read_b128 v[216:219], v214 offset:34816
	ds_read_b128 v[220:223], v214 offset:35840
	ds_read_b128 v[224:227], v214 offset:36864
	ds_read_b128 v[228:231], v214 offset:37888
	ds_read_b128 v[232:235], v214 offset:38912
	ds_read_b128 v[236:239], v214 offset:39936
	global_load_lds_dwordx4 v[246:247], off
	v_lshl_add_u64 v[246:247], s[66:67], 0, v[166:167]
	s_mov_b32 m0, s16
	s_nop 0
	global_load_lds_dwordx4 v[246:247], off
	s_waitcnt vmcnt(8)
	s_waitcnt lgkmcnt(0)
	s_barrier
	s_setprio 1
	v_mfma_i32_16x16x64_i8 v[70:73], v[82:85], v[186:189], v[70:73]
	v_mfma_i32_16x16x64_i8 v[70:73], v[86:89], v[190:193], v[70:73]
	v_mfma_i32_16x16x64_i8 v[66:69], v[142:145], v[190:193], v[66:69]
	v_mfma_i32_16x16x64_i8 v[66:69], v[138:141], v[186:189], v[66:69]
	v_mfma_i32_16x16x64_i8 v[122:125], v[138:141], v[216:219], v[122:125]
	v_mfma_i32_16x16x64_i8 v[122:125], v[142:145], v[220:223], v[122:125]
	v_mfma_i32_16x16x64_i8 v[126:129], v[86:89], v[220:223], v[126:129]
	v_mfma_i32_16x16x64_i8 v[126:129], v[82:85], v[216:219], v[126:129]
	v_mfma_i32_16x16x64_i8 v[110:113], v[82:85], v[224:227], v[110:113]
	v_mfma_i32_16x16x64_i8 v[110:113], v[86:89], v[228:231], v[110:113]
	v_mfma_i32_16x16x64_i8 v[106:109], v[142:145], v[228:231], v[106:109]
	v_mfma_i32_16x16x64_i8 v[106:109], v[138:141], v[224:227], v[106:109]
	v_mfma_i32_16x16x64_i8 v[90:93], v[138:141], v[232:235], v[90:93]
	v_mfma_i32_16x16x64_i8 v[90:93], v[142:145], v[236:239], v[90:93]
	v_mfma_i32_16x16x64_i8 v[94:97], v[86:89], v[236:239], v[94:97]
	v_mfma_i32_16x16x64_i8 v[94:97], v[82:85], v[232:235], v[94:97]
	v_mfma_i32_16x16x64_i8 v[134:137], v[146:149], v[186:189], v[134:137]
	v_mfma_i32_16x16x64_i8 v[134:137], v[150:153], v[190:193], v[134:137]
	v_mfma_i32_16x16x64_i8 v[130:133], v[158:161], v[190:193], v[130:133]
	v_mfma_i32_16x16x64_i8 v[130:133], v[154:157], v[186:189], v[130:133]
	v_mfma_i32_16x16x64_i8 v[114:117], v[154:157], v[216:219], v[114:117]
	v_mfma_i32_16x16x64_i8 v[114:117], v[158:161], v[220:223], v[114:117]
	v_mfma_i32_16x16x64_i8 v[118:121], v[150:153], v[220:223], v[118:121]
	v_mfma_i32_16x16x64_i8 v[118:121], v[146:149], v[216:219], v[118:121]
	v_mfma_i32_16x16x64_i8 v[102:105], v[146:149], v[224:227], v[102:105]
	v_mfma_i32_16x16x64_i8 v[102:105], v[150:153], v[228:231], v[102:105]
	v_mfma_i32_16x16x64_i8 v[98:101], v[158:161], v[228:231], v[98:101]
	v_mfma_i32_16x16x64_i8 v[98:101], v[154:157], v[224:227], v[98:101]
	v_mfma_i32_16x16x64_i8 v[74:77], v[154:157], v[232:235], v[74:77]
	v_mfma_i32_16x16x64_i8 v[74:77], v[158:161], v[236:239], v[74:77]
	v_mfma_i32_16x16x64_i8 v[78:81], v[150:153], v[236:239], v[78:81]
	v_mfma_i32_16x16x64_i8 v[78:81], v[146:149], v[232:235], v[78:81]
	s_setprio 0
	s_barrier
; #define PG8_STAGE(bufoff, gbase, voff) do { _Pragma("unroll") for (int _i = 0; _i < 2; ++_i) \
;         __builtin_amdgcn_global_load_lds((const unsigned*)((const char*)(gbase) + (voff)[_i]), (PG8_LAS unsigned*)(lds + (bufoff) + ldsw + _i * 8192), 16, 0, 0); } while (0)
; #define PG8_LDA(dst, b, h) do { _Pragma("unroll") for (int m = 0; m < 4; ++m) _Pragma("unroll") for (int k = 0; k < 2; ++k) dst[m][k] = *(const PG8_LAS bf16x8*)(lds + PG8_SA(b, h) + aoff + m * 2048 + k * 1024); } while (0)
; #define PG8_MMA(ai, bj, At, Bt) do { __builtin_amdgcn_s_setprio(1); _Pragma("unroll") for (int m = 0; m < 4; ++m) _Pragma("unroll") for (int n = 0; n < 2; ++n) _Pragma("unroll") for (int k = 0; k < 2; ++k) \
;         acc[ai][bj][m][n] = mma16(Bt[n][k], At[m][k], acc[ai][bj][m][n]); __builtin_amdgcn_s_setprio(0); } while (0)
; #define PG8_WAIT_V(n) asm volatile("s_waitcnt vmcnt(" #n ")" ::: "memory")
; #define PG8_WAIT_L(n) asm volatile("s_waitcnt lgkmcnt(" #n ")" ::: "memory")
; #define PG8_BAR __builtin_amdgcn_s_barrier()
; #define PG8_SCHED __builtin_amdgcn_sched_barrier(0)
; template <class Epi, class Sched, bool ALIGN_EPI = false, bool SP2 = false>
; __device__ __forceinline__ void gemm_phase(PG8_LAS unsigned char* lds, const Gemm g, const Sched& S, const Epi& E) {
;     ...
;             PG8_LDA(At, 1, 1); PG8_STAGE(PG8_SB(1, 0), b3, voffB); PG8_STAGE(PG8_SB(1, 1), b3 + hstepB, voffB); PG8_STAGE(PG8_SA(1, 0), a3, voffA);
;             PG8_WAIT_V(8); PG8_WAIT_L(0); PG8_BAR; PG8_MMA(1, 0, At, B0); PG8_MMA(1, 1, At, B1); PG8_BAR; PG8_SCHED;
	s_add_i32 s47, s47, s7
	v_lshl_add_u64 v[194:195], v[194:195], 0, s[50:51]
	s_mov_b32 m0, s47
	ds_read_b128 v[186:189], v214 offset:49152
	ds_read_b128 v[190:193], v214 offset:50176
	ds_read_b128 v[216:219], v214 offset:51200
	ds_read_b128 v[220:223], v214 offset:52224
	ds_read_b128 v[224:227], v214 offset:53248
	ds_read_b128 v[228:231], v214 offset:54272
	ds_read_b128 v[232:235], v214 offset:55296
	ds_read_b128 v[236:239], v214 offset:56320
	global_load_lds_dwordx4 v[194:195], off
	s_add_i32 m0, s47, 0x2000
	s_add_u32 s64, s64, 0x80080
	v_lshl_add_u64 v[194:195], v[240:241], 0, s[50:51]
	s_addc_u32 s65, s65, 0
	s_add_i32 s47, s61, s7
	global_load_lds_dwordx4 v[194:195], off
	v_lshl_add_u64 v[194:195], s[64:65], 0, v[164:165]
	s_mov_b32 m0, s47
	s_nop 0
	global_load_lds_dwordx4 v[194:195], off
	v_lshl_add_u64 v[194:195], s[64:65], 0, v[168:169]
	s_add_i32 m0, s47, 0x2000
	s_nop 0
	global_load_lds_dwordx4 v[194:195], off
	v_lshl_add_u64 v[194:195], v[242:243], 0, s[50:51]
	s_mov_b32 m0, s19
	s_nop 0
	global_load_lds_dwordx4 v[194:195], off
	v_lshl_add_u64 v[194:195], v[244:245], 0, s[50:51]
	s_mov_b32 m0, s20
	s_nop 0
	global_load_lds_dwordx4 v[194:195], off
	s_waitcnt vmcnt(8)
	s_waitcnt lgkmcnt(0)
	s_barrier
	s_setprio 1
	v_mfma_i32_16x16x64_i8 v[62:65], v[82:85], v[186:189], v[62:65]
	v_mfma_i32_16x16x64_i8 v[62:65], v[86:89], v[190:193], v[62:65]
	v_mfma_i32_16x16x64_i8 v[58:61], v[142:145], v[190:193], v[58:61]
	v_mfma_i32_16x16x64_i8 v[58:61], v[138:141], v[186:189], v[58:61]
	v_mfma_i32_16x16x64_i8 v[42:45], v[138:141], v[216:219], v[42:45]
	v_mfma_i32_16x16x64_i8 v[42:45], v[142:145], v[220:223], v[42:45]
	v_mfma_i32_16x16x64_i8 v[46:49], v[86:89], v[220:223], v[46:49]
	v_mfma_i32_16x16x64_i8 v[46:49], v[82:85], v[216:219], v[46:49]
	v_mfma_i32_16x16x64_i8 v[30:33], v[82:85], v[224:227], v[30:33]
	v_mfma_i32_16x16x64_i8 v[30:33], v[86:89], v[228:231], v[30:33]
	v_mfma_i32_16x16x64_i8 v[26:29], v[142:145], v[228:231], v[26:29]
	v_mfma_i32_16x16x64_i8 v[26:29], v[138:141], v[224:227], v[26:29]
	v_mfma_i32_16x16x64_i8 v[10:13], v[138:141], v[232:235], v[10:13]
	v_mfma_i32_16x16x64_i8 v[10:13], v[142:145], v[236:239], v[10:13]
	v_mfma_i32_16x16x64_i8 v[14:17], v[86:89], v[236:239], v[14:17]
	v_mfma_i32_16x16x64_i8 v[14:17], v[82:85], v[232:235], v[14:17]
	v_mfma_i32_16x16x64_i8 v[54:57], v[146:149], v[186:189], v[54:57]
	v_mfma_i32_16x16x64_i8 v[54:57], v[150:153], v[190:193], v[54:57]
	v_mfma_i32_16x16x64_i8 v[50:53], v[158:161], v[190:193], v[50:53]
	v_mfma_i32_16x16x64_i8 v[50:53], v[154:157], v[186:189], v[50:53]
	v_mfma_i32_16x16x64_i8 v[34:37], v[154:157], v[216:219], v[34:37]
	v_mfma_i32_16x16x64_i8 v[34:37], v[158:161], v[220:223], v[34:37]
	v_mfma_i32_16x16x64_i8 v[38:41], v[150:153], v[220:223], v[38:41]
	v_mfma_i32_16x16x64_i8 v[38:41], v[146:149], v[216:219], v[38:41]
	v_mfma_i32_16x16x64_i8 v[22:25], v[146:149], v[224:227], v[22:25]
	v_mfma_i32_16x16x64_i8 v[22:25], v[150:153], v[228:231], v[22:25]
	v_mfma_i32_16x16x64_i8 v[18:21], v[158:161], v[228:231], v[18:21]
	v_mfma_i32_16x16x64_i8 v[18:21], v[154:157], v[224:227], v[18:21]
	v_mfma_i32_16x16x64_i8 v[2:5], v[154:157], v[232:235], v[2:5]
	v_mfma_i32_16x16x64_i8 v[2:5], v[158:161], v[236:239], v[2:5]
	v_mfma_i32_16x16x64_i8 v[6:9], v[150:153], v[236:239], v[6:9]
	v_mfma_i32_16x16x64_i8 v[6:9], v[146:149], v[232:235], v[6:9]
	s_setprio 0
	s_barrier
	s_add_i32 s46, s46, 2
	s_add_u32 s62, s62, 0x100
	s_addc_u32 s63, s63, 0
	s_add_u32 s36, s36, 0x100
	s_addc_u32 s37, s37, 0
	s_cmp_gt_u32 s46, 29
	s_cbranch_scc0 .LBB0_555
	s_and_b64 vcc, exec, s[52:53]
	s_cbranch_vccz .LBB0_558
	s_barrier

; #define PG8_STAGE(bufoff, gbase, voff) do { _Pragma("unroll") for (int _i = 0; _i < 2; ++_i) \
;         __builtin_amdgcn_global_load_lds((const unsigned*)((const char*)(gbase) + (voff)[_i]), (PG8_LAS unsigned*)(lds + (bufoff) + ldsw + _i * 8192), 16, 0, 0); } while (0)
; #define PG8_LDA(dst, b, h) do { _Pragma("unroll") for (int m = 0; m < 4; ++m) _Pragma("unroll") for (int k = 0; k < 2; ++k) dst[m][k] = *(const PG8_LAS bf16x8*)(lds + PG8_SA(b, h) + aoff + m * 2048 + k * 1024); } while (0)
; #define PG8_LDB(dst, b, h) do { _Pragma("unroll") for (int n = 0; n < 2; ++n) _Pragma("unroll") for (int k = 0; k < 2; ++k) dst[n][k] = *(const PG8_LAS bf16x8*)(lds + PG8_SB(b, h) + boff + n * 2048 + k * 1024); } while (0)
; #define PG8_MMA(ai, bj, At, Bt) do { __builtin_amdgcn_s_setprio(1); _Pragma("unroll") for (int m = 0; m < 4; ++m) _Pragma("unroll") for (int n = 0; n < 2; ++n) _Pragma("unroll") for (int k = 0; k < 2; ++k) \
;         acc[ai][bj][m][n] = mma16(Bt[n][k], At[m][k], acc[ai][bj][m][n]); __builtin_amdgcn_s_setprio(0); } while (0)
; #define PG8_WAIT_V(n) asm volatile("s_waitcnt vmcnt(" #n ")" ::: "memory")
; #define PG8_WAIT_L(n) asm volatile("s_waitcnt lgkmcnt(" #n ")" ::: "memory")
; template <class Epi, class Sched, bool ALIGN_EPI = false, bool SP2 = false>
; __device__ __forceinline__ void gemm_phase(PG8_LAS unsigned char* lds, const Gemm g, const Sched& S, const Epi& E) {
;     ...
;         for (int t = 0; t < nt; t += 2) {
;             const bool last = (t == nt - 2);
;             const char* a1 = cA + (size_t)(t + 1) * kstep;
;             const char* a2 = last ? nA : cA + (size_t)(t + 2) * kstep; const char* b2 = last ? nB : cB + (size_t)(t + 2) * kstep;
;             const char* a3 = a2 + kstep; const char* b3 = b2 + kstep;
;             if (last && has_next) S.a_ready(nxt);
;             if constexpr (SP2) {
;             PG8_LDB(B0, 0, 0); PG8_LDB(B1, 0, 1); PG8_SCHED; PG8_LDA(At, 0, 0); PG8_STAGE(PG8_SA(1, 1), a1 + hstepA, voffA);
;             PG8_WAIT_V(8); PG8_WAIT_L(0); PG8_BAR; PG8_MMA(0, 0, At, B0); PG8_MMA(0, 1, At, B1); PG8_BAR; PG8_SCHED;
;             PG8_LDA(At, 0, 1); PG8_STAGE(PG8_SB(0, 0), b2, voffB); PG8_STAGE(PG8_SB(0, 1), b2 + hstepB, voffB); PG8_STAGE(PG8_SA(0, 0), a2, voffA);
;             PG8_WAIT_V(8); PG8_WAIT_L(0); PG8_BAR; PG8_MMA(1, 0, At, B0); PG8_MMA(1, 1, At, B1); PG8_BAR; PG8_SCHED;
.LBB0_579:
	ds_read_b128 v[130:133], v1
	ds_read_b128 v[134:137], v1 offset:1024
	ds_read_b128 v[138:141], v1 offset:2048
	ds_read_b128 v[142:145], v1 offset:3072
	ds_read_b128 v[146:149], v214
	ds_read_b128 v[150:153], v214 offset:1024
	ds_read_b128 v[154:157], v214 offset:2048
	ds_read_b128 v[158:161], v214 offset:3072
	s_add_u32 s35, s56, 0xfff00080
	s_addc_u32 s36, s57, -1
	s_cmp_eq_u32 s33, 60
	s_cselect_b32 s61, s24, s36
	s_cselect_b32 s60, s25, s35
	s_cselect_b32 s59, s26, s29
	s_cselect_b32 s58, s27, s28
	v_lshl_add_u64 v[220:221], s[56:57], 0, v[190:191]
	s_add_i32 m0, s8, 0xc000
	ds_read_b128 v[162:165], v215
	ds_read_b128 v[166:169], v215 offset:1024
	ds_read_b128 v[170:173], v215 offset:2048
	ds_read_b128 v[174:177], v215 offset:3072
	ds_read_b128 v[198:201], v215 offset:4096
	ds_read_b128 v[202:205], v215 offset:5120
	ds_read_b128 v[206:209], v215 offset:6144
	ds_read_b128 v[216:219], v215 offset:7168
	global_load_lds_dwordx4 v[220:221], off
	v_lshl_add_u64 v[220:221], s[56:57], 0, v[192:193]
	s_add_i32 m0, s8, 0xe000
	s_nop 0
	global_load_lds_dwordx4 v[220:221], off
	s_waitcnt vmcnt(8)
	s_waitcnt lgkmcnt(0)
	s_barrier
	s_setprio 1
	v_mfma_f32_16x16x32_bf16 v[126:129], v[130:133], v[162:165], v[126:129]
	v_mfma_f32_16x16x32_bf16 v[126:129], v[134:137], v[166:169], v[126:129]
	v_mfma_f32_16x16x32_bf16 v[122:125], v[142:145], v[166:169], v[122:125]
	v_mfma_f32_16x16x32_bf16 v[122:125], v[138:141], v[162:165], v[122:125]
	v_mfma_f32_16x16x32_bf16 v[106:109], v[138:141], v[170:173], v[106:109]
	v_mfma_f32_16x16x32_bf16 v[106:109], v[142:145], v[174:177], v[106:109]
	v_mfma_f32_16x16x32_bf16 v[110:113], v[134:137], v[174:177], v[110:113]
	v_mfma_f32_16x16x32_bf16 v[110:113], v[130:133], v[170:173], v[110:113]
	v_mfma_f32_16x16x32_bf16 v[94:97], v[130:133], v[198:201], v[94:97]
	v_mfma_f32_16x16x32_bf16 v[94:97], v[134:137], v[202:205], v[94:97]
	v_mfma_f32_16x16x32_bf16 v[90:93], v[142:145], v[202:205], v[90:93]
	v_mfma_f32_16x16x32_bf16 v[90:93], v[138:141], v[198:201], v[90:93]
	v_mfma_f32_16x16x32_bf16 v[74:77], v[138:141], v[206:209], v[74:77]
	v_mfma_f32_16x16x32_bf16 v[74:77], v[142:145], v[216:219], v[74:77]
	v_mfma_f32_16x16x32_bf16 v[78:81], v[134:137], v[216:219], v[78:81]
	v_mfma_f32_16x16x32_bf16 v[78:81], v[130:133], v[206:209], v[78:81]
	v_mfma_f32_16x16x32_bf16 v[118:121], v[146:149], v[162:165], v[118:121]
	v_mfma_f32_16x16x32_bf16 v[118:121], v[150:153], v[166:169], v[118:121]
	v_mfma_f32_16x16x32_bf16 v[114:117], v[158:161], v[166:169], v[114:117]
	v_mfma_f32_16x16x32_bf16 v[114:117], v[154:157], v[162:165], v[114:117]
	v_mfma_f32_16x16x32_bf16 v[98:101], v[154:157], v[170:173], v[98:101]
	v_mfma_f32_16x16x32_bf16 v[98:101], v[158:161], v[174:177], v[98:101]
	v_mfma_f32_16x16x32_bf16 v[102:105], v[150:153], v[174:177], v[102:105]
	v_mfma_f32_16x16x32_bf16 v[102:105], v[146:149], v[170:173], v[102:105]
	v_mfma_f32_16x16x32_bf16 v[86:89], v[146:149], v[198:201], v[86:89]
	v_mfma_f32_16x16x32_bf16 v[86:89], v[150:153], v[202:205], v[86:89]
	v_mfma_f32_16x16x32_bf16 v[82:85], v[158:161], v[202:205], v[82:85]
	v_mfma_f32_16x16x32_bf16 v[82:85], v[154:157], v[198:201], v[82:85]
	v_mfma_f32_16x16x32_bf16 v[66:69], v[154:157], v[206:209], v[66:69]
	v_mfma_f32_16x16x32_bf16 v[66:69], v[158:161], v[216:219], v[66:69]
	v_mfma_f32_16x16x32_bf16 v[70:73], v[150:153], v[216:219], v[70:73]
	v_mfma_f32_16x16x32_bf16 v[70:73], v[146:149], v[206:209], v[70:73]
	s_setprio 0
	s_barrier
	s_add_i32 s35, s21, s7
	v_lshl_add_u64 v[220:221], s[58:59], 0, v[184:185]
	s_mov_b32 m0, s35
	ds_read_b128 v[162:165], v215 offset:16384
	ds_read_b128 v[166:169], v215 offset:17408
	ds_read_b128 v[170:173], v215 offset:18432
	ds_read_b128 v[174:177], v215 offset:19456
	ds_read_b128 v[198:201], v215 offset:20480
	ds_read_b128 v[202:205], v215 offset:21504
	ds_read_b128 v[206:209], v215 offset:22528
	ds_read_b128 v[216:219], v215 offset:23552
	global_load_lds_dwordx4 v[220:221], off
	s_add_i32 m0, s35, 0x2000
	s_add_u32 s36, s58, 0x100000
	v_lshl_add_u64 v[222:223], s[58:59], 0, v[188:189]
	s_addc_u32 s37, s59, 0
	s_add_i32 s35, s22, s7
	global_load_lds_dwordx4 v[222:223], off
	v_lshl_add_u64 v[224:225], s[36:37], 0, v[184:185]
	s_mov_b32 m0, s35
	v_lshl_add_u64 v[226:227], s[60:61], 0, v[186:187]
	global_load_lds_dwordx4 v[224:225], off
	v_lshl_add_u64 v[224:225], s[36:37], 0, v[188:189]
	s_add_i32 m0, s35, 0x2000
	s_nop 0
	global_load_lds_dwordx4 v[224:225], off
	v_lshl_add_u64 v[224:225], s[60:61], 0, v[182:183]
	s_mov_b32 m0, s8
	s_nop 0
	global_load_lds_dwordx4 v[224:225], off
	s_mov_b32 m0, s11
	s_nop 0
	global_load_lds_dwordx4 v[226:227], off
	s_waitcnt vmcnt(8)
	s_waitcnt lgkmcnt(0)
	s_barrier
; #define PG8_STAGE(bufoff, gbase, voff) do { _Pragma("unroll") for (int _i = 0; _i < 2; ++_i) \
;         __builtin_amdgcn_global_load_lds((const unsigned*)((const char*)(gbase) + (voff)[_i]), (PG8_LAS unsigned*)(lds + (bufoff) + ldsw + _i * 8192), 16, 0, 0); } while (0)
; #define PG8_LDA(dst, b, h) do { _Pragma("unroll") for (int m = 0; m < 4; ++m) _Pragma("unroll") for (int k = 0; k < 2; ++k) dst[m][k] = *(const PG8_LAS bf16x8*)(lds + PG8_SA(b, h) + aoff + m * 2048 + k * 1024); } while (0)
; #define PG8_LDB(dst, b, h) do { _Pragma("unroll") for (int n = 0; n < 2; ++n) _Pragma("unroll") for (int k = 0; k < 2; ++k) dst[n][k] = *(const PG8_LAS bf16x8*)(lds + PG8_SB(b, h) + boff + n * 2048 + k * 1024); } while (0)
; #define PG8_MMA(ai, bj, At, Bt) do { __builtin_amdgcn_s_setprio(1); _Pragma("unroll") for (int m = 0; m < 4; ++m) _Pragma("unroll") for (int n = 0; n < 2; ++n) _Pragma("unroll") for (int k = 0; k < 2; ++k) \
;         acc[ai][bj][m][n] = mma16(Bt[n][k], At[m][k], acc[ai][bj][m][n]); __builtin_amdgcn_s_setprio(0); } while (0)
; #define PG8_WAIT_V(n) asm volatile("s_waitcnt vmcnt(" #n ")" ::: "memory")
; #define PG8_WAIT_L(n) asm volatile("s_waitcnt lgkmcnt(" #n ")" ::: "memory")
; #define PG8_BAR __builtin_amdgcn_s_barrier()
; #define PG8_SCHED __builtin_amdgcn_sched_barrier(0)
; template <class Epi, class Sched, bool ALIGN_EPI = false, bool SP2 = false>
; __device__ __forceinline__ void gemm_phase(PG8_LAS unsigned char* lds, const Gemm g, const Sched& S, const Epi& E) {
;     ...
;             PG8_WAIT_V(8); PG8_WAIT_L(0); PG8_BAR; PG8_MMA(1, 0, At, B0); PG8_MMA(1, 1, At, B1); PG8_BAR; PG8_SCHED;
;             PG8_LDB(B0, 1, 0); PG8_LDB(B1, 1, 1); PG8_SCHED; PG8_LDA(At, 1, 0); PG8_STAGE(PG8_SA(0, 1), a2 + hstepA, voffA);
;             PG8_WAIT_V(8); PG8_WAIT_L(0); PG8_BAR; PG8_MMA(0, 0, At, B0); PG8_MMA(0, 1, At, B1); PG8_BAR; PG8_SCHED;
	s_setprio 1
	v_mfma_f32_16x16x32_bf16 v[62:65], v[130:133], v[162:165], v[62:65]
	v_mfma_f32_16x16x32_bf16 v[62:65], v[134:137], v[166:169], v[62:65]
	v_mfma_f32_16x16x32_bf16 v[58:61], v[142:145], v[166:169], v[58:61]
	v_mfma_f32_16x16x32_bf16 v[58:61], v[138:141], v[162:165], v[58:61]
	v_mfma_f32_16x16x32_bf16 v[42:45], v[138:141], v[170:173], v[42:45]
	v_mfma_f32_16x16x32_bf16 v[42:45], v[142:145], v[174:177], v[42:45]
	v_mfma_f32_16x16x32_bf16 v[46:49], v[134:137], v[174:177], v[46:49]
	v_mfma_f32_16x16x32_bf16 v[46:49], v[130:133], v[170:173], v[46:49]
	v_mfma_f32_16x16x32_bf16 v[30:33], v[130:133], v[198:201], v[30:33]
	v_mfma_f32_16x16x32_bf16 v[30:33], v[134:137], v[202:205], v[30:33]
	v_mfma_f32_16x16x32_bf16 v[26:29], v[142:145], v[202:205], v[26:29]
	v_mfma_f32_16x16x32_bf16 v[26:29], v[138:141], v[198:201], v[26:29]
	v_mfma_f32_16x16x32_bf16 v[10:13], v[138:141], v[206:209], v[10:13]
	v_mfma_f32_16x16x32_bf16 v[10:13], v[142:145], v[216:219], v[10:13]
	v_mfma_f32_16x16x32_bf16 v[14:17], v[134:137], v[216:219], v[14:17]
	v_mfma_f32_16x16x32_bf16 v[14:17], v[130:133], v[206:209], v[14:17]
	v_mfma_f32_16x16x32_bf16 v[54:57], v[146:149], v[162:165], v[54:57]
	v_mfma_f32_16x16x32_bf16 v[54:57], v[150:153], v[166:169], v[54:57]
	v_mfma_f32_16x16x32_bf16 v[50:53], v[158:161], v[166:169], v[50:53]
	v_mfma_f32_16x16x32_bf16 v[50:53], v[154:157], v[162:165], v[50:53]
	v_mfma_f32_16x16x32_bf16 v[34:37], v[154:157], v[170:173], v[34:37]
	v_mfma_f32_16x16x32_bf16 v[34:37], v[158:161], v[174:177], v[34:37]
	v_mfma_f32_16x16x32_bf16 v[38:41], v[150:153], v[174:177], v[38:41]
	v_mfma_f32_16x16x32_bf16 v[38:41], v[146:149], v[170:173], v[38:41]
	v_mfma_f32_16x16x32_bf16 v[22:25], v[146:149], v[198:201], v[22:25]
	v_mfma_f32_16x16x32_bf16 v[22:25], v[150:153], v[202:205], v[22:25]
	v_mfma_f32_16x16x32_bf16 v[18:21], v[158:161], v[202:205], v[18:21]
	v_mfma_f32_16x16x32_bf16 v[18:21], v[154:157], v[198:201], v[18:21]
	v_mfma_f32_16x16x32_bf16 v[2:5], v[154:157], v[206:209], v[2:5]
	v_mfma_f32_16x16x32_bf16 v[2:5], v[158:161], v[216:219], v[2:5]
	v_mfma_f32_16x16x32_bf16 v[6:9], v[150:153], v[216:219], v[6:9]
	v_mfma_f32_16x16x32_bf16 v[6:9], v[146:149], v[206:209], v[6:9]
	s_setprio 0
	s_barrier
	s_add_i32 s35, 0, 0x18000
	s_add_i32 s43, 0, 0x1c000
	v_add_u32_e32 v142, s35, v212
	v_add_u32_e32 v158, s43, v212
	ds_read_b128 v[130:133], v142
	ds_read_b128 v[134:137], v142 offset:1024
	ds_read_b128 v[138:141], v142 offset:2048
	ds_read_b128 v[142:145], v142 offset:3072
	ds_read_b128 v[146:149], v158
	ds_read_b128 v[150:153], v158 offset:1024
	ds_read_b128 v[154:157], v158 offset:2048
	ds_read_b128 v[158:161], v158 offset:3072
	s_add_u32 s36, s60, 0x100000
	s_addc_u32 s37, s61, 0
	s_mov_b32 m0, s12
	v_lshl_add_u64 v[228:229], s[36:37], 0, v[182:183]
	ds_read_b128 v[162:165], v215 offset:32768
	ds_read_b128 v[166:169], v215 offset:33792
	ds_read_b128 v[170:173], v215 offset:34816
	ds_read_b128 v[174:177], v215 offset:35840
	ds_read_b128 v[198:201], v215 offset:36864
	ds_read_b128 v[202:205], v215 offset:37888
	ds_read_b128 v[206:209], v215 offset:38912
	ds_read_b128 v[216:219], v215 offset:39936
	global_load_lds_dwordx4 v[228:229], off
	v_lshl_add_u64 v[228:229], s[36:37], 0, v[186:187]
	s_mov_b32 m0, s13
	s_nop 0
	global_load_lds_dwordx4 v[228:229], off
	s_waitcnt vmcnt(8)
	s_waitcnt lgkmcnt(0)
	s_barrier
	s_setprio 1
	v_mfma_f32_16x16x32_bf16 v[126:129], v[130:133], v[162:165], v[126:129]
	v_mfma_f32_16x16x32_bf16 v[126:129], v[134:137], v[166:169], v[126:129]
	v_mfma_f32_16x16x32_bf16 v[122:125], v[142:145], v[166:169], v[122:125]
	v_mfma_f32_16x16x32_bf16 v[122:125], v[138:141], v[162:165], v[122:125]
	v_mfma_f32_16x16x32_bf16 v[106:109], v[138:141], v[170:173], v[106:109]
	v_mfma_f32_16x16x32_bf16 v[106:109], v[142:145], v[174:177], v[106:109]
	v_mfma_f32_16x16x32_bf16 v[110:113], v[134:137], v[174:177], v[110:113]
	v_mfma_f32_16x16x32_bf16 v[110:113], v[130:133], v[170:173], v[110:113]
	v_mfma_f32_16x16x32_bf16 v[94:97], v[130:133], v[198:201], v[94:97]
	v_mfma_f32_16x16x32_bf16 v[94:97], v[134:137], v[202:205], v[94:97]
	v_mfma_f32_16x16x32_bf16 v[90:93], v[142:145], v[202:205], v[90:93]
	v_mfma_f32_16x16x32_bf16 v[90:93], v[138:141], v[198:201], v[90:93]
	v_mfma_f32_16x16x32_bf16 v[74:77], v[138:141], v[206:209], v[74:77]
	v_mfma_f32_16x16x32_bf16 v[74:77], v[142:145], v[216:219], v[74:77]
	v_mfma_f32_16x16x32_bf16 v[78:81], v[134:137], v[216:219], v[78:81]
	v_mfma_f32_16x16x32_bf16 v[78:81], v[130:133], v[206:209], v[78:81]
	v_mfma_f32_16x16x32_bf16 v[118:121], v[146:149], v[162:165], v[118:121]
	v_mfma_f32_16x16x32_bf16 v[118:121], v[150:153], v[166:169], v[118:121]
	v_mfma_f32_16x16x32_bf16 v[114:117], v[158:161], v[166:169], v[114:117]
	v_mfma_f32_16x16x32_bf16 v[114:117], v[154:157], v[162:165], v[114:117]
	v_mfma_f32_16x16x32_bf16 v[98:101], v[154:157], v[170:173], v[98:101]
	v_mfma_f32_16x16x32_bf16 v[98:101], v[158:161], v[174:177], v[98:101]
	v_mfma_f32_16x16x32_bf16 v[102:105], v[150:153], v[174:177], v[102:105]
	v_mfma_f32_16x16x32_bf16 v[102:105], v[146:149], v[170:173], v[102:105]
	v_mfma_f32_16x16x32_bf16 v[86:89], v[146:149], v[198:201], v[86:89]
	v_mfma_f32_16x16x32_bf16 v[86:89], v[150:153], v[202:205], v[86:89]
	v_mfma_f32_16x16x32_bf16 v[82:85], v[158:161], v[202:205], v[82:85]
	v_mfma_f32_16x16x32_bf16 v[82:85], v[154:157], v[198:201], v[82:85]
	v_mfma_f32_16x16x32_bf16 v[66:69], v[154:157], v[206:209], v[66:69]
	v_mfma_f32_16x16x32_bf16 v[66:69], v[158:161], v[216:219], v[66:69]
	v_mfma_f32_16x16x32_bf16 v[70:73], v[150:153], v[216:219], v[70:73]
	v_mfma_f32_16x16x32_bf16 v[70:73], v[146:149], v[206:209], v[70:73]
	s_setprio 0
	s_barrier
; #define PG8_STAGE(bufoff, gbase, voff) do { _Pragma("unroll") for (int _i = 0; _i < 2; ++_i) \
;         __builtin_amdgcn_global_load_lds((const unsigned*)((const char*)(gbase) + (voff)[_i]), (PG8_LAS unsigned*)(lds + (bufoff) + ldsw + _i * 8192), 16, 0, 0); } while (0)
; #define PG8_LDA(dst, b, h) do { _Pragma("unroll") for (int m = 0; m < 4; ++m) _Pragma("unroll") for (int k = 0; k < 2; ++k) dst[m][k] = *(const PG8_LAS bf16x8*)(lds + PG8_SA(b, h) + aoff + m * 2048 + k * 1024); } while (0)
; #define PG8_MMA(ai, bj, At, Bt) do { __builtin_amdgcn_s_setprio(1); _Pragma("unroll") for (int m = 0; m < 4; ++m) _Pragma("unroll") for (int n = 0; n < 2; ++n) _Pragma("unroll") for (int k = 0; k < 2; ++k) \
;         acc[ai][bj][m][n] = mma16(Bt[n][k], At[m][k], acc[ai][bj][m][n]); __builtin_amdgcn_s_setprio(0); } while (0)
; #define PG8_WAIT_V(n) asm volatile("s_waitcnt vmcnt(" #n ")" ::: "memory")
; #define PG8_WAIT_L(n) asm volatile("s_waitcnt lgkmcnt(" #n ")" ::: "memory")
; #define PG8_BAR __builtin_amdgcn_s_barrier()
; #define PG8_SCHED __builtin_amdgcn_sched_barrier(0)
; template <class Epi, class Sched, bool ALIGN_EPI = false, bool SP2 = false>
; __device__ __forceinline__ void gemm_phase(PG8_LAS unsigned char* lds, const Gemm g, const Sched& S, const Epi& E) {
;     ...
;             PG8_LDA(At, 1, 1); PG8_STAGE(PG8_SB(1, 0), b3, voffB); PG8_STAGE(PG8_SB(1, 1), b3 + hstepB, voffB); PG8_STAGE(PG8_SA(1, 0), a3, voffA);
;             PG8_WAIT_V(8); PG8_WAIT_L(0); PG8_BAR; PG8_MMA(1, 0, At, B0); PG8_MMA(1, 1, At, B1); PG8_BAR; PG8_SCHED;
	s_add_i32 s35, s35, s7
	v_lshl_add_u64 v[220:221], v[220:221], 0, s[38:39]
	s_mov_b32 m0, s35
	ds_read_b128 v[162:165], v215 offset:49152
	ds_read_b128 v[166:169], v215 offset:50176
	ds_read_b128 v[170:173], v215 offset:51200
	ds_read_b128 v[174:177], v215 offset:52224
	ds_read_b128 v[198:201], v215 offset:53248
	ds_read_b128 v[202:205], v215 offset:54272
	ds_read_b128 v[206:209], v215 offset:55296
	ds_read_b128 v[216:219], v215 offset:56320
	global_load_lds_dwordx4 v[220:221], off
	s_add_i32 m0, s35, 0x2000
	s_add_u32 s36, s58, 0x100080
	v_lshl_add_u64 v[220:221], v[222:223], 0, s[38:39]
	s_addc_u32 s37, s59, 0
	s_add_i32 s35, s43, s7
	global_load_lds_dwordx4 v[220:221], off
	v_lshl_add_u64 v[220:221], s[36:37], 0, v[184:185]
	s_mov_b32 m0, s35
	s_nop 0
	global_load_lds_dwordx4 v[220:221], off
	v_lshl_add_u64 v[220:221], s[36:37], 0, v[188:189]
	s_add_i32 m0, s35, 0x2000
	s_nop 0
	global_load_lds_dwordx4 v[220:221], off
	v_lshl_add_u64 v[220:221], v[224:225], 0, s[38:39]
	s_mov_b32 m0, s17
	s_nop 0
	global_load_lds_dwordx4 v[220:221], off
	v_lshl_add_u64 v[220:221], v[226:227], 0, s[38:39]
	s_mov_b32 m0, s18
	s_nop 0
	global_load_lds_dwordx4 v[220:221], off
	s_waitcnt vmcnt(8)
	s_waitcnt lgkmcnt(0)
	s_barrier
	s_setprio 1
	v_mfma_f32_16x16x32_bf16 v[62:65], v[130:133], v[162:165], v[62:65]
	v_mfma_f32_16x16x32_bf16 v[62:65], v[134:137], v[166:169], v[62:65]
	v_mfma_f32_16x16x32_bf16 v[58:61], v[142:145], v[166:169], v[58:61]
	v_mfma_f32_16x16x32_bf16 v[58:61], v[138:141], v[162:165], v[58:61]
	v_mfma_f32_16x16x32_bf16 v[42:45], v[138:141], v[170:173], v[42:45]
	v_mfma_f32_16x16x32_bf16 v[42:45], v[142:145], v[174:177], v[42:45]
	v_mfma_f32_16x16x32_bf16 v[46:49], v[134:137], v[174:177], v[46:49]
	v_mfma_f32_16x16x32_bf16 v[46:49], v[130:133], v[170:173], v[46:49]
	v_mfma_f32_16x16x32_bf16 v[30:33], v[130:133], v[198:201], v[30:33]
	v_mfma_f32_16x16x32_bf16 v[30:33], v[134:137], v[202:205], v[30:33]
	v_mfma_f32_16x16x32_bf16 v[26:29], v[142:145], v[202:205], v[26:29]
	v_mfma_f32_16x16x32_bf16 v[26:29], v[138:141], v[198:201], v[26:29]
	v_mfma_f32_16x16x32_bf16 v[10:13], v[138:141], v[206:209], v[10:13]
	v_mfma_f32_16x16x32_bf16 v[10:13], v[142:145], v[216:219], v[10:13]
	v_mfma_f32_16x16x32_bf16 v[14:17], v[134:137], v[216:219], v[14:17]
	v_mfma_f32_16x16x32_bf16 v[14:17], v[130:133], v[206:209], v[14:17]
	v_mfma_f32_16x16x32_bf16 v[54:57], v[146:149], v[162:165], v[54:57]
	v_mfma_f32_16x16x32_bf16 v[54:57], v[150:153], v[166:169], v[54:57]
	v_mfma_f32_16x16x32_bf16 v[50:53], v[158:161], v[166:169], v[50:53]
	v_mfma_f32_16x16x32_bf16 v[50:53], v[154:157], v[162:165], v[50:53]
	v_mfma_f32_16x16x32_bf16 v[34:37], v[154:157], v[170:173], v[34:37]
	v_mfma_f32_16x16x32_bf16 v[34:37], v[158:161], v[174:177], v[34:37]
	v_mfma_f32_16x16x32_bf16 v[38:41], v[150:153], v[174:177], v[38:41]
	v_mfma_f32_16x16x32_bf16 v[38:41], v[146:149], v[170:173], v[38:41]
	v_mfma_f32_16x16x32_bf16 v[22:25], v[146:149], v[198:201], v[22:25]
	v_mfma_f32_16x16x32_bf16 v[22:25], v[150:153], v[202:205], v[22:25]
	v_mfma_f32_16x16x32_bf16 v[18:21], v[158:161], v[202:205], v[18:21]
	v_mfma_f32_16x16x32_bf16 v[18:21], v[154:157], v[198:201], v[18:21]
	v_mfma_f32_16x16x32_bf16 v[2:5], v[154:157], v[206:209], v[2:5]
	v_mfma_f32_16x16x32_bf16 v[2:5], v[158:161], v[216:219], v[2:5]
	v_mfma_f32_16x16x32_bf16 v[6:9], v[150:153], v[216:219], v[6:9]
	v_mfma_f32_16x16x32_bf16 v[6:9], v[146:149], v[206:209], v[6:9]
	s_setprio 0
	s_barrier
	s_add_i32 s33, s33, 2
	s_add_u32 s56, s56, 0x100
	s_addc_u32 s57, s57, 0
	s_add_u32 s28, s28, 0x100
	s_addc_u32 s29, s29, 0
	s_cmp_gt_u32 s33, 61
	s_cbranch_scc0 .LBB0_579
	s_and_b64 vcc, exec, s[40:41]
	s_cbranch_vccz .LBB0_582
	s_barrier

; #define PG8_STAGE(bufoff, gbase, voff) do { _Pragma("unroll") for (int _i = 0; _i < 2; ++_i) \
;         __builtin_amdgcn_global_load_lds((const unsigned*)((const char*)(gbase) + (voff)[_i]), (PG8_LAS unsigned*)(lds + (bufoff) + ldsw + _i * 8192), 16, 0, 0); } while (0)
; #define PG8_LDA(dst, b, h) do { _Pragma("unroll") for (int m = 0; m < 4; ++m) _Pragma("unroll") for (int k = 0; k < 2; ++k) dst[m][k] = *(const PG8_LAS bf16x8*)(lds + PG8_SA(b, h) + aoff + m * 2048 + k * 1024); } while (0)
; #define PG8_LDB(dst, b, h) do { _Pragma("unroll") for (int n = 0; n < 2; ++n) _Pragma("unroll") for (int k = 0; k < 2; ++k) dst[n][k] = *(const PG8_LAS bf16x8*)(lds + PG8_SB(b, h) + boff + n * 2048 + k * 1024); } while (0)
; #define PG8_MMA(ai, bj, At, Bt) do { __builtin_amdgcn_s_setprio(1); _Pragma("unroll") for (int m = 0; m < 4; ++m) _Pragma("unroll") for (int n = 0; n < 2; ++n) _Pragma("unroll") for (int k = 0; k < 2; ++k) \
;         acc[ai][bj][m][n] = mma16(Bt[n][k], At[m][k], acc[ai][bj][m][n]); __builtin_amdgcn_s_setprio(0); } while (0)
; #define PG8_WAIT_V(n) asm volatile("s_waitcnt vmcnt(" #n ")" ::: "memory")
; #define PG8_WAIT_L(n) asm volatile("s_waitcnt lgkmcnt(" #n ")" ::: "memory")
; template <class Epi, class Sched, bool ALIGN_EPI = false, bool SP2 = false>
; __device__ __forceinline__ void gemm_phase(PG8_LAS unsigned char* lds, const Gemm g, const Sched& S, const Epi& E) {
;     ...
;         for (int t = 0; t < nt; t += 2) {
;             const bool last = (t == nt - 2);
;             const char* a1 = cA + (size_t)(t + 1) * kstep;
;             const char* a2 = last ? nA : cA + (size_t)(t + 2) * kstep; const char* b2 = last ? nB : cB + (size_t)(t + 2) * kstep;
;             const char* a3 = a2 + kstep; const char* b3 = b2 + kstep;
;             if (last && has_next) S.a_ready(nxt);
;             if constexpr (SP2) {
;             PG8_LDB(B0, 0, 0); PG8_LDB(B1, 0, 1); PG8_SCHED; PG8_LDA(At, 0, 0); PG8_STAGE(PG8_SA(1, 1), a1 + hstepA, voffA);
;             PG8_WAIT_V(8); PG8_WAIT_L(0); PG8_BAR; PG8_MMA(0, 0, At, B0); PG8_MMA(0, 1, At, B1); PG8_BAR; PG8_SCHED;
;             PG8_LDA(At, 0, 1); PG8_STAGE(PG8_SB(0, 0), b2, voffB); PG8_STAGE(PG8_SB(0, 1), b2 + hstepB, voffB); PG8_STAGE(PG8_SA(0, 0), a2, voffA);
;             PG8_WAIT_V(8); PG8_WAIT_L(0); PG8_BAR; PG8_MMA(1, 0, At, B0); PG8_MMA(1, 1, At, B1); PG8_BAR; PG8_SCHED;
.LBB0_660:
	ds_read_b128 v[154:157], v150
	ds_read_b128 v[158:161], v150 offset:1024
	ds_read_b128 v[162:165], v150 offset:2048
	ds_read_b128 v[166:169], v150 offset:3072
	ds_read_b128 v[170:173], v151
	ds_read_b128 v[174:177], v151 offset:1024
	ds_read_b128 v[182:185], v151 offset:2048
	ds_read_b128 v[186:189], v151 offset:3072
	s_add_u32 s36, s0, 0xfff00080
	s_addc_u32 s37, s1, -1
	s_cmp_eq_u32 s35, 60
	s_cselect_b32 s67, s59, s37
	s_cselect_b32 s66, s58, s36
	s_cselect_b32 s65, s27, s33
	s_cselect_b32 s64, s28, s29
	v_lshl_add_u64 v[146:147], s[0:1], 0, v[138:139]
	s_add_i32 m0, s8, 0xc000
	ds_read_b128 v[190:193], v152
	ds_read_b128 v[194:197], v152 offset:1024
	ds_read_b128 v[198:201], v152 offset:2048
	ds_read_b128 v[202:205], v152 offset:3072
	ds_read_b128 v[206:209], v152 offset:4096
	ds_read_b128 v[212:215], v152 offset:5120
	ds_read_b128 v[216:219], v152 offset:6144
	ds_read_b128 v[220:223], v152 offset:7168
	global_load_lds_dwordx4 v[146:147], off
	v_lshl_add_u64 v[146:147], s[0:1], 0, v[140:141]
	s_add_i32 m0, s8, 0xe000
	s_nop 0
	global_load_lds_dwordx4 v[146:147], off
	s_waitcnt vmcnt(8)
	s_waitcnt lgkmcnt(0)
	s_barrier
	s_setprio 1
	v_mfma_f32_16x16x32_bf16 v[126:129], v[154:157], v[190:193], v[126:129]
	v_mfma_f32_16x16x32_bf16 v[126:129], v[158:161], v[194:197], v[126:129]
	v_mfma_f32_16x16x32_bf16 v[122:125], v[166:169], v[194:197], v[122:125]
	v_mfma_f32_16x16x32_bf16 v[122:125], v[162:165], v[190:193], v[122:125]
	v_mfma_f32_16x16x32_bf16 v[110:113], v[162:165], v[198:201], v[110:113]
	v_mfma_f32_16x16x32_bf16 v[110:113], v[166:169], v[202:205], v[110:113]
	v_mfma_f32_16x16x32_bf16 v[118:121], v[158:161], v[202:205], v[118:121]
	v_mfma_f32_16x16x32_bf16 v[118:121], v[154:157], v[198:201], v[118:121]
	v_mfma_f32_16x16x32_bf16 v[102:105], v[154:157], v[206:209], v[102:105]
	v_mfma_f32_16x16x32_bf16 v[102:105], v[158:161], v[212:215], v[102:105]
	v_mfma_f32_16x16x32_bf16 v[94:97], v[166:169], v[212:215], v[94:97]
	v_mfma_f32_16x16x32_bf16 v[94:97], v[162:165], v[206:209], v[94:97]
	v_mfma_f32_16x16x32_bf16 v[78:81], v[162:165], v[216:219], v[78:81]
	v_mfma_f32_16x16x32_bf16 v[78:81], v[166:169], v[220:223], v[78:81]
	v_mfma_f32_16x16x32_bf16 v[86:89], v[158:161], v[220:223], v[86:89]
	v_mfma_f32_16x16x32_bf16 v[86:89], v[154:157], v[216:219], v[86:89]
	v_mfma_f32_16x16x32_bf16 v[114:117], v[170:173], v[190:193], v[114:117]
	v_mfma_f32_16x16x32_bf16 v[114:117], v[174:177], v[194:197], v[114:117]
	v_mfma_f32_16x16x32_bf16 v[106:109], v[186:189], v[194:197], v[106:109]
	v_mfma_f32_16x16x32_bf16 v[106:109], v[182:185], v[190:193], v[106:109]
	v_mfma_f32_16x16x32_bf16 v[90:93], v[182:185], v[198:201], v[90:93]
	v_mfma_f32_16x16x32_bf16 v[90:93], v[186:189], v[202:205], v[90:93]
	v_mfma_f32_16x16x32_bf16 v[98:101], v[174:177], v[202:205], v[98:101]
	v_mfma_f32_16x16x32_bf16 v[98:101], v[170:173], v[198:201], v[98:101]
	v_mfma_f32_16x16x32_bf16 v[82:85], v[170:173], v[206:209], v[82:85]
	v_mfma_f32_16x16x32_bf16 v[82:85], v[174:177], v[212:215], v[82:85]
	v_mfma_f32_16x16x32_bf16 v[74:77], v[186:189], v[212:215], v[74:77]
	v_mfma_f32_16x16x32_bf16 v[74:77], v[182:185], v[206:209], v[74:77]
	v_mfma_f32_16x16x32_bf16 v[66:69], v[182:185], v[216:219], v[66:69]
	v_mfma_f32_16x16x32_bf16 v[66:69], v[186:189], v[220:223], v[66:69]
	v_mfma_f32_16x16x32_bf16 v[70:73], v[174:177], v[220:223], v[70:73]
	v_mfma_f32_16x16x32_bf16 v[70:73], v[170:173], v[216:219], v[70:73]
	s_setprio 0
	s_barrier
	s_add_i32 s36, s20, s7
	v_lshl_add_u64 v[146:147], s[64:65], 0, v[132:133]
	s_mov_b32 m0, s36
	ds_read_b128 v[190:193], v152 offset:16384
	ds_read_b128 v[194:197], v152 offset:17408
	ds_read_b128 v[198:201], v152 offset:18432
	ds_read_b128 v[202:205], v152 offset:19456
	ds_read_b128 v[206:209], v152 offset:20480
	ds_read_b128 v[212:215], v152 offset:21504
	ds_read_b128 v[216:219], v152 offset:22528
	ds_read_b128 v[220:223], v152 offset:23552
	global_load_lds_dwordx4 v[146:147], off
	s_add_i32 m0, s36, 0x2000
	s_add_u32 s36, s64, 0x100000
	v_lshl_add_u64 v[224:225], s[64:65], 0, v[136:137]
	s_addc_u32 s37, s65, 0
	s_add_i32 s46, s21, s7
	global_load_lds_dwordx4 v[224:225], off
	v_lshl_add_u64 v[226:227], s[36:37], 0, v[132:133]
	s_mov_b32 m0, s46
	v_lshl_add_u64 v[228:229], s[66:67], 0, v[134:135]
	global_load_lds_dwordx4 v[226:227], off
	v_lshl_add_u64 v[226:227], s[36:37], 0, v[136:137]
	s_add_i32 m0, s46, 0x2000
	s_nop 0
	global_load_lds_dwordx4 v[226:227], off
	v_lshl_add_u64 v[226:227], s[66:67], 0, v[130:131]
	s_mov_b32 m0, s8
	s_nop 0
	global_load_lds_dwordx4 v[226:227], off
	s_mov_b32 m0, s11
	s_nop 0
	global_load_lds_dwordx4 v[228:229], off
	s_waitcnt vmcnt(8)
	s_waitcnt lgkmcnt(0)
	s_barrier
; #define PG8_STAGE(bufoff, gbase, voff) do { _Pragma("unroll") for (int _i = 0; _i < 2; ++_i) \
;         __builtin_amdgcn_global_load_lds((const unsigned*)((const char*)(gbase) + (voff)[_i]), (PG8_LAS unsigned*)(lds + (bufoff) + ldsw + _i * 8192), 16, 0, 0); } while (0)
; #define PG8_LDA(dst, b, h) do { _Pragma("unroll") for (int m = 0; m < 4; ++m) _Pragma("unroll") for (int k = 0; k < 2; ++k) dst[m][k] = *(const PG8_LAS bf16x8*)(lds + PG8_SA(b, h) + aoff + m * 2048 + k * 1024); } while (0)
; #define PG8_LDB(dst, b, h) do { _Pragma("unroll") for (int n = 0; n < 2; ++n) _Pragma("unroll") for (int k = 0; k < 2; ++k) dst[n][k] = *(const PG8_LAS bf16x8*)(lds + PG8_SB(b, h) + boff + n * 2048 + k * 1024); } while (0)
; #define PG8_MMA(ai, bj, At, Bt) do { __builtin_amdgcn_s_setprio(1); _Pragma("unroll") for (int m = 0; m < 4; ++m) _Pragma("unroll") for (int n = 0; n < 2; ++n) _Pragma("unroll") for (int k = 0; k < 2; ++k) \
;         acc[ai][bj][m][n] = mma16(Bt[n][k], At[m][k], acc[ai][bj][m][n]); __builtin_amdgcn_s_setprio(0); } while (0)
; #define PG8_WAIT_V(n) asm volatile("s_waitcnt vmcnt(" #n ")" ::: "memory")
; #define PG8_WAIT_L(n) asm volatile("s_waitcnt lgkmcnt(" #n ")" ::: "memory")
; #define PG8_BAR __builtin_amdgcn_s_barrier()
; #define PG8_SCHED __builtin_amdgcn_sched_barrier(0)
; template <class Epi, class Sched, bool ALIGN_EPI = false, bool SP2 = false>
; __device__ __forceinline__ void gemm_phase(PG8_LAS unsigned char* lds, const Gemm g, const Sched& S, const Epi& E) {
;     ...
;             PG8_WAIT_V(8); PG8_WAIT_L(0); PG8_BAR; PG8_MMA(1, 0, At, B0); PG8_MMA(1, 1, At, B1); PG8_BAR; PG8_SCHED;
;             PG8_LDB(B0, 1, 0); PG8_LDB(B1, 1, 1); PG8_SCHED; PG8_LDA(At, 1, 0); PG8_STAGE(PG8_SA(0, 1), a2 + hstepA, voffA);
;             PG8_WAIT_V(8); PG8_WAIT_L(0); PG8_BAR; PG8_MMA(0, 0, At, B0); PG8_MMA(0, 1, At, B1); PG8_BAR; PG8_SCHED;
	s_setprio 1
	v_mfma_f32_16x16x32_bf16 v[62:65], v[154:157], v[190:193], v[62:65]
	v_mfma_f32_16x16x32_bf16 v[62:65], v[158:161], v[194:197], v[62:65]
	v_mfma_f32_16x16x32_bf16 v[58:61], v[166:169], v[194:197], v[58:61]
	v_mfma_f32_16x16x32_bf16 v[58:61], v[162:165], v[190:193], v[58:61]
	v_mfma_f32_16x16x32_bf16 v[46:49], v[162:165], v[198:201], v[46:49]
	v_mfma_f32_16x16x32_bf16 v[46:49], v[166:169], v[202:205], v[46:49]
	v_mfma_f32_16x16x32_bf16 v[54:57], v[158:161], v[202:205], v[54:57]
	v_mfma_f32_16x16x32_bf16 v[54:57], v[154:157], v[198:201], v[54:57]
	v_mfma_f32_16x16x32_bf16 v[38:41], v[154:157], v[206:209], v[38:41]
	v_mfma_f32_16x16x32_bf16 v[38:41], v[158:161], v[212:215], v[38:41]
	v_mfma_f32_16x16x32_bf16 v[30:33], v[166:169], v[212:215], v[30:33]
	v_mfma_f32_16x16x32_bf16 v[30:33], v[162:165], v[206:209], v[30:33]
	v_mfma_f32_16x16x32_bf16 v[14:17], v[162:165], v[216:219], v[14:17]
	v_mfma_f32_16x16x32_bf16 v[14:17], v[166:169], v[220:223], v[14:17]
	v_mfma_f32_16x16x32_bf16 v[22:25], v[158:161], v[220:223], v[22:25]
	v_mfma_f32_16x16x32_bf16 v[22:25], v[154:157], v[216:219], v[22:25]
	v_mfma_f32_16x16x32_bf16 v[50:53], v[170:173], v[190:193], v[50:53]
	v_mfma_f32_16x16x32_bf16 v[50:53], v[174:177], v[194:197], v[50:53]
	v_mfma_f32_16x16x32_bf16 v[42:45], v[186:189], v[194:197], v[42:45]
	v_mfma_f32_16x16x32_bf16 v[42:45], v[182:185], v[190:193], v[42:45]
	v_mfma_f32_16x16x32_bf16 v[26:29], v[182:185], v[198:201], v[26:29]
	v_mfma_f32_16x16x32_bf16 v[26:29], v[186:189], v[202:205], v[26:29]
	v_mfma_f32_16x16x32_bf16 v[34:37], v[174:177], v[202:205], v[34:37]
	v_mfma_f32_16x16x32_bf16 v[34:37], v[170:173], v[198:201], v[34:37]
	v_mfma_f32_16x16x32_bf16 v[18:21], v[170:173], v[206:209], v[18:21]
	v_mfma_f32_16x16x32_bf16 v[18:21], v[174:177], v[212:215], v[18:21]
	v_mfma_f32_16x16x32_bf16 v[10:13], v[186:189], v[212:215], v[10:13]
	v_mfma_f32_16x16x32_bf16 v[10:13], v[182:185], v[206:209], v[10:13]
	v_mfma_f32_16x16x32_bf16 v[2:5], v[182:185], v[216:219], v[2:5]
	v_mfma_f32_16x16x32_bf16 v[2:5], v[186:189], v[220:223], v[2:5]
	v_mfma_f32_16x16x32_bf16 v[6:9], v[174:177], v[220:223], v[6:9]
	v_mfma_f32_16x16x32_bf16 v[6:9], v[170:173], v[216:219], v[6:9]
	s_setprio 0
	s_barrier
	s_add_i32 s46, 0, 0x18000
	v_add_u32_e32 v153, s46, v148
	s_add_i32 s47, 0, 0x1c000
	ds_read_b128 v[154:157], v153
	ds_read_b128 v[158:161], v153 offset:1024
	ds_read_b128 v[162:165], v153 offset:2048
	ds_read_b128 v[166:169], v153 offset:3072
	v_add_u32_e32 v153, s47, v148
	ds_read_b128 v[170:173], v153
	ds_read_b128 v[174:177], v153 offset:1024
	ds_read_b128 v[182:185], v153 offset:2048
	ds_read_b128 v[186:189], v153 offset:3072
	s_add_u32 s36, s66, 0x100000
	s_addc_u32 s37, s67, 0
	s_mov_b32 m0, s12
	v_lshl_add_u64 v[230:231], s[36:37], 0, v[130:131]
	ds_read_b128 v[190:193], v152 offset:32768
	ds_read_b128 v[194:197], v152 offset:33792
	ds_read_b128 v[198:201], v152 offset:34816
	ds_read_b128 v[202:205], v152 offset:35840
	ds_read_b128 v[206:209], v152 offset:36864
	ds_read_b128 v[212:215], v152 offset:37888
	ds_read_b128 v[216:219], v152 offset:38912
	ds_read_b128 v[220:223], v152 offset:39936
	global_load_lds_dwordx4 v[230:231], off
	v_lshl_add_u64 v[230:231], s[36:37], 0, v[134:135]
	s_mov_b32 m0, s13
	s_nop 0
	global_load_lds_dwordx4 v[230:231], off
	s_waitcnt vmcnt(8)
	s_waitcnt lgkmcnt(0)
	s_barrier
	s_setprio 1
	v_mfma_f32_16x16x32_bf16 v[126:129], v[154:157], v[190:193], v[126:129]
	v_mfma_f32_16x16x32_bf16 v[126:129], v[158:161], v[194:197], v[126:129]
	v_mfma_f32_16x16x32_bf16 v[122:125], v[166:169], v[194:197], v[122:125]
	v_mfma_f32_16x16x32_bf16 v[122:125], v[162:165], v[190:193], v[122:125]
	v_mfma_f32_16x16x32_bf16 v[110:113], v[162:165], v[198:201], v[110:113]
	v_mfma_f32_16x16x32_bf16 v[110:113], v[166:169], v[202:205], v[110:113]
	v_mfma_f32_16x16x32_bf16 v[118:121], v[158:161], v[202:205], v[118:121]
	v_mfma_f32_16x16x32_bf16 v[118:121], v[154:157], v[198:201], v[118:121]
	v_mfma_f32_16x16x32_bf16 v[102:105], v[154:157], v[206:209], v[102:105]
	v_mfma_f32_16x16x32_bf16 v[102:105], v[158:161], v[212:215], v[102:105]
	v_mfma_f32_16x16x32_bf16 v[94:97], v[166:169], v[212:215], v[94:97]
	v_mfma_f32_16x16x32_bf16 v[94:97], v[162:165], v[206:209], v[94:97]
	v_mfma_f32_16x16x32_bf16 v[78:81], v[162:165], v[216:219], v[78:81]
	v_mfma_f32_16x16x32_bf16 v[78:81], v[166:169], v[220:223], v[78:81]
	v_mfma_f32_16x16x32_bf16 v[86:89], v[158:161], v[220:223], v[86:89]
	v_mfma_f32_16x16x32_bf16 v[86:89], v[154:157], v[216:219], v[86:89]
	v_mfma_f32_16x16x32_bf16 v[114:117], v[170:173], v[190:193], v[114:117]
	v_mfma_f32_16x16x32_bf16 v[114:117], v[174:177], v[194:197], v[114:117]
	v_mfma_f32_16x16x32_bf16 v[106:109], v[186:189], v[194:197], v[106:109]
	v_mfma_f32_16x16x32_bf16 v[106:109], v[182:185], v[190:193], v[106:109]
	v_mfma_f32_16x16x32_bf16 v[90:93], v[182:185], v[198:201], v[90:93]
	v_mfma_f32_16x16x32_bf16 v[90:93], v[186:189], v[202:205], v[90:93]
	v_mfma_f32_16x16x32_bf16 v[98:101], v[174:177], v[202:205], v[98:101]
	v_mfma_f32_16x16x32_bf16 v[98:101], v[170:173], v[198:201], v[98:101]
	v_mfma_f32_16x16x32_bf16 v[82:85], v[170:173], v[206:209], v[82:85]
	v_mfma_f32_16x16x32_bf16 v[82:85], v[174:177], v[212:215], v[82:85]
	v_mfma_f32_16x16x32_bf16 v[74:77], v[186:189], v[212:215], v[74:77]
	v_mfma_f32_16x16x32_bf16 v[74:77], v[182:185], v[206:209], v[74:77]
	v_mfma_f32_16x16x32_bf16 v[66:69], v[182:185], v[216:219], v[66:69]
	v_mfma_f32_16x16x32_bf16 v[66:69], v[186:189], v[220:223], v[66:69]
	v_mfma_f32_16x16x32_bf16 v[70:73], v[174:177], v[220:223], v[70:73]
	v_mfma_f32_16x16x32_bf16 v[70:73], v[170:173], v[216:219], v[70:73]
	s_setprio 0
	s_barrier
; #define PG8_STAGE(bufoff, gbase, voff) do { _Pragma("unroll") for (int _i = 0; _i < 2; ++_i) \
;         __builtin_amdgcn_global_load_lds((const unsigned*)((const char*)(gbase) + (voff)[_i]), (PG8_LAS unsigned*)(lds + (bufoff) + ldsw + _i * 8192), 16, 0, 0); } while (0)
; #define PG8_LDA(dst, b, h) do { _Pragma("unroll") for (int m = 0; m < 4; ++m) _Pragma("unroll") for (int k = 0; k < 2; ++k) dst[m][k] = *(const PG8_LAS bf16x8*)(lds + PG8_SA(b, h) + aoff + m * 2048 + k * 1024); } while (0)
; #define PG8_MMA(ai, bj, At, Bt) do { __builtin_amdgcn_s_setprio(1); _Pragma("unroll") for (int m = 0; m < 4; ++m) _Pragma("unroll") for (int n = 0; n < 2; ++n) _Pragma("unroll") for (int k = 0; k < 2; ++k) \
;         acc[ai][bj][m][n] = mma16(Bt[n][k], At[m][k], acc[ai][bj][m][n]); __builtin_amdgcn_s_setprio(0); } while (0)
; #define PG8_WAIT_V(n) asm volatile("s_waitcnt vmcnt(" #n ")" ::: "memory")
; #define PG8_WAIT_L(n) asm volatile("s_waitcnt lgkmcnt(" #n ")" ::: "memory")
; #define PG8_BAR __builtin_amdgcn_s_barrier()
; #define PG8_SCHED __builtin_amdgcn_sched_barrier(0)
; template <class Epi, class Sched, bool ALIGN_EPI = false, bool SP2 = false>
; __device__ __forceinline__ void gemm_phase(PG8_LAS unsigned char* lds, const Gemm g, const Sched& S, const Epi& E) {
;     ...
;             PG8_LDA(At, 1, 1); PG8_STAGE(PG8_SB(1, 0), b3, voffB); PG8_STAGE(PG8_SB(1, 1), b3 + hstepB, voffB); PG8_STAGE(PG8_SA(1, 0), a3, voffA);
;             PG8_WAIT_V(8); PG8_WAIT_L(0); PG8_BAR; PG8_MMA(1, 0, At, B0); PG8_MMA(1, 1, At, B1); PG8_BAR; PG8_SCHED;
	s_add_i32 s36, s46, s7
	v_lshl_add_u64 v[146:147], v[146:147], 0, s[40:41]
	s_mov_b32 m0, s36
	ds_read_b128 v[190:193], v152 offset:49152
	ds_read_b128 v[194:197], v152 offset:50176
	ds_read_b128 v[198:201], v152 offset:51200
	ds_read_b128 v[202:205], v152 offset:52224
	ds_read_b128 v[206:209], v152 offset:53248
	ds_read_b128 v[212:215], v152 offset:54272
	ds_read_b128 v[216:219], v152 offset:55296
	ds_read_b128 v[220:223], v152 offset:56320
	global_load_lds_dwordx4 v[146:147], off
	s_add_i32 m0, s36, 0x2000
	s_add_u32 s36, s64, 0x100080
	v_lshl_add_u64 v[146:147], v[224:225], 0, s[40:41]
	s_addc_u32 s37, s65, 0
	s_add_i32 s46, s47, s7
	global_load_lds_dwordx4 v[146:147], off
	v_lshl_add_u64 v[146:147], s[36:37], 0, v[132:133]
	s_mov_b32 m0, s46
	s_nop 0
	global_load_lds_dwordx4 v[146:147], off
	v_lshl_add_u64 v[146:147], s[36:37], 0, v[136:137]
	s_add_i32 m0, s46, 0x2000
	s_nop 0
	global_load_lds_dwordx4 v[146:147], off
	v_lshl_add_u64 v[146:147], v[226:227], 0, s[40:41]
	s_mov_b32 m0, s17
	s_nop 0
	global_load_lds_dwordx4 v[146:147], off
	v_lshl_add_u64 v[146:147], v[228:229], 0, s[40:41]
	s_mov_b32 m0, s18
	s_nop 0
	global_load_lds_dwordx4 v[146:147], off
	s_waitcnt vmcnt(8)
	s_waitcnt lgkmcnt(0)
	s_barrier
	s_setprio 1
	v_mfma_f32_16x16x32_bf16 v[62:65], v[154:157], v[190:193], v[62:65]
	v_mfma_f32_16x16x32_bf16 v[62:65], v[158:161], v[194:197], v[62:65]
	v_mfma_f32_16x16x32_bf16 v[58:61], v[166:169], v[194:197], v[58:61]
	v_mfma_f32_16x16x32_bf16 v[58:61], v[162:165], v[190:193], v[58:61]
	v_mfma_f32_16x16x32_bf16 v[46:49], v[162:165], v[198:201], v[46:49]
	v_mfma_f32_16x16x32_bf16 v[46:49], v[166:169], v[202:205], v[46:49]
	v_mfma_f32_16x16x32_bf16 v[54:57], v[158:161], v[202:205], v[54:57]
	v_mfma_f32_16x16x32_bf16 v[54:57], v[154:157], v[198:201], v[54:57]
	v_mfma_f32_16x16x32_bf16 v[38:41], v[154:157], v[206:209], v[38:41]
	v_mfma_f32_16x16x32_bf16 v[38:41], v[158:161], v[212:215], v[38:41]
	v_mfma_f32_16x16x32_bf16 v[30:33], v[166:169], v[212:215], v[30:33]
	v_mfma_f32_16x16x32_bf16 v[30:33], v[162:165], v[206:209], v[30:33]
	v_mfma_f32_16x16x32_bf16 v[14:17], v[162:165], v[216:219], v[14:17]
	v_mfma_f32_16x16x32_bf16 v[14:17], v[166:169], v[220:223], v[14:17]
	v_mfma_f32_16x16x32_bf16 v[22:25], v[158:161], v[220:223], v[22:25]
	v_mfma_f32_16x16x32_bf16 v[22:25], v[154:157], v[216:219], v[22:25]
	v_mfma_f32_16x16x32_bf16 v[50:53], v[170:173], v[190:193], v[50:53]
	v_mfma_f32_16x16x32_bf16 v[50:53], v[174:177], v[194:197], v[50:53]
	v_mfma_f32_16x16x32_bf16 v[42:45], v[186:189], v[194:197], v[42:45]
	v_mfma_f32_16x16x32_bf16 v[42:45], v[182:185], v[190:193], v[42:45]
	v_mfma_f32_16x16x32_bf16 v[26:29], v[182:185], v[198:201], v[26:29]
	v_mfma_f32_16x16x32_bf16 v[26:29], v[186:189], v[202:205], v[26:29]
	v_mfma_f32_16x16x32_bf16 v[34:37], v[174:177], v[202:205], v[34:37]
	v_mfma_f32_16x16x32_bf16 v[34:37], v[170:173], v[198:201], v[34:37]
	v_mfma_f32_16x16x32_bf16 v[18:21], v[170:173], v[206:209], v[18:21]
	v_mfma_f32_16x16x32_bf16 v[18:21], v[174:177], v[212:215], v[18:21]
	v_mfma_f32_16x16x32_bf16 v[10:13], v[186:189], v[212:215], v[10:13]
	v_mfma_f32_16x16x32_bf16 v[10:13], v[182:185], v[206:209], v[10:13]
	v_mfma_f32_16x16x32_bf16 v[2:5], v[182:185], v[216:219], v[2:5]
	v_mfma_f32_16x16x32_bf16 v[2:5], v[186:189], v[220:223], v[2:5]
	v_mfma_f32_16x16x32_bf16 v[6:9], v[174:177], v[220:223], v[6:9]
	v_mfma_f32_16x16x32_bf16 v[6:9], v[170:173], v[216:219], v[6:9]
	s_setprio 0
	s_barrier
	s_add_i32 s35, s35, 2
	s_add_u32 s0, s0, 0x100
	s_addc_u32 s1, s1, 0
	s_add_u32 s29, s29, 0x100
	s_addc_u32 s33, s33, 0
	s_cmp_gt_u32 s35, 61
	s_cbranch_scc0 .LBB0_660
	s_and_b64 vcc, exec, s[42:43]
	s_cbranch_vccz .LBB0_663
	s_barrier

; #define PG8_STAGE(bufoff, gbase, voff) do { _Pragma("unroll") for (int _i = 0; _i < 2; ++_i) \
;         __builtin_amdgcn_global_load_lds((const unsigned*)((const char*)(gbase) + (voff)[_i]), (PG8_LAS unsigned*)(lds + (bufoff) + ldsw + _i * 8192), 16, 0, 0); } while (0)
; #define PG8_LDA(dst, b, h) do { _Pragma("unroll") for (int m = 0; m < 4; ++m) _Pragma("unroll") for (int k = 0; k < 2; ++k) dst[m][k] = *(const PG8_LAS bf16x8*)(lds + PG8_SA(b, h) + aoff + m * 2048 + k * 1024); } while (0)
; #define PG8_LDB(dst, b, h) do { _Pragma("unroll") for (int n = 0; n < 2; ++n) _Pragma("unroll") for (int k = 0; k < 2; ++k) dst[n][k] = *(const PG8_LAS bf16x8*)(lds + PG8_SB(b, h) + boff + n * 2048 + k * 1024); } while (0)
; #define PG8_MMA(ai, bj, At, Bt) do { __builtin_amdgcn_s_setprio(1); _Pragma("unroll") for (int m = 0; m < 4; ++m) _Pragma("unroll") for (int n = 0; n < 2; ++n) _Pragma("unroll") for (int k = 0; k < 2; ++k) \
;         acc[ai][bj][m][n] = mma16(Bt[n][k], At[m][k], acc[ai][bj][m][n]); __builtin_amdgcn_s_setprio(0); } while (0)
; #define PG8_WAIT_V(n) asm volatile("s_waitcnt vmcnt(" #n ")" ::: "memory")
; #define PG8_WAIT_L(n) asm volatile("s_waitcnt lgkmcnt(" #n ")" ::: "memory")
; template <class Epi, class Sched, bool ALIGN_EPI = false, bool SP2 = false>
; __device__ __forceinline__ void gemm_phase(PG8_LAS unsigned char* lds, const Gemm g, const Sched& S, const Epi& E) {
;     ...
;         for (int t = 0; t < nt; t += 2) {
;             const bool last = (t == nt - 2);
;             const char* a1 = cA + (size_t)(t + 1) * kstep;
;             const char* a2 = last ? nA : cA + (size_t)(t + 2) * kstep; const char* b2 = last ? nB : cB + (size_t)(t + 2) * kstep;
;             const char* a3 = a2 + kstep; const char* b3 = b2 + kstep;
;             if (last && has_next) S.a_ready(nxt);
;             if constexpr (SP2) {
;             PG8_LDB(B0, 0, 0); PG8_LDB(B1, 0, 1); PG8_SCHED; PG8_LDA(At, 0, 0); PG8_STAGE(PG8_SA(1, 1), a1 + hstepA, voffA);
;             PG8_WAIT_V(8); PG8_WAIT_L(0); PG8_BAR; PG8_MMA(0, 0, At, B0); PG8_MMA(0, 1, At, B1); PG8_BAR; PG8_SCHED;
;             PG8_LDA(At, 0, 1); PG8_STAGE(PG8_SB(0, 0), b2, voffB); PG8_STAGE(PG8_SB(0, 1), b2 + hstepB, voffB); PG8_STAGE(PG8_SA(0, 0), a2, voffA);
;             PG8_WAIT_V(8); PG8_WAIT_L(0); PG8_BAR; PG8_MMA(1, 0, At, B0); PG8_MMA(1, 1, At, B1); PG8_BAR; PG8_SCHED;
.LBB0_841:
	ds_read_b128 v[90:93], v173
	ds_read_b128 v[94:97], v173 offset:1024
	ds_read_b128 v[98:101], v173 offset:2048
	ds_read_b128 v[106:109], v173 offset:3072
	ds_read_b128 v[182:185], v174
	ds_read_b128 v[186:189], v174 offset:1024
	ds_read_b128 v[190:193], v174 offset:2048
	ds_read_b128 v[194:197], v174 offset:3072
	s_add_u32 s58, s56, 0xfff80080
	s_addc_u32 s59, s57, -1
	s_cmp_eq_u32 s68, 28
	s_cselect_b32 s61, s62, s59
	s_cselect_b32 s60, s63, s58
	s_cselect_b32 s59, s64, s67
	s_cselect_b32 s58, s65, s66
	v_lshl_add_u64 v[166:167], s[56:57], 0, v[158:159]
	s_add_i32 m0, s12, 0xc000
	ds_read_b128 v[198:201], v175
	ds_read_b128 v[202:205], v175 offset:1024
	ds_read_b128 v[206:209], v175 offset:2048
	ds_read_b128 v[212:215], v175 offset:3072
	ds_read_b128 v[216:219], v175 offset:4096
	ds_read_b128 v[220:223], v175 offset:5120
	ds_read_b128 v[224:227], v175 offset:6144
	ds_read_b128 v[228:231], v175 offset:7168
	global_load_lds_dwordx4 v[166:167], off
	v_lshl_add_u64 v[166:167], s[56:57], 0, v[160:161]
	s_add_i32 m0, s12, 0xe000
	s_nop 0
	global_load_lds_dwordx4 v[166:167], off
	s_waitcnt vmcnt(8)
	s_waitcnt lgkmcnt(0)
	s_barrier
	s_setprio 1
	v_mfma_i32_16x16x64_i8 v[142:145], v[90:93], v[198:201], v[142:145]
	v_mfma_i32_16x16x64_i8 v[142:145], v[94:97], v[202:205], v[142:145]
	v_mfma_i32_16x16x64_i8 v[138:141], v[106:109], v[202:205], v[138:141]
	v_mfma_i32_16x16x64_i8 v[138:141], v[98:101], v[198:201], v[138:141]
	v_mfma_i32_16x16x64_i8 v[122:125], v[98:101], v[206:209], v[122:125]
	v_mfma_i32_16x16x64_i8 v[122:125], v[106:109], v[212:215], v[122:125]
	v_mfma_i32_16x16x64_i8 v[126:129], v[94:97], v[212:215], v[126:129]
	v_mfma_i32_16x16x64_i8 v[126:129], v[90:93], v[206:209], v[126:129]
	v_mfma_i32_16x16x64_i8 v[110:113], v[90:93], v[216:219], v[110:113]
	v_mfma_i32_16x16x64_i8 v[110:113], v[94:97], v[220:223], v[110:113]
	v_mfma_i32_16x16x64_i8 v[102:105], v[106:109], v[220:223], v[102:105]
	v_mfma_i32_16x16x64_i8 v[102:105], v[98:101], v[216:219], v[102:105]
	v_mfma_i32_16x16x64_i8 v[74:77], v[98:101], v[224:227], v[74:77]
	v_mfma_i32_16x16x64_i8 v[74:77], v[106:109], v[228:231], v[74:77]
	v_mfma_i32_16x16x64_i8 v[78:81], v[94:97], v[228:231], v[78:81]
	v_mfma_i32_16x16x64_i8 v[78:81], v[90:93], v[224:227], v[78:81]
	v_mfma_i32_16x16x64_i8 v[134:137], v[182:185], v[198:201], v[134:137]
	v_mfma_i32_16x16x64_i8 v[134:137], v[186:189], v[202:205], v[134:137]
	v_mfma_i32_16x16x64_i8 v[130:133], v[194:197], v[202:205], v[130:133]
	v_mfma_i32_16x16x64_i8 v[130:133], v[190:193], v[198:201], v[130:133]
	v_mfma_i32_16x16x64_i8 v[114:117], v[190:193], v[206:209], v[114:117]
	v_mfma_i32_16x16x64_i8 v[114:117], v[194:197], v[212:215], v[114:117]
	v_mfma_i32_16x16x64_i8 v[118:121], v[186:189], v[212:215], v[118:121]
	v_mfma_i32_16x16x64_i8 v[118:121], v[182:185], v[206:209], v[118:121]
	v_mfma_i32_16x16x64_i8 v[86:89], v[182:185], v[216:219], v[86:89]
	v_mfma_i32_16x16x64_i8 v[86:89], v[186:189], v[220:223], v[86:89]
	v_mfma_i32_16x16x64_i8 v[82:85], v[194:197], v[220:223], v[82:85]
	v_mfma_i32_16x16x64_i8 v[82:85], v[190:193], v[216:219], v[82:85]
	v_mfma_i32_16x16x64_i8 v[66:69], v[190:193], v[224:227], v[66:69]
	v_mfma_i32_16x16x64_i8 v[66:69], v[194:197], v[228:231], v[66:69]
	v_mfma_i32_16x16x64_i8 v[70:73], v[186:189], v[228:231], v[70:73]
	v_mfma_i32_16x16x64_i8 v[70:73], v[182:185], v[224:227], v[70:73]
	s_setprio 0
	s_barrier
	s_add_i32 s69, s27, s6
	v_lshl_add_u64 v[166:167], s[58:59], 0, v[150:151]
	s_mov_b32 m0, s69
	ds_read_b128 v[198:201], v175 offset:16384
	ds_read_b128 v[202:205], v175 offset:17408
	ds_read_b128 v[206:209], v175 offset:18432
	ds_read_b128 v[212:215], v175 offset:19456
	ds_read_b128 v[216:219], v175 offset:20480
	ds_read_b128 v[220:223], v175 offset:21504
	ds_read_b128 v[224:227], v175 offset:22528
	ds_read_b128 v[228:231], v175 offset:23552
	global_load_lds_dwordx4 v[166:167], off
	s_add_i32 m0, s69, 0x2000
	s_add_u32 s70, s58, 0x80000
	v_lshl_add_u64 v[176:177], s[58:59], 0, v[146:147]
	s_addc_u32 s71, s59, 0
	s_add_i32 s69, s28, s6
	global_load_lds_dwordx4 v[176:177], off
	v_lshl_add_u64 v[232:233], s[70:71], 0, v[150:151]
	s_mov_b32 m0, s69
	v_lshl_add_u64 v[234:235], s[60:61], 0, v[148:149]
	global_load_lds_dwordx4 v[232:233], off
	v_lshl_add_u64 v[232:233], s[70:71], 0, v[146:147]
	s_add_i32 m0, s69, 0x2000
	s_nop 0
	global_load_lds_dwordx4 v[232:233], off
	v_lshl_add_u64 v[232:233], s[60:61], 0, v[152:153]
	s_mov_b32 m0, s12
	s_nop 0
	global_load_lds_dwordx4 v[232:233], off
	s_mov_b32 m0, s13
	s_nop 0
	global_load_lds_dwordx4 v[234:235], off
	s_waitcnt vmcnt(8)
	s_waitcnt lgkmcnt(0)
	s_barrier
; #define PG8_STAGE(bufoff, gbase, voff) do { _Pragma("unroll") for (int _i = 0; _i < 2; ++_i) \
;         __builtin_amdgcn_global_load_lds((const unsigned*)((const char*)(gbase) + (voff)[_i]), (PG8_LAS unsigned*)(lds + (bufoff) + ldsw + _i * 8192), 16, 0, 0); } while (0)
; #define PG8_LDA(dst, b, h) do { _Pragma("unroll") for (int m = 0; m < 4; ++m) _Pragma("unroll") for (int k = 0; k < 2; ++k) dst[m][k] = *(const PG8_LAS bf16x8*)(lds + PG8_SA(b, h) + aoff + m * 2048 + k * 1024); } while (0)
; #define PG8_LDB(dst, b, h) do { _Pragma("unroll") for (int n = 0; n < 2; ++n) _Pragma("unroll") for (int k = 0; k < 2; ++k) dst[n][k] = *(const PG8_LAS bf16x8*)(lds + PG8_SB(b, h) + boff + n * 2048 + k * 1024); } while (0)
; #define PG8_MMA(ai, bj, At, Bt) do { __builtin_amdgcn_s_setprio(1); _Pragma("unroll") for (int m = 0; m < 4; ++m) _Pragma("unroll") for (int n = 0; n < 2; ++n) _Pragma("unroll") for (int k = 0; k < 2; ++k) \
;         acc[ai][bj][m][n] = mma16(Bt[n][k], At[m][k], acc[ai][bj][m][n]); __builtin_amdgcn_s_setprio(0); } while (0)
; #define PG8_WAIT_V(n) asm volatile("s_waitcnt vmcnt(" #n ")" ::: "memory")
; #define PG8_WAIT_L(n) asm volatile("s_waitcnt lgkmcnt(" #n ")" ::: "memory")
; #define PG8_BAR __builtin_amdgcn_s_barrier()
; #define PG8_SCHED __builtin_amdgcn_sched_barrier(0)
; template <class Epi, class Sched, bool ALIGN_EPI = false, bool SP2 = false>
; __device__ __forceinline__ void gemm_phase(PG8_LAS unsigned char* lds, const Gemm g, const Sched& S, const Epi& E) {
;     ...
;             PG8_WAIT_V(8); PG8_WAIT_L(0); PG8_BAR; PG8_MMA(1, 0, At, B0); PG8_MMA(1, 1, At, B1); PG8_BAR; PG8_SCHED;
;             PG8_LDB(B0, 1, 0); PG8_LDB(B1, 1, 1); PG8_SCHED; PG8_LDA(At, 1, 0); PG8_STAGE(PG8_SA(0, 1), a2 + hstepA, voffA);
;             PG8_WAIT_V(8); PG8_WAIT_L(0); PG8_BAR; PG8_MMA(0, 0, At, B0); PG8_MMA(0, 1, At, B1); PG8_BAR; PG8_SCHED;
	s_setprio 1
	v_mfma_i32_16x16x64_i8 v[62:65], v[90:93], v[198:201], v[62:65]
	v_mfma_i32_16x16x64_i8 v[62:65], v[94:97], v[202:205], v[62:65]
	v_mfma_i32_16x16x64_i8 v[58:61], v[106:109], v[202:205], v[58:61]
	v_mfma_i32_16x16x64_i8 v[58:61], v[98:101], v[198:201], v[58:61]
	v_mfma_i32_16x16x64_i8 v[42:45], v[98:101], v[206:209], v[42:45]
	v_mfma_i32_16x16x64_i8 v[42:45], v[106:109], v[212:215], v[42:45]
	v_mfma_i32_16x16x64_i8 v[46:49], v[94:97], v[212:215], v[46:49]
	v_mfma_i32_16x16x64_i8 v[46:49], v[90:93], v[206:209], v[46:49]
	v_mfma_i32_16x16x64_i8 v[30:33], v[90:93], v[216:219], v[30:33]
	v_mfma_i32_16x16x64_i8 v[30:33], v[94:97], v[220:223], v[30:33]
	v_mfma_i32_16x16x64_i8 v[26:29], v[106:109], v[220:223], v[26:29]
	v_mfma_i32_16x16x64_i8 v[26:29], v[98:101], v[216:219], v[26:29]
	v_mfma_i32_16x16x64_i8 v[10:13], v[98:101], v[224:227], v[10:13]
	v_mfma_i32_16x16x64_i8 v[10:13], v[106:109], v[228:231], v[10:13]
	v_mfma_i32_16x16x64_i8 v[14:17], v[94:97], v[228:231], v[14:17]
	v_mfma_i32_16x16x64_i8 v[14:17], v[90:93], v[224:227], v[14:17]
	v_mfma_i32_16x16x64_i8 v[54:57], v[182:185], v[198:201], v[54:57]
	v_mfma_i32_16x16x64_i8 v[54:57], v[186:189], v[202:205], v[54:57]
	v_mfma_i32_16x16x64_i8 v[50:53], v[194:197], v[202:205], v[50:53]
	v_mfma_i32_16x16x64_i8 v[50:53], v[190:193], v[198:201], v[50:53]
	v_mfma_i32_16x16x64_i8 v[34:37], v[190:193], v[206:209], v[34:37]
	v_mfma_i32_16x16x64_i8 v[34:37], v[194:197], v[212:215], v[34:37]
	v_mfma_i32_16x16x64_i8 v[38:41], v[186:189], v[212:215], v[38:41]
	v_mfma_i32_16x16x64_i8 v[38:41], v[182:185], v[206:209], v[38:41]
	v_mfma_i32_16x16x64_i8 v[22:25], v[182:185], v[216:219], v[22:25]
	v_mfma_i32_16x16x64_i8 v[22:25], v[186:189], v[220:223], v[22:25]
	v_mfma_i32_16x16x64_i8 v[18:21], v[194:197], v[220:223], v[18:21]
	v_mfma_i32_16x16x64_i8 v[18:21], v[190:193], v[216:219], v[18:21]
	v_mfma_i32_16x16x64_i8 v[2:5], v[190:193], v[224:227], v[2:5]
	v_mfma_i32_16x16x64_i8 v[2:5], v[194:197], v[228:231], v[2:5]
	v_mfma_i32_16x16x64_i8 v[6:9], v[186:189], v[228:231], v[6:9]
	v_mfma_i32_16x16x64_i8 v[6:9], v[182:185], v[224:227], v[6:9]
	s_setprio 0
	s_barrier
	s_add_i32 s69, 0, 0x18000
	s_add_i32 s70, 0, 0x1c000
	v_add_u32_e32 v106, s69, v171
	v_add_u32_e32 v181, s70, v171
	ds_read_b128 v[90:93], v106
	ds_read_b128 v[94:97], v106 offset:1024
	ds_read_b128 v[98:101], v106 offset:2048
	ds_read_b128 v[106:109], v106 offset:3072
	ds_read_b128 v[182:185], v181
	ds_read_b128 v[186:189], v181 offset:1024
	ds_read_b128 v[190:193], v181 offset:2048
	ds_read_b128 v[194:197], v181 offset:3072
	s_add_u32 s60, s60, 0x80000
	s_addc_u32 s61, s61, 0
	s_mov_b32 m0, s16
	v_lshl_add_u64 v[236:237], s[60:61], 0, v[152:153]
	ds_read_b128 v[198:201], v175 offset:32768
	ds_read_b128 v[202:205], v175 offset:33792
	ds_read_b128 v[206:209], v175 offset:34816
	ds_read_b128 v[212:215], v175 offset:35840
	ds_read_b128 v[216:219], v175 offset:36864
	ds_read_b128 v[220:223], v175 offset:37888
	ds_read_b128 v[224:227], v175 offset:38912
	ds_read_b128 v[228:231], v175 offset:39936
	global_load_lds_dwordx4 v[236:237], off
	v_lshl_add_u64 v[236:237], s[60:61], 0, v[148:149]
	s_mov_b32 m0, s17
	s_nop 0
	global_load_lds_dwordx4 v[236:237], off
	s_waitcnt vmcnt(8)
	s_waitcnt lgkmcnt(0)
	s_barrier
	s_setprio 1
	v_mfma_i32_16x16x64_i8 v[142:145], v[90:93], v[198:201], v[142:145]
	v_mfma_i32_16x16x64_i8 v[142:145], v[94:97], v[202:205], v[142:145]
	v_mfma_i32_16x16x64_i8 v[138:141], v[106:109], v[202:205], v[138:141]
	v_mfma_i32_16x16x64_i8 v[138:141], v[98:101], v[198:201], v[138:141]
	v_mfma_i32_16x16x64_i8 v[122:125], v[98:101], v[206:209], v[122:125]
	v_mfma_i32_16x16x64_i8 v[122:125], v[106:109], v[212:215], v[122:125]
	v_mfma_i32_16x16x64_i8 v[126:129], v[94:97], v[212:215], v[126:129]
	v_mfma_i32_16x16x64_i8 v[126:129], v[90:93], v[206:209], v[126:129]
	v_mfma_i32_16x16x64_i8 v[110:113], v[90:93], v[216:219], v[110:113]
	v_mfma_i32_16x16x64_i8 v[110:113], v[94:97], v[220:223], v[110:113]
	v_mfma_i32_16x16x64_i8 v[102:105], v[106:109], v[220:223], v[102:105]
	v_mfma_i32_16x16x64_i8 v[102:105], v[98:101], v[216:219], v[102:105]
	v_mfma_i32_16x16x64_i8 v[74:77], v[98:101], v[224:227], v[74:77]
	v_mfma_i32_16x16x64_i8 v[74:77], v[106:109], v[228:231], v[74:77]
	v_mfma_i32_16x16x64_i8 v[78:81], v[94:97], v[228:231], v[78:81]
	v_mfma_i32_16x16x64_i8 v[78:81], v[90:93], v[224:227], v[78:81]
	v_mfma_i32_16x16x64_i8 v[134:137], v[182:185], v[198:201], v[134:137]
	v_mfma_i32_16x16x64_i8 v[134:137], v[186:189], v[202:205], v[134:137]
	v_mfma_i32_16x16x64_i8 v[130:133], v[194:197], v[202:205], v[130:133]
	v_mfma_i32_16x16x64_i8 v[130:133], v[190:193], v[198:201], v[130:133]
	v_mfma_i32_16x16x64_i8 v[114:117], v[190:193], v[206:209], v[114:117]
	v_mfma_i32_16x16x64_i8 v[114:117], v[194:197], v[212:215], v[114:117]
	v_mfma_i32_16x16x64_i8 v[118:121], v[186:189], v[212:215], v[118:121]
	v_mfma_i32_16x16x64_i8 v[118:121], v[182:185], v[206:209], v[118:121]
	v_mfma_i32_16x16x64_i8 v[86:89], v[182:185], v[216:219], v[86:89]
	v_mfma_i32_16x16x64_i8 v[86:89], v[186:189], v[220:223], v[86:89]
	v_mfma_i32_16x16x64_i8 v[82:85], v[194:197], v[220:223], v[82:85]
	v_mfma_i32_16x16x64_i8 v[82:85], v[190:193], v[216:219], v[82:85]
	v_mfma_i32_16x16x64_i8 v[66:69], v[190:193], v[224:227], v[66:69]
	v_mfma_i32_16x16x64_i8 v[66:69], v[194:197], v[228:231], v[66:69]
	v_mfma_i32_16x16x64_i8 v[70:73], v[186:189], v[228:231], v[70:73]
	v_mfma_i32_16x16x64_i8 v[70:73], v[182:185], v[224:227], v[70:73]
	s_setprio 0
	s_barrier
; #define PG8_STAGE(bufoff, gbase, voff) do { _Pragma("unroll") for (int _i = 0; _i < 2; ++_i) \
;         __builtin_amdgcn_global_load_lds((const unsigned*)((const char*)(gbase) + (voff)[_i]), (PG8_LAS unsigned*)(lds + (bufoff) + ldsw + _i * 8192), 16, 0, 0); } while (0)
; #define PG8_LDA(dst, b, h) do { _Pragma("unroll") for (int m = 0; m < 4; ++m) _Pragma("unroll") for (int k = 0; k < 2; ++k) dst[m][k] = *(const PG8_LAS bf16x8*)(lds + PG8_SA(b, h) + aoff + m * 2048 + k * 1024); } while (0)
; #define PG8_MMA(ai, bj, At, Bt) do { __builtin_amdgcn_s_setprio(1); _Pragma("unroll") for (int m = 0; m < 4; ++m) _Pragma("unroll") for (int n = 0; n < 2; ++n) _Pragma("unroll") for (int k = 0; k < 2; ++k) \
;         acc[ai][bj][m][n] = mma16(Bt[n][k], At[m][k], acc[ai][bj][m][n]); __builtin_amdgcn_s_setprio(0); } while (0)
; #define PG8_WAIT_V(n) asm volatile("s_waitcnt vmcnt(" #n ")" ::: "memory")
; #define PG8_WAIT_L(n) asm volatile("s_waitcnt lgkmcnt(" #n ")" ::: "memory")
; #define PG8_BAR __builtin_amdgcn_s_barrier()
; #define PG8_SCHED __builtin_amdgcn_sched_barrier(0)
; template <class Epi, class Sched, bool ALIGN_EPI = false, bool SP2 = false>
; __device__ __forceinline__ void gemm_phase(PG8_LAS unsigned char* lds, const Gemm g, const Sched& S, const Epi& E) {
;     ...
;             PG8_LDA(At, 1, 1); PG8_STAGE(PG8_SB(1, 0), b3, voffB); PG8_STAGE(PG8_SB(1, 1), b3 + hstepB, voffB); PG8_STAGE(PG8_SA(1, 0), a3, voffA);
;             PG8_WAIT_V(8); PG8_WAIT_L(0); PG8_BAR; PG8_MMA(1, 0, At, B0); PG8_MMA(1, 1, At, B1); PG8_BAR; PG8_SCHED;
	s_add_i32 s60, s69, s6
	v_lshl_add_u64 v[166:167], v[166:167], 0, s[36:37]
	s_mov_b32 m0, s60
	ds_read_b128 v[198:201], v175 offset:49152
	ds_read_b128 v[202:205], v175 offset:50176
	ds_read_b128 v[206:209], v175 offset:51200
	ds_read_b128 v[212:215], v175 offset:52224
	ds_read_b128 v[216:219], v175 offset:53248
	ds_read_b128 v[220:223], v175 offset:54272
	ds_read_b128 v[224:227], v175 offset:55296
	ds_read_b128 v[228:231], v175 offset:56320
	global_load_lds_dwordx4 v[166:167], off
	s_add_i32 m0, s60, 0x2000
	s_add_u32 s58, s58, 0x80080
	v_lshl_add_u64 v[166:167], v[176:177], 0, s[36:37]
	s_addc_u32 s59, s59, 0
	s_add_i32 s60, s70, s6
	global_load_lds_dwordx4 v[166:167], off
	v_lshl_add_u64 v[166:167], s[58:59], 0, v[150:151]
	s_mov_b32 m0, s60
	s_nop 0
	global_load_lds_dwordx4 v[166:167], off
	v_lshl_add_u64 v[166:167], s[58:59], 0, v[146:147]
	s_add_i32 m0, s60, 0x2000
	s_nop 0
	global_load_lds_dwordx4 v[166:167], off
	v_lshl_add_u64 v[166:167], v[232:233], 0, s[36:37]
	s_mov_b32 m0, s24
	s_nop 0
	global_load_lds_dwordx4 v[166:167], off
	v_lshl_add_u64 v[166:167], v[234:235], 0, s[36:37]
	s_mov_b32 m0, s25
	s_nop 0
	global_load_lds_dwordx4 v[166:167], off
	s_waitcnt vmcnt(8)
	s_waitcnt lgkmcnt(0)
	s_barrier
	s_setprio 1
	v_mfma_i32_16x16x64_i8 v[62:65], v[90:93], v[198:201], v[62:65]
	v_mfma_i32_16x16x64_i8 v[62:65], v[94:97], v[202:205], v[62:65]
	v_mfma_i32_16x16x64_i8 v[58:61], v[106:109], v[202:205], v[58:61]
	v_mfma_i32_16x16x64_i8 v[58:61], v[98:101], v[198:201], v[58:61]
	v_mfma_i32_16x16x64_i8 v[42:45], v[98:101], v[206:209], v[42:45]
	v_mfma_i32_16x16x64_i8 v[42:45], v[106:109], v[212:215], v[42:45]
	v_mfma_i32_16x16x64_i8 v[46:49], v[94:97], v[212:215], v[46:49]
	v_mfma_i32_16x16x64_i8 v[46:49], v[90:93], v[206:209], v[46:49]
	v_mfma_i32_16x16x64_i8 v[30:33], v[90:93], v[216:219], v[30:33]
	v_mfma_i32_16x16x64_i8 v[30:33], v[94:97], v[220:223], v[30:33]
	v_mfma_i32_16x16x64_i8 v[26:29], v[106:109], v[220:223], v[26:29]
	v_mfma_i32_16x16x64_i8 v[26:29], v[98:101], v[216:219], v[26:29]
	v_mfma_i32_16x16x64_i8 v[10:13], v[98:101], v[224:227], v[10:13]
	v_mfma_i32_16x16x64_i8 v[10:13], v[106:109], v[228:231], v[10:13]
	v_mfma_i32_16x16x64_i8 v[14:17], v[94:97], v[228:231], v[14:17]
	v_mfma_i32_16x16x64_i8 v[14:17], v[90:93], v[224:227], v[14:17]
	v_mfma_i32_16x16x64_i8 v[54:57], v[182:185], v[198:201], v[54:57]
	v_mfma_i32_16x16x64_i8 v[54:57], v[186:189], v[202:205], v[54:57]
	v_mfma_i32_16x16x64_i8 v[50:53], v[194:197], v[202:205], v[50:53]
	v_mfma_i32_16x16x64_i8 v[50:53], v[190:193], v[198:201], v[50:53]
	v_mfma_i32_16x16x64_i8 v[34:37], v[190:193], v[206:209], v[34:37]
	v_mfma_i32_16x16x64_i8 v[34:37], v[194:197], v[212:215], v[34:37]
	v_mfma_i32_16x16x64_i8 v[38:41], v[186:189], v[212:215], v[38:41]
	v_mfma_i32_16x16x64_i8 v[38:41], v[182:185], v[206:209], v[38:41]
	v_mfma_i32_16x16x64_i8 v[22:25], v[182:185], v[216:219], v[22:25]
	v_mfma_i32_16x16x64_i8 v[22:25], v[186:189], v[220:223], v[22:25]
	v_mfma_i32_16x16x64_i8 v[18:21], v[194:197], v[220:223], v[18:21]
	v_mfma_i32_16x16x64_i8 v[18:21], v[190:193], v[216:219], v[18:21]
	v_mfma_i32_16x16x64_i8 v[2:5], v[190:193], v[224:227], v[2:5]
	v_mfma_i32_16x16x64_i8 v[2:5], v[194:197], v[228:231], v[2:5]
	v_mfma_i32_16x16x64_i8 v[6:9], v[186:189], v[228:231], v[6:9]
	v_mfma_i32_16x16x64_i8 v[6:9], v[182:185], v[224:227], v[6:9]
	s_setprio 0
	s_barrier
	s_add_i32 s68, s68, 2
	s_add_u32 s56, s56, 0x100
	s_addc_u32 s57, s57, 0
	s_add_u32 s66, s66, 0x100
	s_addc_u32 s67, s67, 0
	s_cmp_gt_u32 s68, 29
	s_cbranch_scc0 .LBB0_841
	s_and_b64 vcc, exec, s[44:45]
	s_cbranch_vccz .LBB0_844
	s_barrier

; #define PG8_STAGE(bufoff, gbase, voff) do { _Pragma("unroll") for (int _i = 0; _i < 2; ++_i) \
;         __builtin_amdgcn_global_load_lds((const unsigned*)((const char*)(gbase) + (voff)[_i]), (PG8_LAS unsigned*)(lds + (bufoff) + ldsw + _i * 8192), 16, 0, 0); } while (0)
; #define PG8_LDA(dst, b, h) do { _Pragma("unroll") for (int m = 0; m < 4; ++m) _Pragma("unroll") for (int k = 0; k < 2; ++k) dst[m][k] = *(const PG8_LAS bf16x8*)(lds + PG8_SA(b, h) + aoff + m * 2048 + k * 1024); } while (0)
; #define PG8_LDB(dst, b, h) do { _Pragma("unroll") for (int n = 0; n < 2; ++n) _Pragma("unroll") for (int k = 0; k < 2; ++k) dst[n][k] = *(const PG8_LAS bf16x8*)(lds + PG8_SB(b, h) + boff + n * 2048 + k * 1024); } while (0)
; #define PG8_MMA(ai, bj, At, Bt) do { __builtin_amdgcn_s_setprio(1); _Pragma("unroll") for (int m = 0; m < 4; ++m) _Pragma("unroll") for (int n = 0; n < 2; ++n) _Pragma("unroll") for (int k = 0; k < 2; ++k) \
;         acc[ai][bj][m][n] = mma16(Bt[n][k], At[m][k], acc[ai][bj][m][n]); __builtin_amdgcn_s_setprio(0); } while (0)
; #define PG8_WAIT_V(n) asm volatile("s_waitcnt vmcnt(" #n ")" ::: "memory")
; #define PG8_WAIT_L(n) asm volatile("s_waitcnt lgkmcnt(" #n ")" ::: "memory")
; template <class Epi, class Sched, bool ALIGN_EPI = false, bool SP2 = false>
; __device__ __forceinline__ void gemm_phase(PG8_LAS unsigned char* lds, const Gemm g, const Sched& S, const Epi& E) {
;     ...
;         for (int t = 0; t < nt; t += 2) {
;             const bool last = (t == nt - 2);
;             const char* a1 = cA + (size_t)(t + 1) * kstep;
;             const char* a2 = last ? nA : cA + (size_t)(t + 2) * kstep; const char* b2 = last ? nB : cB + (size_t)(t + 2) * kstep;
;             const char* a3 = a2 + kstep; const char* b3 = b2 + kstep;
;             if (last && has_next) S.a_ready(nxt);
;             if constexpr (SP2) {
;             PG8_LDB(B0, 0, 0); PG8_LDB(B1, 0, 1); PG8_SCHED; PG8_LDA(At, 0, 0); PG8_STAGE(PG8_SA(1, 1), a1 + hstepA, voffA);
;             PG8_WAIT_V(8); PG8_WAIT_L(0); PG8_BAR; PG8_MMA(0, 0, At, B0); PG8_MMA(0, 1, At, B1); PG8_BAR; PG8_SCHED;
;             PG8_LDA(At, 0, 1); PG8_STAGE(PG8_SB(0, 0), b2, voffB); PG8_STAGE(PG8_SB(0, 1), b2 + hstepB, voffB); PG8_STAGE(PG8_SA(0, 0), a2, voffA);
;             PG8_WAIT_V(8); PG8_WAIT_L(0); PG8_BAR; PG8_MMA(1, 0, At, B0); PG8_MMA(1, 1, At, B1); PG8_BAR; PG8_SCHED;
.LBB0_1020:
	ds_read_b128 v[122:125], v172
	ds_read_b128 v[126:129], v172 offset:1024
	ds_read_b128 v[130:133], v172 offset:2048
	ds_read_b128 v[138:141], v172 offset:3072
	ds_read_b128 v[182:185], v173
	ds_read_b128 v[186:189], v173 offset:1024
	ds_read_b128 v[190:193], v173 offset:2048
	ds_read_b128 v[194:197], v173 offset:3072
	s_add_u32 s58, s56, 0xffea8080
	s_addc_u32 s59, s57, -1
	s_cmpk_eq_i32 s67, 0x52
	s_cselect_b32 s61, s1, s59
	s_cselect_b32 s60, s0, s58
	s_cselect_b32 s59, s53, s66
	s_cselect_b32 s58, s52, s65
	v_lshl_add_u64 v[166:167], s[56:57], 0, v[158:159]
	s_add_i32 m0, s9, 0xc000
	ds_read_b128 v[198:201], v174
	ds_read_b128 v[202:205], v174 offset:1024
	ds_read_b128 v[206:209], v174 offset:2048
	ds_read_b128 v[212:215], v174 offset:3072
	ds_read_b128 v[216:219], v174 offset:4096
	ds_read_b128 v[220:223], v174 offset:5120
	ds_read_b128 v[224:227], v174 offset:6144
	ds_read_b128 v[228:231], v174 offset:7168
	global_load_lds_dwordx4 v[166:167], off
	v_lshl_add_u64 v[166:167], s[56:57], 0, v[160:161]
	s_add_i32 m0, s9, 0xe000
	s_nop 0
	global_load_lds_dwordx4 v[166:167], off
	s_waitcnt vmcnt(8)
	s_waitcnt lgkmcnt(0)
	s_barrier
	s_setprio 1
	v_mfma_i32_16x16x64_i8 v[142:145], v[122:125], v[198:201], v[142:145]
	v_mfma_i32_16x16x64_i8 v[142:145], v[126:129], v[202:205], v[142:145]
	v_mfma_i32_16x16x64_i8 v[134:137], v[138:141], v[202:205], v[134:137]
	v_mfma_i32_16x16x64_i8 v[134:137], v[130:133], v[198:201], v[134:137]
	v_mfma_i32_16x16x64_i8 v[106:109], v[130:133], v[206:209], v[106:109]
	v_mfma_i32_16x16x64_i8 v[106:109], v[138:141], v[212:215], v[106:109]
	v_mfma_i32_16x16x64_i8 v[110:113], v[126:129], v[212:215], v[110:113]
	v_mfma_i32_16x16x64_i8 v[110:113], v[122:125], v[206:209], v[110:113]
	v_mfma_i32_16x16x64_i8 v[94:97], v[122:125], v[216:219], v[94:97]
	v_mfma_i32_16x16x64_i8 v[94:97], v[126:129], v[220:223], v[94:97]
	v_mfma_i32_16x16x64_i8 v[90:93], v[138:141], v[220:223], v[90:93]
	v_mfma_i32_16x16x64_i8 v[90:93], v[130:133], v[216:219], v[90:93]
	v_mfma_i32_16x16x64_i8 v[74:77], v[130:133], v[224:227], v[74:77]
	v_mfma_i32_16x16x64_i8 v[74:77], v[138:141], v[228:231], v[74:77]
	v_mfma_i32_16x16x64_i8 v[78:81], v[126:129], v[228:231], v[78:81]
	v_mfma_i32_16x16x64_i8 v[78:81], v[122:125], v[224:227], v[78:81]
	v_mfma_i32_16x16x64_i8 v[118:121], v[182:185], v[198:201], v[118:121]
	v_mfma_i32_16x16x64_i8 v[118:121], v[186:189], v[202:205], v[118:121]
	v_mfma_i32_16x16x64_i8 v[114:117], v[194:197], v[202:205], v[114:117]
	v_mfma_i32_16x16x64_i8 v[114:117], v[190:193], v[198:201], v[114:117]
	v_mfma_i32_16x16x64_i8 v[98:101], v[190:193], v[206:209], v[98:101]
	v_mfma_i32_16x16x64_i8 v[98:101], v[194:197], v[212:215], v[98:101]
	v_mfma_i32_16x16x64_i8 v[102:105], v[186:189], v[212:215], v[102:105]
	v_mfma_i32_16x16x64_i8 v[102:105], v[182:185], v[206:209], v[102:105]
	v_mfma_i32_16x16x64_i8 v[86:89], v[182:185], v[216:219], v[86:89]
	v_mfma_i32_16x16x64_i8 v[86:89], v[186:189], v[220:223], v[86:89]
	v_mfma_i32_16x16x64_i8 v[82:85], v[194:197], v[220:223], v[82:85]
	v_mfma_i32_16x16x64_i8 v[82:85], v[190:193], v[216:219], v[82:85]
	v_mfma_i32_16x16x64_i8 v[66:69], v[190:193], v[224:227], v[66:69]
	v_mfma_i32_16x16x64_i8 v[66:69], v[194:197], v[228:231], v[66:69]
	v_mfma_i32_16x16x64_i8 v[70:73], v[186:189], v[228:231], v[70:73]
	v_mfma_i32_16x16x64_i8 v[70:73], v[182:185], v[224:227], v[70:73]
	s_setprio 0
	s_barrier
	s_add_i32 s68, s29, s7
	v_lshl_add_u64 v[166:167], s[58:59], 0, v[148:149]
	s_mov_b32 m0, s68
	ds_read_b128 v[198:201], v174 offset:16384
	ds_read_b128 v[202:205], v174 offset:17408
	ds_read_b128 v[206:209], v174 offset:18432
	ds_read_b128 v[212:215], v174 offset:19456
	ds_read_b128 v[216:219], v174 offset:20480
	ds_read_b128 v[220:223], v174 offset:21504
	ds_read_b128 v[224:227], v174 offset:22528
	ds_read_b128 v[228:231], v174 offset:23552
	global_load_lds_dwordx4 v[166:167], off
	s_add_i32 m0, s68, 0x2000
	s_add_u32 s68, s58, 0x158000
	v_lshl_add_u64 v[176:177], s[58:59], 0, v[152:153]
	s_addc_u32 s69, s59, 0
	s_add_i32 s70, s33, s7
	global_load_lds_dwordx4 v[176:177], off
	v_lshl_add_u64 v[232:233], s[68:69], 0, v[148:149]
	s_mov_b32 m0, s70
	v_lshl_add_u64 v[234:235], s[60:61], 0, v[150:151]
	global_load_lds_dwordx4 v[232:233], off
	v_lshl_add_u64 v[232:233], s[68:69], 0, v[152:153]
	s_add_i32 m0, s70, 0x2000
	s_nop 0
	global_load_lds_dwordx4 v[232:233], off
	v_lshl_add_u64 v[232:233], s[60:61], 0, v[146:147]
	s_mov_b32 m0, s9
	s_nop 0
	global_load_lds_dwordx4 v[232:233], off
	s_mov_b32 m0, s11
	s_nop 0
	global_load_lds_dwordx4 v[234:235], off
	s_waitcnt vmcnt(8)
	s_waitcnt lgkmcnt(0)
	s_barrier
; #define PG8_STAGE(bufoff, gbase, voff) do { _Pragma("unroll") for (int _i = 0; _i < 2; ++_i) \
;         __builtin_amdgcn_global_load_lds((const unsigned*)((const char*)(gbase) + (voff)[_i]), (PG8_LAS unsigned*)(lds + (bufoff) + ldsw + _i * 8192), 16, 0, 0); } while (0)
; #define PG8_LDA(dst, b, h) do { _Pragma("unroll") for (int m = 0; m < 4; ++m) _Pragma("unroll") for (int k = 0; k < 2; ++k) dst[m][k] = *(const PG8_LAS bf16x8*)(lds + PG8_SA(b, h) + aoff + m * 2048 + k * 1024); } while (0)
; #define PG8_LDB(dst, b, h) do { _Pragma("unroll") for (int n = 0; n < 2; ++n) _Pragma("unroll") for (int k = 0; k < 2; ++k) dst[n][k] = *(const PG8_LAS bf16x8*)(lds + PG8_SB(b, h) + boff + n * 2048 + k * 1024); } while (0)
; #define PG8_MMA(ai, bj, At, Bt) do { __builtin_amdgcn_s_setprio(1); _Pragma("unroll") for (int m = 0; m < 4; ++m) _Pragma("unroll") for (int n = 0; n < 2; ++n) _Pragma("unroll") for (int k = 0; k < 2; ++k) \
;         acc[ai][bj][m][n] = mma16(Bt[n][k], At[m][k], acc[ai][bj][m][n]); __builtin_amdgcn_s_setprio(0); } while (0)
; #define PG8_WAIT_V(n) asm volatile("s_waitcnt vmcnt(" #n ")" ::: "memory")
; #define PG8_WAIT_L(n) asm volatile("s_waitcnt lgkmcnt(" #n ")" ::: "memory")
; #define PG8_BAR __builtin_amdgcn_s_barrier()
; #define PG8_SCHED __builtin_amdgcn_sched_barrier(0)
; template <class Epi, class Sched, bool ALIGN_EPI = false, bool SP2 = false>
; __device__ __forceinline__ void gemm_phase(PG8_LAS unsigned char* lds, const Gemm g, const Sched& S, const Epi& E) {
;     ...
;             PG8_WAIT_V(8); PG8_WAIT_L(0); PG8_BAR; PG8_MMA(1, 0, At, B0); PG8_MMA(1, 1, At, B1); PG8_BAR; PG8_SCHED;
;             PG8_LDB(B0, 1, 0); PG8_LDB(B1, 1, 1); PG8_SCHED; PG8_LDA(At, 1, 0); PG8_STAGE(PG8_SA(0, 1), a2 + hstepA, voffA);
;             PG8_WAIT_V(8); PG8_WAIT_L(0); PG8_BAR; PG8_MMA(0, 0, At, B0); PG8_MMA(0, 1, At, B1); PG8_BAR; PG8_SCHED;
	s_setprio 1
	v_mfma_i32_16x16x64_i8 v[62:65], v[122:125], v[198:201], v[62:65]
	v_mfma_i32_16x16x64_i8 v[62:65], v[126:129], v[202:205], v[62:65]
	v_mfma_i32_16x16x64_i8 v[58:61], v[138:141], v[202:205], v[58:61]
	v_mfma_i32_16x16x64_i8 v[58:61], v[130:133], v[198:201], v[58:61]
	v_mfma_i32_16x16x64_i8 v[42:45], v[130:133], v[206:209], v[42:45]
	v_mfma_i32_16x16x64_i8 v[42:45], v[138:141], v[212:215], v[42:45]
	v_mfma_i32_16x16x64_i8 v[46:49], v[126:129], v[212:215], v[46:49]
	v_mfma_i32_16x16x64_i8 v[46:49], v[122:125], v[206:209], v[46:49]
	v_mfma_i32_16x16x64_i8 v[30:33], v[122:125], v[216:219], v[30:33]
	v_mfma_i32_16x16x64_i8 v[30:33], v[126:129], v[220:223], v[30:33]
	v_mfma_i32_16x16x64_i8 v[26:29], v[138:141], v[220:223], v[26:29]
	v_mfma_i32_16x16x64_i8 v[26:29], v[130:133], v[216:219], v[26:29]
	v_mfma_i32_16x16x64_i8 v[10:13], v[130:133], v[224:227], v[10:13]
	v_mfma_i32_16x16x64_i8 v[10:13], v[138:141], v[228:231], v[10:13]
	v_mfma_i32_16x16x64_i8 v[14:17], v[126:129], v[228:231], v[14:17]
	v_mfma_i32_16x16x64_i8 v[14:17], v[122:125], v[224:227], v[14:17]
	v_mfma_i32_16x16x64_i8 v[54:57], v[182:185], v[198:201], v[54:57]
	v_mfma_i32_16x16x64_i8 v[54:57], v[186:189], v[202:205], v[54:57]
	v_mfma_i32_16x16x64_i8 v[50:53], v[194:197], v[202:205], v[50:53]
	v_mfma_i32_16x16x64_i8 v[50:53], v[190:193], v[198:201], v[50:53]
	v_mfma_i32_16x16x64_i8 v[34:37], v[190:193], v[206:209], v[34:37]
	v_mfma_i32_16x16x64_i8 v[34:37], v[194:197], v[212:215], v[34:37]
	v_mfma_i32_16x16x64_i8 v[38:41], v[186:189], v[212:215], v[38:41]
	v_mfma_i32_16x16x64_i8 v[38:41], v[182:185], v[206:209], v[38:41]
	v_mfma_i32_16x16x64_i8 v[22:25], v[182:185], v[216:219], v[22:25]
	v_mfma_i32_16x16x64_i8 v[22:25], v[186:189], v[220:223], v[22:25]
	v_mfma_i32_16x16x64_i8 v[18:21], v[194:197], v[220:223], v[18:21]
	v_mfma_i32_16x16x64_i8 v[18:21], v[190:193], v[216:219], v[18:21]
	v_mfma_i32_16x16x64_i8 v[2:5], v[190:193], v[224:227], v[2:5]
	v_mfma_i32_16x16x64_i8 v[2:5], v[194:197], v[228:231], v[2:5]
	v_mfma_i32_16x16x64_i8 v[6:9], v[186:189], v[228:231], v[6:9]
	v_mfma_i32_16x16x64_i8 v[6:9], v[182:185], v[224:227], v[6:9]
	s_setprio 0
	s_barrier
	s_add_i32 s68, 0, 0x18000
	s_add_i32 s69, 0, 0x1c000
	v_add_u32_e32 v138, s68, v170
	v_add_u32_e32 v175, s69, v170
	ds_read_b128 v[122:125], v138
	ds_read_b128 v[126:129], v138 offset:1024
	ds_read_b128 v[130:133], v138 offset:2048
	ds_read_b128 v[138:141], v138 offset:3072
	ds_read_b128 v[182:185], v175
	ds_read_b128 v[186:189], v175 offset:1024
	ds_read_b128 v[190:193], v175 offset:2048
	ds_read_b128 v[194:197], v175 offset:3072
	s_add_u32 s60, s60, 0x158000
	s_addc_u32 s61, s61, 0
	s_mov_b32 m0, s12
	v_lshl_add_u64 v[236:237], s[60:61], 0, v[146:147]
	ds_read_b128 v[198:201], v174 offset:32768
	ds_read_b128 v[202:205], v174 offset:33792
	ds_read_b128 v[206:209], v174 offset:34816
	ds_read_b128 v[212:215], v174 offset:35840
	ds_read_b128 v[216:219], v174 offset:36864
	ds_read_b128 v[220:223], v174 offset:37888
	ds_read_b128 v[224:227], v174 offset:38912
	ds_read_b128 v[228:231], v174 offset:39936
	global_load_lds_dwordx4 v[236:237], off
	v_lshl_add_u64 v[236:237], s[60:61], 0, v[150:151]
	s_mov_b32 m0, s13
	s_nop 0
	global_load_lds_dwordx4 v[236:237], off
	s_waitcnt vmcnt(8)
	s_waitcnt lgkmcnt(0)
	s_barrier
	s_setprio 1
	v_mfma_i32_16x16x64_i8 v[142:145], v[122:125], v[198:201], v[142:145]
	v_mfma_i32_16x16x64_i8 v[142:145], v[126:129], v[202:205], v[142:145]
	v_mfma_i32_16x16x64_i8 v[134:137], v[138:141], v[202:205], v[134:137]
	v_mfma_i32_16x16x64_i8 v[134:137], v[130:133], v[198:201], v[134:137]
	v_mfma_i32_16x16x64_i8 v[106:109], v[130:133], v[206:209], v[106:109]
	v_mfma_i32_16x16x64_i8 v[106:109], v[138:141], v[212:215], v[106:109]
	v_mfma_i32_16x16x64_i8 v[110:113], v[126:129], v[212:215], v[110:113]
	v_mfma_i32_16x16x64_i8 v[110:113], v[122:125], v[206:209], v[110:113]
	v_mfma_i32_16x16x64_i8 v[94:97], v[122:125], v[216:219], v[94:97]
	v_mfma_i32_16x16x64_i8 v[94:97], v[126:129], v[220:223], v[94:97]
	v_mfma_i32_16x16x64_i8 v[90:93], v[138:141], v[220:223], v[90:93]
	v_mfma_i32_16x16x64_i8 v[90:93], v[130:133], v[216:219], v[90:93]
	v_mfma_i32_16x16x64_i8 v[74:77], v[130:133], v[224:227], v[74:77]
	v_mfma_i32_16x16x64_i8 v[74:77], v[138:141], v[228:231], v[74:77]
	v_mfma_i32_16x16x64_i8 v[78:81], v[126:129], v[228:231], v[78:81]
	v_mfma_i32_16x16x64_i8 v[78:81], v[122:125], v[224:227], v[78:81]
	v_mfma_i32_16x16x64_i8 v[118:121], v[182:185], v[198:201], v[118:121]
	v_mfma_i32_16x16x64_i8 v[118:121], v[186:189], v[202:205], v[118:121]
	v_mfma_i32_16x16x64_i8 v[114:117], v[194:197], v[202:205], v[114:117]
	v_mfma_i32_16x16x64_i8 v[114:117], v[190:193], v[198:201], v[114:117]
	v_mfma_i32_16x16x64_i8 v[98:101], v[190:193], v[206:209], v[98:101]
	v_mfma_i32_16x16x64_i8 v[98:101], v[194:197], v[212:215], v[98:101]
	v_mfma_i32_16x16x64_i8 v[102:105], v[186:189], v[212:215], v[102:105]
	v_mfma_i32_16x16x64_i8 v[102:105], v[182:185], v[206:209], v[102:105]
	v_mfma_i32_16x16x64_i8 v[86:89], v[182:185], v[216:219], v[86:89]
	v_mfma_i32_16x16x64_i8 v[86:89], v[186:189], v[220:223], v[86:89]
	v_mfma_i32_16x16x64_i8 v[82:85], v[194:197], v[220:223], v[82:85]
	v_mfma_i32_16x16x64_i8 v[82:85], v[190:193], v[216:219], v[82:85]
	v_mfma_i32_16x16x64_i8 v[66:69], v[190:193], v[224:227], v[66:69]
	v_mfma_i32_16x16x64_i8 v[66:69], v[194:197], v[228:231], v[66:69]
	v_mfma_i32_16x16x64_i8 v[70:73], v[186:189], v[228:231], v[70:73]
	v_mfma_i32_16x16x64_i8 v[70:73], v[182:185], v[224:227], v[70:73]
	s_setprio 0
	s_barrier
; #define PG8_STAGE(bufoff, gbase, voff) do { _Pragma("unroll") for (int _i = 0; _i < 2; ++_i) \
;         __builtin_amdgcn_global_load_lds((const unsigned*)((const char*)(gbase) + (voff)[_i]), (PG8_LAS unsigned*)(lds + (bufoff) + ldsw + _i * 8192), 16, 0, 0); } while (0)
; #define PG8_LDA(dst, b, h) do { _Pragma("unroll") for (int m = 0; m < 4; ++m) _Pragma("unroll") for (int k = 0; k < 2; ++k) dst[m][k] = *(const PG8_LAS bf16x8*)(lds + PG8_SA(b, h) + aoff + m * 2048 + k * 1024); } while (0)
; #define PG8_MMA(ai, bj, At, Bt) do { __builtin_amdgcn_s_setprio(1); _Pragma("unroll") for (int m = 0; m < 4; ++m) _Pragma("unroll") for (int n = 0; n < 2; ++n) _Pragma("unroll") for (int k = 0; k < 2; ++k) \
;         acc[ai][bj][m][n] = mma16(Bt[n][k], At[m][k], acc[ai][bj][m][n]); __builtin_amdgcn_s_setprio(0); } while (0)
; #define PG8_WAIT_V(n) asm volatile("s_waitcnt vmcnt(" #n ")" ::: "memory")
; #define PG8_WAIT_L(n) asm volatile("s_waitcnt lgkmcnt(" #n ")" ::: "memory")
; #define PG8_BAR __builtin_amdgcn_s_barrier()
; #define PG8_SCHED __builtin_amdgcn_sched_barrier(0)
; template <class Epi, class Sched, bool ALIGN_EPI = false, bool SP2 = false>
; __device__ __forceinline__ void gemm_phase(PG8_LAS unsigned char* lds, const Gemm g, const Sched& S, const Epi& E) {
;     ...
;             PG8_LDA(At, 1, 1); PG8_STAGE(PG8_SB(1, 0), b3, voffB); PG8_STAGE(PG8_SB(1, 1), b3 + hstepB, voffB); PG8_STAGE(PG8_SA(1, 0), a3, voffA);
;             PG8_WAIT_V(8); PG8_WAIT_L(0); PG8_BAR; PG8_MMA(1, 0, At, B0); PG8_MMA(1, 1, At, B1); PG8_BAR; PG8_SCHED;
	s_add_i32 s60, s68, s7
	v_lshl_add_u64 v[166:167], v[166:167], 0, s[24:25]
	s_mov_b32 m0, s60
	ds_read_b128 v[198:201], v174 offset:49152
	ds_read_b128 v[202:205], v174 offset:50176
	ds_read_b128 v[206:209], v174 offset:51200
	ds_read_b128 v[212:215], v174 offset:52224
	ds_read_b128 v[216:219], v174 offset:53248
	ds_read_b128 v[220:223], v174 offset:54272
	ds_read_b128 v[224:227], v174 offset:55296
	ds_read_b128 v[228:231], v174 offset:56320
	global_load_lds_dwordx4 v[166:167], off
	s_add_i32 m0, s60, 0x2000
	s_add_u32 s58, s58, 0x158080
	v_lshl_add_u64 v[166:167], v[176:177], 0, s[24:25]
	s_addc_u32 s59, s59, 0
	s_add_i32 s60, s69, s7
	global_load_lds_dwordx4 v[166:167], off
	v_lshl_add_u64 v[166:167], s[58:59], 0, v[148:149]
	s_mov_b32 m0, s60
	s_nop 0
	global_load_lds_dwordx4 v[166:167], off
	v_lshl_add_u64 v[166:167], s[58:59], 0, v[152:153]
	s_add_i32 m0, s60, 0x2000
	s_nop 0
	global_load_lds_dwordx4 v[166:167], off
	v_lshl_add_u64 v[166:167], v[232:233], 0, s[24:25]
	s_mov_b32 m0, s26
	s_nop 0
	global_load_lds_dwordx4 v[166:167], off
	v_lshl_add_u64 v[166:167], v[234:235], 0, s[24:25]
	s_mov_b32 m0, s27
	s_nop 0
	global_load_lds_dwordx4 v[166:167], off
	s_waitcnt vmcnt(8)
	s_waitcnt lgkmcnt(0)
	s_barrier
	s_setprio 1
	v_mfma_i32_16x16x64_i8 v[62:65], v[122:125], v[198:201], v[62:65]
	v_mfma_i32_16x16x64_i8 v[62:65], v[126:129], v[202:205], v[62:65]
	v_mfma_i32_16x16x64_i8 v[58:61], v[138:141], v[202:205], v[58:61]
	v_mfma_i32_16x16x64_i8 v[58:61], v[130:133], v[198:201], v[58:61]
	v_mfma_i32_16x16x64_i8 v[42:45], v[130:133], v[206:209], v[42:45]
	v_mfma_i32_16x16x64_i8 v[42:45], v[138:141], v[212:215], v[42:45]
	v_mfma_i32_16x16x64_i8 v[46:49], v[126:129], v[212:215], v[46:49]
	v_mfma_i32_16x16x64_i8 v[46:49], v[122:125], v[206:209], v[46:49]
	v_mfma_i32_16x16x64_i8 v[30:33], v[122:125], v[216:219], v[30:33]
	v_mfma_i32_16x16x64_i8 v[30:33], v[126:129], v[220:223], v[30:33]
	v_mfma_i32_16x16x64_i8 v[26:29], v[138:141], v[220:223], v[26:29]
	v_mfma_i32_16x16x64_i8 v[26:29], v[130:133], v[216:219], v[26:29]
	v_mfma_i32_16x16x64_i8 v[10:13], v[130:133], v[224:227], v[10:13]
	v_mfma_i32_16x16x64_i8 v[10:13], v[138:141], v[228:231], v[10:13]
	v_mfma_i32_16x16x64_i8 v[14:17], v[126:129], v[228:231], v[14:17]
	v_mfma_i32_16x16x64_i8 v[14:17], v[122:125], v[224:227], v[14:17]
	v_mfma_i32_16x16x64_i8 v[54:57], v[182:185], v[198:201], v[54:57]
	v_mfma_i32_16x16x64_i8 v[54:57], v[186:189], v[202:205], v[54:57]
	v_mfma_i32_16x16x64_i8 v[50:53], v[194:197], v[202:205], v[50:53]
	v_mfma_i32_16x16x64_i8 v[50:53], v[190:193], v[198:201], v[50:53]
	v_mfma_i32_16x16x64_i8 v[34:37], v[190:193], v[206:209], v[34:37]
	v_mfma_i32_16x16x64_i8 v[34:37], v[194:197], v[212:215], v[34:37]
	v_mfma_i32_16x16x64_i8 v[38:41], v[186:189], v[212:215], v[38:41]
	v_mfma_i32_16x16x64_i8 v[38:41], v[182:185], v[206:209], v[38:41]
	v_mfma_i32_16x16x64_i8 v[22:25], v[182:185], v[216:219], v[22:25]
	v_mfma_i32_16x16x64_i8 v[22:25], v[186:189], v[220:223], v[22:25]
	v_mfma_i32_16x16x64_i8 v[18:21], v[194:197], v[220:223], v[18:21]
	v_mfma_i32_16x16x64_i8 v[18:21], v[190:193], v[216:219], v[18:21]
	v_mfma_i32_16x16x64_i8 v[2:5], v[190:193], v[224:227], v[2:5]
	v_mfma_i32_16x16x64_i8 v[2:5], v[194:197], v[228:231], v[2:5]
	v_mfma_i32_16x16x64_i8 v[6:9], v[186:189], v[228:231], v[6:9]
	v_mfma_i32_16x16x64_i8 v[6:9], v[182:185], v[224:227], v[6:9]
	s_setprio 0
	s_barrier
	s_add_i32 s67, s67, 2
	s_add_u32 s56, s56, 0x100
	s_addc_u32 s57, s57, 0
	s_add_u32 s65, s65, 0x100
	s_addc_u32 s66, s66, 0
	s_cmpk_gt_u32 s67, 0x53
	s_cbranch_scc0 .LBB0_1020
	s_and_b64 vcc, exec, s[36:37]
	s_cbranch_vccz .LBB0_1023
	s_barrier

; #define PG8_STAGE(bufoff, gbase, voff) do { _Pragma("unroll") for (int _i = 0; _i < 2; ++_i) \
;         __builtin_amdgcn_global_load_lds((const unsigned*)((const char*)(gbase) + (voff)[_i]), (PG8_LAS unsigned*)(lds + (bufoff) + ldsw + _i * 8192), 16, 0, 0); } while (0)
; #define PG8_LDA(dst, b, h) do { _Pragma("unroll") for (int m = 0; m < 4; ++m) _Pragma("unroll") for (int k = 0; k < 2; ++k) dst[m][k] = *(const PG8_LAS bf16x8*)(lds + PG8_SA(b, h) + aoff + m * 2048 + k * 1024); } while (0)
; #define PG8_LDB(dst, b, h) do { _Pragma("unroll") for (int n = 0; n < 2; ++n) _Pragma("unroll") for (int k = 0; k < 2; ++k) dst[n][k] = *(const PG8_LAS bf16x8*)(lds + PG8_SB(b, h) + boff + n * 2048 + k * 1024); } while (0)
; #define PG8_MMA(ai, bj, At, Bt) do { __builtin_amdgcn_s_setprio(1); _Pragma("unroll") for (int m = 0; m < 4; ++m) _Pragma("unroll") for (int n = 0; n < 2; ++n) _Pragma("unroll") for (int k = 0; k < 2; ++k) \
;         acc[ai][bj][m][n] = mma16(Bt[n][k], At[m][k], acc[ai][bj][m][n]); __builtin_amdgcn_s_setprio(0); } while (0)
; #define PG8_WAIT_V(n) asm volatile("s_waitcnt vmcnt(" #n ")" ::: "memory")
; #define PG8_WAIT_L(n) asm volatile("s_waitcnt lgkmcnt(" #n ")" ::: "memory")
; template <class Epi, class Sched, bool ALIGN_EPI = false, bool SP2 = false>
; __device__ __forceinline__ void gemm_phase(PG8_LAS unsigned char* lds, const Gemm g, const Sched& S, const Epi& E) {
;     ...
;         for (int t = 0; t < nt; t += 2) {
;             const bool last = (t == nt - 2);
;             const char* a1 = cA + (size_t)(t + 1) * kstep;
;             const char* a2 = last ? nA : cA + (size_t)(t + 2) * kstep; const char* b2 = last ? nB : cB + (size_t)(t + 2) * kstep;
;             const char* a3 = a2 + kstep; const char* b3 = b2 + kstep;
;             if (last && has_next) S.a_ready(nxt);
;             if constexpr (SP2) {
;             PG8_LDB(B0, 0, 0); PG8_LDB(B1, 0, 1); PG8_SCHED; PG8_LDA(At, 0, 0); PG8_STAGE(PG8_SA(1, 1), a1 + hstepA, voffA);
;             PG8_WAIT_V(8); PG8_WAIT_L(0); PG8_BAR; PG8_MMA(0, 0, At, B0); PG8_MMA(0, 1, At, B1); PG8_BAR; PG8_SCHED;
;             PG8_LDA(At, 0, 1); PG8_STAGE(PG8_SB(0, 0), b2, voffB); PG8_STAGE(PG8_SB(0, 1), b2 + hstepB, voffB); PG8_STAGE(PG8_SA(0, 0), a2, voffA);
;             PG8_WAIT_V(8); PG8_WAIT_L(0); PG8_BAR; PG8_MMA(1, 0, At, B0); PG8_MMA(1, 1, At, B1); PG8_BAR; PG8_SCHED;
.LBB0_1037:
	ds_read_b128 v[118:121], v167
	ds_read_b128 v[126:129], v167 offset:1024
	ds_read_b128 v[130:133], v167 offset:2048
	ds_read_b128 v[134:137], v167 offset:3072
	ds_read_b128 v[172:175], v168
	ds_read_b128 v[182:185], v168 offset:1024
	ds_read_b128 v[186:189], v168 offset:2048
	ds_read_b128 v[190:193], v168 offset:3072
	s_add_u32 s52, s50, 0xffea8080
	s_addc_u32 s53, s51, -1
	s_cmpk_eq_i32 s71, 0x52
	s_cselect_b32 s55, s47, s53
	s_cselect_b32 s54, s46, s52
	s_cselect_b32 s53, s9, s70
	s_cselect_b32 s52, s8, s45
	s_mov_b32 m0, s35
	v_lshl_add_u64 v[162:163], s[50:51], 0, v[158:159]
	ds_read_b128 v[194:197], v169
	ds_read_b128 v[198:201], v169 offset:1024
	ds_read_b128 v[202:205], v169 offset:2048
	ds_read_b128 v[206:209], v169 offset:3072
	ds_read_b128 v[212:215], v169 offset:4096
	ds_read_b128 v[216:219], v169 offset:5120
	ds_read_b128 v[220:223], v169 offset:6144
	ds_read_b128 v[224:227], v169 offset:7168
	global_load_lds_dwordx4 v[162:163], off
	v_lshl_add_u64 v[162:163], s[50:51], 0, v[160:161]
	s_mov_b32 m0, s56
	s_nop 0
	global_load_lds_dwordx4 v[162:163], off
	s_waitcnt vmcnt(8)
	s_waitcnt lgkmcnt(0)
	s_barrier
	s_setprio 1
	v_mfma_i32_16x16x64_i8 v[142:145], v[118:121], v[194:197], v[142:145]
	v_mfma_i32_16x16x64_i8 v[142:145], v[126:129], v[198:201], v[142:145]
	v_mfma_i32_16x16x64_i8 v[138:141], v[134:137], v[198:201], v[138:141]
	v_mfma_i32_16x16x64_i8 v[138:141], v[130:133], v[194:197], v[138:141]
	v_mfma_i32_16x16x64_i8 v[106:109], v[130:133], v[202:205], v[106:109]
	v_mfma_i32_16x16x64_i8 v[106:109], v[134:137], v[206:209], v[106:109]
	v_mfma_i32_16x16x64_i8 v[110:113], v[126:129], v[206:209], v[110:113]
	v_mfma_i32_16x16x64_i8 v[110:113], v[118:121], v[202:205], v[110:113]
	v_mfma_i32_16x16x64_i8 v[94:97], v[118:121], v[212:215], v[94:97]
	v_mfma_i32_16x16x64_i8 v[94:97], v[126:129], v[216:219], v[94:97]
	v_mfma_i32_16x16x64_i8 v[90:93], v[134:137], v[216:219], v[90:93]
	v_mfma_i32_16x16x64_i8 v[90:93], v[130:133], v[212:215], v[90:93]
	v_mfma_i32_16x16x64_i8 v[74:77], v[130:133], v[220:223], v[74:77]
	v_mfma_i32_16x16x64_i8 v[74:77], v[134:137], v[224:227], v[74:77]
	v_mfma_i32_16x16x64_i8 v[78:81], v[126:129], v[224:227], v[78:81]
	v_mfma_i32_16x16x64_i8 v[78:81], v[118:121], v[220:223], v[78:81]
	v_mfma_i32_16x16x64_i8 v[122:125], v[172:175], v[194:197], v[122:125]
	v_mfma_i32_16x16x64_i8 v[122:125], v[182:185], v[198:201], v[122:125]
	v_mfma_i32_16x16x64_i8 v[114:117], v[190:193], v[198:201], v[114:117]
	v_mfma_i32_16x16x64_i8 v[114:117], v[186:189], v[194:197], v[114:117]
	v_mfma_i32_16x16x64_i8 v[98:101], v[186:189], v[202:205], v[98:101]
	v_mfma_i32_16x16x64_i8 v[98:101], v[190:193], v[206:209], v[98:101]
	v_mfma_i32_16x16x64_i8 v[102:105], v[182:185], v[206:209], v[102:105]
	v_mfma_i32_16x16x64_i8 v[102:105], v[172:175], v[202:205], v[102:105]
	v_mfma_i32_16x16x64_i8 v[86:89], v[172:175], v[212:215], v[86:89]
	v_mfma_i32_16x16x64_i8 v[86:89], v[182:185], v[216:219], v[86:89]
	v_mfma_i32_16x16x64_i8 v[82:85], v[190:193], v[216:219], v[82:85]
	v_mfma_i32_16x16x64_i8 v[82:85], v[186:189], v[212:215], v[82:85]
	v_mfma_i32_16x16x64_i8 v[66:69], v[186:189], v[220:223], v[66:69]
	v_mfma_i32_16x16x64_i8 v[66:69], v[190:193], v[224:227], v[66:69]
	v_mfma_i32_16x16x64_i8 v[70:73], v[182:185], v[224:227], v[70:73]
	v_mfma_i32_16x16x64_i8 v[70:73], v[172:175], v[220:223], v[70:73]
	s_setprio 0
	s_barrier
	s_mov_b32 m0, s57
	v_lshl_add_u64 v[162:163], s[52:53], 0, v[150:151]
	s_add_u32 s74, s52, 0x158000
	ds_read_b128 v[194:197], v169 offset:16384
	ds_read_b128 v[198:201], v169 offset:17408
	ds_read_b128 v[202:205], v169 offset:18432
	ds_read_b128 v[206:209], v169 offset:19456
	ds_read_b128 v[212:215], v169 offset:20480
	ds_read_b128 v[216:219], v169 offset:21504
	ds_read_b128 v[220:223], v169 offset:22528
	ds_read_b128 v[224:227], v169 offset:23552
	global_load_lds_dwordx4 v[162:163], off
	v_lshl_add_u64 v[176:177], s[52:53], 0, v[146:147]
	s_mov_b32 m0, s58
	s_addc_u32 s75, s53, 0
	global_load_lds_dwordx4 v[176:177], off
	v_lshl_add_u64 v[228:229], s[74:75], 0, v[150:151]
	s_mov_b32 m0, s63
	v_lshl_add_u64 v[230:231], s[54:55], 0, v[148:149]
	global_load_lds_dwordx4 v[228:229], off
	v_lshl_add_u64 v[228:229], s[74:75], 0, v[146:147]
	s_mov_b32 m0, s64
	s_nop 0
	global_load_lds_dwordx4 v[228:229], off
	v_lshl_add_u64 v[228:229], s[54:55], 0, v[152:153]
	s_mov_b32 m0, s5
	s_nop 0
	global_load_lds_dwordx4 v[228:229], off
	s_mov_b32 m0, s6
	s_nop 0
	global_load_lds_dwordx4 v[230:231], off
	s_waitcnt vmcnt(8)
	s_waitcnt lgkmcnt(0)
	s_barrier
	s_setprio 1
	v_mfma_i32_16x16x64_i8 v[62:65], v[118:121], v[194:197], v[62:65]
	v_mfma_i32_16x16x64_i8 v[62:65], v[126:129], v[198:201], v[62:65]
	v_mfma_i32_16x16x64_i8 v[58:61], v[134:137], v[198:201], v[58:61]
	v_mfma_i32_16x16x64_i8 v[58:61], v[130:133], v[194:197], v[58:61]
	v_mfma_i32_16x16x64_i8 v[42:45], v[130:133], v[202:205], v[42:45]
	v_mfma_i32_16x16x64_i8 v[42:45], v[134:137], v[206:209], v[42:45]
	v_mfma_i32_16x16x64_i8 v[46:49], v[126:129], v[206:209], v[46:49]
	v_mfma_i32_16x16x64_i8 v[46:49], v[118:121], v[202:205], v[46:49]
	v_mfma_i32_16x16x64_i8 v[30:33], v[118:121], v[212:215], v[30:33]
	v_mfma_i32_16x16x64_i8 v[30:33], v[126:129], v[216:219], v[30:33]
	v_mfma_i32_16x16x64_i8 v[26:29], v[134:137], v[216:219], v[26:29]
	v_mfma_i32_16x16x64_i8 v[26:29], v[130:133], v[212:215], v[26:29]
	v_mfma_i32_16x16x64_i8 v[10:13], v[130:133], v[220:223], v[10:13]
	v_mfma_i32_16x16x64_i8 v[10:13], v[134:137], v[224:227], v[10:13]
	v_mfma_i32_16x16x64_i8 v[14:17], v[126:129], v[224:227], v[14:17]
	v_mfma_i32_16x16x64_i8 v[14:17], v[118:121], v[220:223], v[14:17]
	v_mfma_i32_16x16x64_i8 v[54:57], v[172:175], v[194:197], v[54:57]
	v_mfma_i32_16x16x64_i8 v[54:57], v[182:185], v[198:201], v[54:57]
	v_mfma_i32_16x16x64_i8 v[50:53], v[190:193], v[198:201], v[50:53]
	v_mfma_i32_16x16x64_i8 v[50:53], v[186:189], v[194:197], v[50:53]
	v_mfma_i32_16x16x64_i8 v[34:37], v[186:189], v[202:205], v[34:37]
	v_mfma_i32_16x16x64_i8 v[34:37], v[190:193], v[206:209], v[34:37]
	v_mfma_i32_16x16x64_i8 v[38:41], v[182:185], v[206:209], v[38:41]
	v_mfma_i32_16x16x64_i8 v[38:41], v[172:175], v[202:205], v[38:41]
	v_mfma_i32_16x16x64_i8 v[22:25], v[172:175], v[212:215], v[22:25]
	v_mfma_i32_16x16x64_i8 v[22:25], v[182:185], v[216:219], v[22:25]
	v_mfma_i32_16x16x64_i8 v[18:21], v[190:193], v[216:219], v[18:21]
	v_mfma_i32_16x16x64_i8 v[18:21], v[186:189], v[212:215], v[18:21]
	v_mfma_i32_16x16x64_i8 v[2:5], v[186:189], v[220:223], v[2:5]
	v_mfma_i32_16x16x64_i8 v[2:5], v[190:193], v[224:227], v[2:5]
	v_mfma_i32_16x16x64_i8 v[6:9], v[182:185], v[224:227], v[6:9]
	v_mfma_i32_16x16x64_i8 v[6:9], v[172:175], v[220:223], v[6:9]
	s_setprio 0
	s_barrier
; #define PG8_STAGE(bufoff, gbase, voff) do { _Pragma("unroll") for (int _i = 0; _i < 2; ++_i) \
;         __builtin_amdgcn_global_load_lds((const unsigned*)((const char*)(gbase) + (voff)[_i]), (PG8_LAS unsigned*)(lds + (bufoff) + ldsw + _i * 8192), 16, 0, 0); } while (0)
; #define PG8_LDA(dst, b, h) do { _Pragma("unroll") for (int m = 0; m < 4; ++m) _Pragma("unroll") for (int k = 0; k < 2; ++k) dst[m][k] = *(const PG8_LAS bf16x8*)(lds + PG8_SA(b, h) + aoff + m * 2048 + k * 1024); } while (0)
; #define PG8_LDB(dst, b, h) do { _Pragma("unroll") for (int n = 0; n < 2; ++n) _Pragma("unroll") for (int k = 0; k < 2; ++k) dst[n][k] = *(const PG8_LAS bf16x8*)(lds + PG8_SB(b, h) + boff + n * 2048 + k * 1024); } while (0)
; #define PG8_MMA(ai, bj, At, Bt) do { __builtin_amdgcn_s_setprio(1); _Pragma("unroll") for (int m = 0; m < 4; ++m) _Pragma("unroll") for (int n = 0; n < 2; ++n) _Pragma("unroll") for (int k = 0; k < 2; ++k) \
;         acc[ai][bj][m][n] = mma16(Bt[n][k], At[m][k], acc[ai][bj][m][n]); __builtin_amdgcn_s_setprio(0); } while (0)
; #define PG8_WAIT_V(n) asm volatile("s_waitcnt vmcnt(" #n ")" ::: "memory")
; #define PG8_WAIT_L(n) asm volatile("s_waitcnt lgkmcnt(" #n ")" ::: "memory")
; #define PG8_BAR __builtin_amdgcn_s_barrier()
; #define PG8_SCHED __builtin_amdgcn_sched_barrier(0)
; template <class Epi, class Sched, bool ALIGN_EPI = false, bool SP2 = false>
; __device__ __forceinline__ void gemm_phase(PG8_LAS unsigned char* lds, const Gemm g, const Sched& S, const Epi& E) {
;     ...
;             PG8_WAIT_V(8); PG8_WAIT_L(0); PG8_BAR; PG8_MMA(1, 0, At, B0); PG8_MMA(1, 1, At, B1); PG8_BAR; PG8_SCHED;
;             PG8_LDB(B0, 1, 0); PG8_LDB(B1, 1, 1); PG8_SCHED; PG8_LDA(At, 1, 0); PG8_STAGE(PG8_SA(0, 1), a2 + hstepA, voffA);
;             PG8_WAIT_V(8); PG8_WAIT_L(0); PG8_BAR; PG8_MMA(0, 0, At, B0); PG8_MMA(0, 1, At, B1); PG8_BAR; PG8_SCHED;
;             PG8_LDA(At, 1, 1); PG8_STAGE(PG8_SB(1, 0), b3, voffB); PG8_STAGE(PG8_SB(1, 1), b3 + hstepB, voffB); PG8_STAGE(PG8_SA(1, 0), a3, voffA);
;             PG8_WAIT_V(8); PG8_WAIT_L(0); PG8_BAR; PG8_MMA(1, 0, At, B0); PG8_MMA(1, 1, At, B1); PG8_BAR; PG8_SCHED;
	ds_read_b128 v[118:121], v170
	ds_read_b128 v[126:129], v170 offset:1024
	ds_read_b128 v[130:133], v170 offset:2048
	ds_read_b128 v[134:137], v170 offset:3072
	ds_read_b128 v[172:175], v171
	ds_read_b128 v[182:185], v171 offset:1024
	ds_read_b128 v[186:189], v171 offset:2048
	ds_read_b128 v[190:193], v171 offset:3072
	s_add_u32 s54, s54, 0x158000
	s_addc_u32 s55, s55, 0
	s_mov_b32 m0, s7
	v_lshl_add_u64 v[232:233], s[54:55], 0, v[152:153]
	ds_read_b128 v[194:197], v169 offset:32768
	ds_read_b128 v[198:201], v169 offset:33792
	ds_read_b128 v[202:205], v169 offset:34816
	ds_read_b128 v[206:209], v169 offset:35840
	ds_read_b128 v[212:215], v169 offset:36864
	ds_read_b128 v[216:219], v169 offset:37888
	ds_read_b128 v[220:223], v169 offset:38912
	ds_read_b128 v[224:227], v169 offset:39936
	global_load_lds_dwordx4 v[232:233], off
	v_lshl_add_u64 v[232:233], s[54:55], 0, v[148:149]
	s_mov_b32 m0, s11
	s_nop 0
	global_load_lds_dwordx4 v[232:233], off
	s_waitcnt vmcnt(8)
	s_waitcnt lgkmcnt(0)
	s_barrier
	s_setprio 1
	v_mfma_i32_16x16x64_i8 v[142:145], v[118:121], v[194:197], v[142:145]
	v_mfma_i32_16x16x64_i8 v[142:145], v[126:129], v[198:201], v[142:145]
	v_mfma_i32_16x16x64_i8 v[138:141], v[134:137], v[198:201], v[138:141]
	v_mfma_i32_16x16x64_i8 v[138:141], v[130:133], v[194:197], v[138:141]
	v_mfma_i32_16x16x64_i8 v[106:109], v[130:133], v[202:205], v[106:109]
	v_mfma_i32_16x16x64_i8 v[106:109], v[134:137], v[206:209], v[106:109]
	v_mfma_i32_16x16x64_i8 v[110:113], v[126:129], v[206:209], v[110:113]
	v_mfma_i32_16x16x64_i8 v[110:113], v[118:121], v[202:205], v[110:113]
	v_mfma_i32_16x16x64_i8 v[94:97], v[118:121], v[212:215], v[94:97]
	v_mfma_i32_16x16x64_i8 v[94:97], v[126:129], v[216:219], v[94:97]
	v_mfma_i32_16x16x64_i8 v[90:93], v[134:137], v[216:219], v[90:93]
	v_mfma_i32_16x16x64_i8 v[90:93], v[130:133], v[212:215], v[90:93]
	v_mfma_i32_16x16x64_i8 v[74:77], v[130:133], v[220:223], v[74:77]
	v_mfma_i32_16x16x64_i8 v[74:77], v[134:137], v[224:227], v[74:77]
	v_mfma_i32_16x16x64_i8 v[78:81], v[126:129], v[224:227], v[78:81]
	v_mfma_i32_16x16x64_i8 v[78:81], v[118:121], v[220:223], v[78:81]
	v_mfma_i32_16x16x64_i8 v[122:125], v[172:175], v[194:197], v[122:125]
	v_mfma_i32_16x16x64_i8 v[122:125], v[182:185], v[198:201], v[122:125]
	v_mfma_i32_16x16x64_i8 v[114:117], v[190:193], v[198:201], v[114:117]
	v_mfma_i32_16x16x64_i8 v[114:117], v[186:189], v[194:197], v[114:117]
	v_mfma_i32_16x16x64_i8 v[98:101], v[186:189], v[202:205], v[98:101]
	v_mfma_i32_16x16x64_i8 v[98:101], v[190:193], v[206:209], v[98:101]
	v_mfma_i32_16x16x64_i8 v[102:105], v[182:185], v[206:209], v[102:105]
	v_mfma_i32_16x16x64_i8 v[102:105], v[172:175], v[202:205], v[102:105]
	v_mfma_i32_16x16x64_i8 v[86:89], v[172:175], v[212:215], v[86:89]
	v_mfma_i32_16x16x64_i8 v[86:89], v[182:185], v[216:219], v[86:89]
	v_mfma_i32_16x16x64_i8 v[82:85], v[190:193], v[216:219], v[82:85]
	v_mfma_i32_16x16x64_i8 v[82:85], v[186:189], v[212:215], v[82:85]
	v_mfma_i32_16x16x64_i8 v[66:69], v[186:189], v[220:223], v[66:69]
	v_mfma_i32_16x16x64_i8 v[66:69], v[190:193], v[224:227], v[66:69]
	v_mfma_i32_16x16x64_i8 v[70:73], v[182:185], v[224:227], v[70:73]
	v_mfma_i32_16x16x64_i8 v[70:73], v[172:175], v[220:223], v[70:73]
	s_setprio 0
	s_barrier
	s_mov_b32 m0, s65
	v_lshl_add_u64 v[162:163], v[162:163], 0, s[22:23]
	s_add_u32 s52, s52, 0x158080
	ds_read_b128 v[194:197], v169 offset:49152
	ds_read_b128 v[198:201], v169 offset:50176
	ds_read_b128 v[202:205], v169 offset:51200
	ds_read_b128 v[206:209], v169 offset:52224
	ds_read_b128 v[212:215], v169 offset:53248
	ds_read_b128 v[216:219], v169 offset:54272
	ds_read_b128 v[220:223], v169 offset:55296
	ds_read_b128 v[224:227], v169 offset:56320
	global_load_lds_dwordx4 v[162:163], off
	v_lshl_add_u64 v[162:163], v[176:177], 0, s[22:23]
	s_mov_b32 m0, s66
	s_addc_u32 s53, s53, 0
	global_load_lds_dwordx4 v[162:163], off
	v_lshl_add_u64 v[162:163], s[52:53], 0, v[150:151]
	s_mov_b32 m0, s67
	s_nop 0
	global_load_lds_dwordx4 v[162:163], off
	v_lshl_add_u64 v[162:163], s[52:53], 0, v[146:147]
	s_mov_b32 m0, s68
	s_nop 0
	global_load_lds_dwordx4 v[162:163], off
	v_lshl_add_u64 v[162:163], v[228:229], 0, s[22:23]
	s_mov_b32 m0, s26
	s_nop 0
	global_load_lds_dwordx4 v[162:163], off
	v_lshl_add_u64 v[162:163], v[230:231], 0, s[22:23]
	s_mov_b32 m0, s27
	s_nop 0
	global_load_lds_dwordx4 v[162:163], off
	s_waitcnt vmcnt(8)
	s_waitcnt lgkmcnt(0)
	s_barrier
	s_setprio 1
	v_mfma_i32_16x16x64_i8 v[62:65], v[118:121], v[194:197], v[62:65]
	v_mfma_i32_16x16x64_i8 v[62:65], v[126:129], v[198:201], v[62:65]
	v_mfma_i32_16x16x64_i8 v[58:61], v[134:137], v[198:201], v[58:61]
	v_mfma_i32_16x16x64_i8 v[58:61], v[130:133], v[194:197], v[58:61]
	v_mfma_i32_16x16x64_i8 v[42:45], v[130:133], v[202:205], v[42:45]
	v_mfma_i32_16x16x64_i8 v[42:45], v[134:137], v[206:209], v[42:45]
	v_mfma_i32_16x16x64_i8 v[46:49], v[126:129], v[206:209], v[46:49]
	v_mfma_i32_16x16x64_i8 v[46:49], v[118:121], v[202:205], v[46:49]
	v_mfma_i32_16x16x64_i8 v[30:33], v[118:121], v[212:215], v[30:33]
	v_mfma_i32_16x16x64_i8 v[30:33], v[126:129], v[216:219], v[30:33]
	v_mfma_i32_16x16x64_i8 v[26:29], v[134:137], v[216:219], v[26:29]
	v_mfma_i32_16x16x64_i8 v[26:29], v[130:133], v[212:215], v[26:29]
	v_mfma_i32_16x16x64_i8 v[10:13], v[130:133], v[220:223], v[10:13]
	v_mfma_i32_16x16x64_i8 v[10:13], v[134:137], v[224:227], v[10:13]
	v_mfma_i32_16x16x64_i8 v[14:17], v[126:129], v[224:227], v[14:17]
	v_mfma_i32_16x16x64_i8 v[14:17], v[118:121], v[220:223], v[14:17]
	v_mfma_i32_16x16x64_i8 v[54:57], v[172:175], v[194:197], v[54:57]
	v_mfma_i32_16x16x64_i8 v[54:57], v[182:185], v[198:201], v[54:57]
	v_mfma_i32_16x16x64_i8 v[50:53], v[190:193], v[198:201], v[50:53]
	v_mfma_i32_16x16x64_i8 v[50:53], v[186:189], v[194:197], v[50:53]
	v_mfma_i32_16x16x64_i8 v[34:37], v[186:189], v[202:205], v[34:37]
	v_mfma_i32_16x16x64_i8 v[34:37], v[190:193], v[206:209], v[34:37]
	v_mfma_i32_16x16x64_i8 v[38:41], v[182:185], v[206:209], v[38:41]
	v_mfma_i32_16x16x64_i8 v[38:41], v[172:175], v[202:205], v[38:41]
	v_mfma_i32_16x16x64_i8 v[22:25], v[172:175], v[212:215], v[22:25]
	v_mfma_i32_16x16x64_i8 v[22:25], v[182:185], v[216:219], v[22:25]
	v_mfma_i32_16x16x64_i8 v[18:21], v[190:193], v[216:219], v[18:21]
	v_mfma_i32_16x16x64_i8 v[18:21], v[186:189], v[212:215], v[18:21]
	v_mfma_i32_16x16x64_i8 v[2:5], v[186:189], v[220:223], v[2:5]
	v_mfma_i32_16x16x64_i8 v[2:5], v[190:193], v[224:227], v[2:5]
	v_mfma_i32_16x16x64_i8 v[6:9], v[182:185], v[224:227], v[6:9]
	v_mfma_i32_16x16x64_i8 v[6:9], v[172:175], v[220:223], v[6:9]
	s_setprio 0
	s_barrier
	s_add_i32 s71, s71, 2
	s_add_u32 s50, s50, 0x100
	s_addc_u32 s51, s51, 0
	s_add_u32 s45, s45, 0x100
	s_addc_u32 s70, s70, 0
	s_cmpk_gt_u32 s71, 0x53
	s_cbranch_scc0 .LBB0_1037
	s_and_b64 vcc, exec, s[24:25]
	s_cbranch_vccz .LBB0_1040
	s_barrier
